# attention: packed f32 adds beside the MFMAs split into scalar adds; K-loop: no-op setprio 0/1 pairs in the middle of MMA blocks removed
# speedup vs baseline: 1.0015x; 1.0015x over previous
.LBB0_322:
	s_ashr_i32 s43, s42, 31
	s_lshl_b64 s[46:47], s[42:43], 19
	s_add_u32 s46, s12, s46
	s_addc_u32 s47, s13, s47
	s_and_b64 s[48:49], s[4:5], exec
	s_cselect_b32 s18, s47, s7
	s_cselect_b32 s43, s46, s6
	s_ashr_i32 s45, s44, 31
	s_lshl_b64 s[48:49], s[44:45], 19
	s_add_u32 s48, s59, s48
	s_addc_u32 s49, s60, s49
	s_and_b64 s[50:51], s[4:5], exec
	s_cselect_b32 s45, s49, s9
	s_cselect_b32 s55, s48, s8
	s_add_u32 s6, s6, 0x40080
	s_addc_u32 s7, s7, 0
	s_add_u32 s56, s8, 0x100
	s_addc_u32 s57, s9, 0
	s_mov_b32 s78, -2
	ds_read_b128 v[96:99], v209
	ds_read_b128 v[100:103], v209 offset:1024
	ds_read_b128 v[120:123], v209 offset:2048
	ds_read_b128 v[124:127], v209 offset:3072
	ds_read_b128 v[144:147], v210
	ds_read_b128 v[148:151], v210 offset:1024
	ds_read_b128 v[152:155], v210 offset:2048
	ds_read_b128 v[156:159], v210 offset:3072
	s_add_u32 s8, s6, 0xfffc0080
	s_addc_u32 s9, s7, -1
	s_cmp_eq_u32 s78, 12
	s_cselect_b32 s51, s18, s9
	s_cselect_b32 s50, s43, s8
	s_cselect_b32 s9, s45, s57
	s_cselect_b32 s8, s55, s56
	v_lshl_add_u64 v[206:207], s[6:7], 0, v[170:171]
	s_add_i32 m0, s17, 0xc000
	ds_read_b128 v[178:181], v211
	ds_read_b128 v[182:185], v211 offset:1024
	ds_read_b128 v[186:189], v211 offset:2048
	ds_read_b128 v[190:193], v211 offset:3072
	ds_read_b128 v[194:197], v211 offset:4096
	ds_read_b128 v[198:201], v211 offset:5120
	ds_read_b128 v[202:205], v211 offset:6144
	ds_read_b128 v[218:221], v211 offset:7168
	global_load_lds_dwordx4 v[206:207], off
	s_add_i32 m0, s17, 0xe000
	v_lshl_add_u64 v[206:207], s[6:7], 0, v[172:173]
	global_load_lds_dwordx4 v[206:207], off
	s_waitcnt vmcnt(8) lgkmcnt(0)
	s_barrier
	s_setprio 1
	v_mfma_f32_16x16x32_bf16 v[140:143], v[96:99], v[178:181], 0
	v_mfma_f32_16x16x32_bf16 v[136:139], v[120:123], v[178:181], 0
	v_mfma_f32_16x16x32_bf16 v[116:119], v[96:99], v[186:189], 0
	v_mfma_f32_16x16x32_bf16 v[112:115], v[120:123], v[186:189], 0
	v_mfma_f32_16x16x32_bf16 v[92:95], v[96:99], v[194:197], 0
	v_mfma_f32_16x16x32_bf16 v[88:91], v[120:123], v[194:197], 0
	v_mfma_f32_16x16x32_bf16 v[76:79], v[96:99], v[202:205], 0
	v_mfma_f32_16x16x32_bf16 v[72:75], v[120:123], v[202:205], 0
	v_mfma_f32_16x16x32_bf16 v[140:143], v[100:103], v[182:185], v[140:143]
	v_mfma_f32_16x16x32_bf16 v[136:139], v[124:127], v[182:185], v[136:139]
	v_mfma_f32_16x16x32_bf16 v[116:119], v[100:103], v[190:193], v[116:119]
	v_mfma_f32_16x16x32_bf16 v[112:115], v[124:127], v[190:193], v[112:115]
	v_mfma_f32_16x16x32_bf16 v[92:95], v[100:103], v[198:201], v[92:95]
	v_mfma_f32_16x16x32_bf16 v[88:91], v[124:127], v[198:201], v[88:91]
	v_mfma_f32_16x16x32_bf16 v[76:79], v[100:103], v[218:221], v[76:79]
	v_mfma_f32_16x16x32_bf16 v[72:75], v[124:127], v[218:221], v[72:75]
	v_mfma_f32_16x16x32_bf16 v[132:135], v[144:147], v[178:181], 0
	v_mfma_f32_16x16x32_bf16 v[128:131], v[152:155], v[178:181], 0
	v_mfma_f32_16x16x32_bf16 v[108:111], v[144:147], v[186:189], 0
	v_mfma_f32_16x16x32_bf16 v[104:107], v[152:155], v[186:189], 0
	v_mfma_f32_16x16x32_bf16 v[84:87], v[144:147], v[194:197], 0
	v_mfma_f32_16x16x32_bf16 v[80:83], v[152:155], v[194:197], 0
	v_mfma_f32_16x16x32_bf16 v[68:71], v[144:147], v[202:205], 0
	v_mfma_f32_16x16x32_bf16 v[64:67], v[152:155], v[202:205], 0
	v_mfma_f32_16x16x32_bf16 v[132:135], v[148:151], v[182:185], v[132:135]
	v_mfma_f32_16x16x32_bf16 v[128:131], v[156:159], v[182:185], v[128:131]
	v_mfma_f32_16x16x32_bf16 v[108:111], v[148:151], v[190:193], v[108:111]
	v_mfma_f32_16x16x32_bf16 v[104:107], v[156:159], v[190:193], v[104:107]
	s_setprio 2
	s_barrier
	v_mfma_f32_16x16x32_bf16 v[84:87], v[148:151], v[198:201], v[84:87]
	v_mfma_f32_16x16x32_bf16 v[80:83], v[156:159], v[198:201], v[80:83]
	v_mfma_f32_16x16x32_bf16 v[68:71], v[148:151], v[218:221], v[68:71]
	v_mfma_f32_16x16x32_bf16 v[64:67], v[156:159], v[218:221], v[64:67]
	s_setprio 2
	s_add_i32 s79, s73, s61
	v_lshl_add_u64 v[206:207], s[8:9], 0, v[162:163]
	s_mov_b32 m0, s79
	ds_read_b128 v[178:181], v211 offset:16384
	ds_read_b128 v[182:185], v211 offset:17408
	ds_read_b128 v[186:189], v211 offset:18432
	ds_read_b128 v[190:193], v211 offset:19456
	ds_read_b128 v[194:197], v211 offset:20480
	ds_read_b128 v[198:201], v211 offset:21504
	ds_read_b128 v[202:205], v211 offset:22528
	ds_read_b128 v[218:221], v211 offset:23552
	global_load_lds_dwordx4 v[206:207], off
	s_add_i32 m0, s79, 0x2000
	s_add_u32 s80, s8, 0x40000
	v_lshl_add_u64 v[222:223], s[8:9], 0, v[166:167]
	s_addc_u32 s81, s9, 0
	s_add_i32 s79, s74, s61
	global_load_lds_dwordx4 v[222:223], off
	v_lshl_add_u64 v[224:225], s[80:81], 0, v[162:163]
	s_mov_b32 m0, s79
	v_lshl_add_u64 v[226:227], s[50:51], 0, v[164:165]
	global_load_lds_dwordx4 v[224:225], off
	s_add_i32 m0, s79, 0x2000
	v_lshl_add_u64 v[224:225], s[80:81], 0, v[166:167]
	global_load_lds_dwordx4 v[224:225], off
	s_mov_b32 m0, s17
	v_lshl_add_u64 v[224:225], s[50:51], 0, v[160:161]
	global_load_lds_dwordx4 v[224:225], off
	s_mov_b32 m0, s62
	s_nop 0
	global_load_lds_dwordx4 v[226:227], off
	s_waitcnt vmcnt(8) lgkmcnt(0)
	s_barrier
	s_setprio 1
	v_mfma_f32_16x16x32_bf16 v[60:63], v[96:99], v[178:181], 0
	v_mfma_f32_16x16x32_bf16 v[56:59], v[120:123], v[178:181], 0
	v_mfma_f32_16x16x32_bf16 v[44:47], v[96:99], v[186:189], 0
	v_mfma_f32_16x16x32_bf16 v[40:43], v[120:123], v[186:189], 0
	v_mfma_f32_16x16x32_bf16 v[28:31], v[96:99], v[194:197], 0
	v_mfma_f32_16x16x32_bf16 v[24:27], v[120:123], v[194:197], 0
	v_mfma_f32_16x16x32_bf16 v[12:15], v[96:99], v[202:205], 0
	v_mfma_f32_16x16x32_bf16 v[8:11], v[120:123], v[202:205], 0
	v_mfma_f32_16x16x32_bf16 v[60:63], v[100:103], v[182:185], v[60:63]
	v_mfma_f32_16x16x32_bf16 v[56:59], v[124:127], v[182:185], v[56:59]
	v_mfma_f32_16x16x32_bf16 v[44:47], v[100:103], v[190:193], v[44:47]
	v_mfma_f32_16x16x32_bf16 v[40:43], v[124:127], v[190:193], v[40:43]
	v_mfma_f32_16x16x32_bf16 v[28:31], v[100:103], v[198:201], v[28:31]
	v_mfma_f32_16x16x32_bf16 v[24:27], v[124:127], v[198:201], v[24:27]
	v_mfma_f32_16x16x32_bf16 v[12:15], v[100:103], v[218:221], v[12:15]
	v_mfma_f32_16x16x32_bf16 v[8:11], v[124:127], v[218:221], v[8:11]
	v_mfma_f32_16x16x32_bf16 v[52:55], v[144:147], v[178:181], 0
	v_mfma_f32_16x16x32_bf16 v[48:51], v[152:155], v[178:181], 0
	v_mfma_f32_16x16x32_bf16 v[36:39], v[144:147], v[186:189], 0
	v_mfma_f32_16x16x32_bf16 v[32:35], v[152:155], v[186:189], 0
	v_mfma_f32_16x16x32_bf16 v[20:23], v[144:147], v[194:197], 0
	v_mfma_f32_16x16x32_bf16 v[16:19], v[152:155], v[194:197], 0
	v_mfma_f32_16x16x32_bf16 v[4:7], v[144:147], v[202:205], 0
	v_mfma_f32_16x16x32_bf16 v[0:3], v[152:155], v[202:205], 0
	v_mfma_f32_16x16x32_bf16 v[52:55], v[148:151], v[182:185], v[52:55]
	v_mfma_f32_16x16x32_bf16 v[48:51], v[156:159], v[182:185], v[48:51]
	v_mfma_f32_16x16x32_bf16 v[36:39], v[148:151], v[190:193], v[36:39]
	v_mfma_f32_16x16x32_bf16 v[32:35], v[156:159], v[190:193], v[32:35]
	s_setprio 2
	s_barrier
	v_mfma_f32_16x16x32_bf16 v[20:23], v[148:151], v[198:201], v[20:23]
	v_mfma_f32_16x16x32_bf16 v[16:19], v[156:159], v[198:201], v[16:19]
	v_mfma_f32_16x16x32_bf16 v[4:7], v[148:151], v[218:221], v[4:7]
	v_mfma_f32_16x16x32_bf16 v[0:3], v[156:159], v[218:221], v[0:3]
	s_setprio 0
	s_add_i32 s79, 0, 0x18000
	s_add_i32 s80, 0, 0x1c000
	v_add_u32_e32 v124, s79, v208
	v_add_u32_e32 v156, s80, v208
	ds_read_b128 v[96:99], v124
	ds_read_b128 v[100:103], v124 offset:1024
	ds_read_b128 v[120:123], v124 offset:2048
	ds_read_b128 v[124:127], v124 offset:3072
	ds_read_b128 v[144:147], v156
	ds_read_b128 v[148:151], v156 offset:1024
	ds_read_b128 v[152:155], v156 offset:2048
	ds_read_b128 v[156:159], v156 offset:3072
	s_add_u32 s50, s50, 0x40000
	s_addc_u32 s51, s51, 0
	s_mov_b32 m0, s63
	v_lshl_add_u64 v[228:229], s[50:51], 0, v[160:161]
	ds_read_b128 v[178:181], v211 offset:32768
	ds_read_b128 v[182:185], v211 offset:33792
	ds_read_b128 v[186:189], v211 offset:34816
	ds_read_b128 v[190:193], v211 offset:35840
	ds_read_b128 v[194:197], v211 offset:36864
	ds_read_b128 v[198:201], v211 offset:37888
	ds_read_b128 v[202:205], v211 offset:38912
	ds_read_b128 v[218:221], v211 offset:39936
	global_load_lds_dwordx4 v[228:229], off
	s_mov_b32 m0, s64
	v_lshl_add_u64 v[228:229], s[50:51], 0, v[164:165]
	global_load_lds_dwordx4 v[228:229], off
	s_waitcnt vmcnt(8) lgkmcnt(0)
	s_barrier
	s_setprio 1
	v_mfma_f32_16x16x32_bf16 v[140:143], v[96:99], v[178:181], v[140:143]
	v_mfma_f32_16x16x32_bf16 v[136:139], v[120:123], v[178:181], v[136:139]
	v_mfma_f32_16x16x32_bf16 v[116:119], v[96:99], v[186:189], v[116:119]
	v_mfma_f32_16x16x32_bf16 v[112:115], v[120:123], v[186:189], v[112:115]
	v_mfma_f32_16x16x32_bf16 v[92:95], v[96:99], v[194:197], v[92:95]
	v_mfma_f32_16x16x32_bf16 v[88:91], v[120:123], v[194:197], v[88:91]
	v_mfma_f32_16x16x32_bf16 v[76:79], v[96:99], v[202:205], v[76:79]
	v_mfma_f32_16x16x32_bf16 v[72:75], v[120:123], v[202:205], v[72:75]
	v_mfma_f32_16x16x32_bf16 v[140:143], v[100:103], v[182:185], v[140:143]
	v_mfma_f32_16x16x32_bf16 v[136:139], v[124:127], v[182:185], v[136:139]
	v_mfma_f32_16x16x32_bf16 v[116:119], v[100:103], v[190:193], v[116:119]
	v_mfma_f32_16x16x32_bf16 v[112:115], v[124:127], v[190:193], v[112:115]
	v_mfma_f32_16x16x32_bf16 v[92:95], v[100:103], v[198:201], v[92:95]
	v_mfma_f32_16x16x32_bf16 v[88:91], v[124:127], v[198:201], v[88:91]
	v_mfma_f32_16x16x32_bf16 v[76:79], v[100:103], v[218:221], v[76:79]
	v_mfma_f32_16x16x32_bf16 v[72:75], v[124:127], v[218:221], v[72:75]
	v_mfma_f32_16x16x32_bf16 v[132:135], v[144:147], v[178:181], v[132:135]
	v_mfma_f32_16x16x32_bf16 v[128:131], v[152:155], v[178:181], v[128:131]
	v_mfma_f32_16x16x32_bf16 v[108:111], v[144:147], v[186:189], v[108:111]
	v_mfma_f32_16x16x32_bf16 v[104:107], v[152:155], v[186:189], v[104:107]
	v_mfma_f32_16x16x32_bf16 v[84:87], v[144:147], v[194:197], v[84:87]
	v_mfma_f32_16x16x32_bf16 v[80:83], v[152:155], v[194:197], v[80:83]
	v_mfma_f32_16x16x32_bf16 v[68:71], v[144:147], v[202:205], v[68:71]
	v_mfma_f32_16x16x32_bf16 v[64:67], v[152:155], v[202:205], v[64:67]
	v_mfma_f32_16x16x32_bf16 v[132:135], v[148:151], v[182:185], v[132:135]
	v_mfma_f32_16x16x32_bf16 v[128:131], v[156:159], v[182:185], v[128:131]
	v_mfma_f32_16x16x32_bf16 v[108:111], v[148:151], v[190:193], v[108:111]
	v_mfma_f32_16x16x32_bf16 v[104:107], v[156:159], v[190:193], v[104:107]
	s_setprio 2
	s_barrier
	v_mfma_f32_16x16x32_bf16 v[84:87], v[148:151], v[198:201], v[84:87]
	v_mfma_f32_16x16x32_bf16 v[80:83], v[156:159], v[198:201], v[80:83]
	v_mfma_f32_16x16x32_bf16 v[68:71], v[148:151], v[218:221], v[68:71]
	v_mfma_f32_16x16x32_bf16 v[64:67], v[156:159], v[218:221], v[64:67]
	s_setprio 2
	s_add_i32 s50, s79, s61
	v_lshl_add_u64 v[206:207], v[206:207], 0, s[36:37]
	s_mov_b32 m0, s50
	ds_read_b128 v[178:181], v211 offset:49152
	ds_read_b128 v[182:185], v211 offset:50176
	ds_read_b128 v[186:189], v211 offset:51200
	ds_read_b128 v[190:193], v211 offset:52224
	ds_read_b128 v[194:197], v211 offset:53248
	ds_read_b128 v[198:201], v211 offset:54272
	ds_read_b128 v[202:205], v211 offset:55296
	ds_read_b128 v[218:221], v211 offset:56320
	global_load_lds_dwordx4 v[206:207], off
	s_add_i32 m0, s50, 0x2000
	s_add_u32 s8, s8, 0x40080
	v_lshl_add_u64 v[206:207], v[222:223], 0, s[36:37]
	s_addc_u32 s9, s9, 0
	s_add_i32 s50, s80, s61
	global_load_lds_dwordx4 v[206:207], off
	s_mov_b32 m0, s50
	v_lshl_add_u64 v[206:207], s[8:9], 0, v[162:163]
	global_load_lds_dwordx4 v[206:207], off
	s_add_i32 m0, s50, 0x2000
	v_lshl_add_u64 v[206:207], s[8:9], 0, v[166:167]
	global_load_lds_dwordx4 v[206:207], off
	s_mov_b32 m0, s68
	v_lshl_add_u64 v[206:207], v[224:225], 0, s[36:37]
	global_load_lds_dwordx4 v[206:207], off
	s_mov_b32 m0, s69
	v_lshl_add_u64 v[206:207], v[226:227], 0, s[36:37]
	global_load_lds_dwordx4 v[206:207], off
	s_waitcnt vmcnt(8) lgkmcnt(0)
	s_barrier
	s_setprio 1
	v_mfma_f32_16x16x32_bf16 v[60:63], v[96:99], v[178:181], v[60:63]
	v_mfma_f32_16x16x32_bf16 v[56:59], v[120:123], v[178:181], v[56:59]
	v_mfma_f32_16x16x32_bf16 v[44:47], v[96:99], v[186:189], v[44:47]
	v_mfma_f32_16x16x32_bf16 v[40:43], v[120:123], v[186:189], v[40:43]
	v_mfma_f32_16x16x32_bf16 v[28:31], v[96:99], v[194:197], v[28:31]
	v_mfma_f32_16x16x32_bf16 v[24:27], v[120:123], v[194:197], v[24:27]
	v_mfma_f32_16x16x32_bf16 v[12:15], v[96:99], v[202:205], v[12:15]
	v_mfma_f32_16x16x32_bf16 v[8:11], v[120:123], v[202:205], v[8:11]
	v_mfma_f32_16x16x32_bf16 v[60:63], v[100:103], v[182:185], v[60:63]
	v_mfma_f32_16x16x32_bf16 v[56:59], v[124:127], v[182:185], v[56:59]
	v_mfma_f32_16x16x32_bf16 v[44:47], v[100:103], v[190:193], v[44:47]
	v_mfma_f32_16x16x32_bf16 v[40:43], v[124:127], v[190:193], v[40:43]
	v_mfma_f32_16x16x32_bf16 v[28:31], v[100:103], v[198:201], v[28:31]
	v_mfma_f32_16x16x32_bf16 v[24:27], v[124:127], v[198:201], v[24:27]
	v_mfma_f32_16x16x32_bf16 v[12:15], v[100:103], v[218:221], v[12:15]
	v_mfma_f32_16x16x32_bf16 v[8:11], v[124:127], v[218:221], v[8:11]
	v_mfma_f32_16x16x32_bf16 v[52:55], v[144:147], v[178:181], v[52:55]
	v_mfma_f32_16x16x32_bf16 v[48:51], v[152:155], v[178:181], v[48:51]
	v_mfma_f32_16x16x32_bf16 v[36:39], v[144:147], v[186:189], v[36:39]
	v_mfma_f32_16x16x32_bf16 v[32:35], v[152:155], v[186:189], v[32:35]
	v_mfma_f32_16x16x32_bf16 v[20:23], v[144:147], v[194:197], v[20:23]
	v_mfma_f32_16x16x32_bf16 v[16:19], v[152:155], v[194:197], v[16:19]
	v_mfma_f32_16x16x32_bf16 v[4:7], v[144:147], v[202:205], v[4:7]
	v_mfma_f32_16x16x32_bf16 v[0:3], v[152:155], v[202:205], v[0:3]
	v_mfma_f32_16x16x32_bf16 v[52:55], v[148:151], v[182:185], v[52:55]
	v_mfma_f32_16x16x32_bf16 v[48:51], v[156:159], v[182:185], v[48:51]
	v_mfma_f32_16x16x32_bf16 v[36:39], v[148:151], v[190:193], v[36:39]
	v_mfma_f32_16x16x32_bf16 v[32:35], v[156:159], v[190:193], v[32:35]
	s_setprio 2
	s_barrier
	v_mfma_f32_16x16x32_bf16 v[20:23], v[148:151], v[198:201], v[20:23]
	v_mfma_f32_16x16x32_bf16 v[16:19], v[156:159], v[198:201], v[16:19]
	v_mfma_f32_16x16x32_bf16 v[4:7], v[148:151], v[218:221], v[4:7]
	v_mfma_f32_16x16x32_bf16 v[0:3], v[156:159], v[218:221], v[0:3]
	s_setprio 0
	s_add_i32 s78, s78, 2
	s_add_u32 s6, s6, 0x100
	s_addc_u32 s7, s7, 0
	s_add_u32 s56, s56, 0x100
	s_addc_u32 s57, s57, 0
	s_cmp_gt_u32 s78, 13
.LBB0_323:
	ds_read_b128 v[96:99], v209
	ds_read_b128 v[100:103], v209 offset:1024
	ds_read_b128 v[120:123], v209 offset:2048
	ds_read_b128 v[124:127], v209 offset:3072
	ds_read_b128 v[144:147], v210
	ds_read_b128 v[148:151], v210 offset:1024
	ds_read_b128 v[152:155], v210 offset:2048
	ds_read_b128 v[156:159], v210 offset:3072
	s_add_u32 s8, s6, 0xfffc0080
	s_addc_u32 s9, s7, -1
	s_cmp_eq_u32 s78, 12
	s_cselect_b32 s51, s18, s9
	s_cselect_b32 s50, s43, s8
	s_cselect_b32 s9, s45, s57
	s_cselect_b32 s8, s55, s56
	v_lshl_add_u64 v[206:207], s[6:7], 0, v[170:171]
	s_add_i32 m0, s17, 0xc000
	ds_read_b128 v[178:181], v211
	ds_read_b128 v[182:185], v211 offset:1024
	ds_read_b128 v[186:189], v211 offset:2048
	ds_read_b128 v[190:193], v211 offset:3072
	ds_read_b128 v[194:197], v211 offset:4096
	ds_read_b128 v[198:201], v211 offset:5120
	ds_read_b128 v[202:205], v211 offset:6144
	ds_read_b128 v[218:221], v211 offset:7168
	global_load_lds_dwordx4 v[206:207], off
	s_add_i32 m0, s17, 0xe000
	v_lshl_add_u64 v[206:207], s[6:7], 0, v[172:173]
	global_load_lds_dwordx4 v[206:207], off
	s_waitcnt vmcnt(8) lgkmcnt(0)
	s_barrier
	s_setprio 1
	v_mfma_f32_16x16x32_bf16 v[140:143], v[96:99], v[178:181], v[140:143]
	v_mfma_f32_16x16x32_bf16 v[136:139], v[120:123], v[178:181], v[136:139]
	v_mfma_f32_16x16x32_bf16 v[116:119], v[96:99], v[186:189], v[116:119]
	v_mfma_f32_16x16x32_bf16 v[112:115], v[120:123], v[186:189], v[112:115]
	v_mfma_f32_16x16x32_bf16 v[92:95], v[96:99], v[194:197], v[92:95]
	v_mfma_f32_16x16x32_bf16 v[88:91], v[120:123], v[194:197], v[88:91]
	v_mfma_f32_16x16x32_bf16 v[76:79], v[96:99], v[202:205], v[76:79]
	v_mfma_f32_16x16x32_bf16 v[72:75], v[120:123], v[202:205], v[72:75]
	v_mfma_f32_16x16x32_bf16 v[140:143], v[100:103], v[182:185], v[140:143]
	v_mfma_f32_16x16x32_bf16 v[136:139], v[124:127], v[182:185], v[136:139]
	v_mfma_f32_16x16x32_bf16 v[116:119], v[100:103], v[190:193], v[116:119]
	v_mfma_f32_16x16x32_bf16 v[112:115], v[124:127], v[190:193], v[112:115]
	v_mfma_f32_16x16x32_bf16 v[92:95], v[100:103], v[198:201], v[92:95]
	v_mfma_f32_16x16x32_bf16 v[88:91], v[124:127], v[198:201], v[88:91]
	v_mfma_f32_16x16x32_bf16 v[76:79], v[100:103], v[218:221], v[76:79]
	v_mfma_f32_16x16x32_bf16 v[72:75], v[124:127], v[218:221], v[72:75]
	v_mfma_f32_16x16x32_bf16 v[132:135], v[144:147], v[178:181], v[132:135]
	v_mfma_f32_16x16x32_bf16 v[128:131], v[152:155], v[178:181], v[128:131]
	v_mfma_f32_16x16x32_bf16 v[108:111], v[144:147], v[186:189], v[108:111]
	v_mfma_f32_16x16x32_bf16 v[104:107], v[152:155], v[186:189], v[104:107]
	v_mfma_f32_16x16x32_bf16 v[84:87], v[144:147], v[194:197], v[84:87]
	v_mfma_f32_16x16x32_bf16 v[80:83], v[152:155], v[194:197], v[80:83]
	v_mfma_f32_16x16x32_bf16 v[68:71], v[144:147], v[202:205], v[68:71]
	v_mfma_f32_16x16x32_bf16 v[64:67], v[152:155], v[202:205], v[64:67]
	v_mfma_f32_16x16x32_bf16 v[132:135], v[148:151], v[182:185], v[132:135]
	v_mfma_f32_16x16x32_bf16 v[128:131], v[156:159], v[182:185], v[128:131]
	v_mfma_f32_16x16x32_bf16 v[108:111], v[148:151], v[190:193], v[108:111]
	v_mfma_f32_16x16x32_bf16 v[104:107], v[156:159], v[190:193], v[104:107]
	s_setprio 2
	s_barrier
	v_mfma_f32_16x16x32_bf16 v[84:87], v[148:151], v[198:201], v[84:87]
	v_mfma_f32_16x16x32_bf16 v[80:83], v[156:159], v[198:201], v[80:83]
	v_mfma_f32_16x16x32_bf16 v[68:71], v[148:151], v[218:221], v[68:71]
	v_mfma_f32_16x16x32_bf16 v[64:67], v[156:159], v[218:221], v[64:67]
	s_setprio 2
	s_add_i32 s79, s73, s61
	v_lshl_add_u64 v[206:207], s[8:9], 0, v[162:163]
	s_mov_b32 m0, s79
	ds_read_b128 v[178:181], v211 offset:16384
	ds_read_b128 v[182:185], v211 offset:17408
	ds_read_b128 v[186:189], v211 offset:18432
	ds_read_b128 v[190:193], v211 offset:19456
	ds_read_b128 v[194:197], v211 offset:20480
	ds_read_b128 v[198:201], v211 offset:21504
	ds_read_b128 v[202:205], v211 offset:22528
	ds_read_b128 v[218:221], v211 offset:23552
	global_load_lds_dwordx4 v[206:207], off
	s_add_i32 m0, s79, 0x2000
	s_add_u32 s80, s8, 0x40000
	v_lshl_add_u64 v[222:223], s[8:9], 0, v[166:167]
	s_addc_u32 s81, s9, 0
	s_add_i32 s79, s74, s61
	global_load_lds_dwordx4 v[222:223], off
	v_lshl_add_u64 v[224:225], s[80:81], 0, v[162:163]
	s_mov_b32 m0, s79
	v_lshl_add_u64 v[226:227], s[50:51], 0, v[164:165]
	global_load_lds_dwordx4 v[224:225], off
	s_add_i32 m0, s79, 0x2000
	v_lshl_add_u64 v[224:225], s[80:81], 0, v[166:167]
	global_load_lds_dwordx4 v[224:225], off
	s_mov_b32 m0, s17
	v_lshl_add_u64 v[224:225], s[50:51], 0, v[160:161]
	global_load_lds_dwordx4 v[224:225], off
	s_mov_b32 m0, s62
	s_nop 0
	global_load_lds_dwordx4 v[226:227], off
	s_waitcnt vmcnt(8) lgkmcnt(0)
	s_barrier
	s_setprio 1
	v_mfma_f32_16x16x32_bf16 v[60:63], v[96:99], v[178:181], v[60:63]
	v_mfma_f32_16x16x32_bf16 v[56:59], v[120:123], v[178:181], v[56:59]
	v_mfma_f32_16x16x32_bf16 v[44:47], v[96:99], v[186:189], v[44:47]
	v_mfma_f32_16x16x32_bf16 v[40:43], v[120:123], v[186:189], v[40:43]
	v_mfma_f32_16x16x32_bf16 v[28:31], v[96:99], v[194:197], v[28:31]
	v_mfma_f32_16x16x32_bf16 v[24:27], v[120:123], v[194:197], v[24:27]
	v_mfma_f32_16x16x32_bf16 v[12:15], v[96:99], v[202:205], v[12:15]
	v_mfma_f32_16x16x32_bf16 v[8:11], v[120:123], v[202:205], v[8:11]
	v_mfma_f32_16x16x32_bf16 v[60:63], v[100:103], v[182:185], v[60:63]
	v_mfma_f32_16x16x32_bf16 v[56:59], v[124:127], v[182:185], v[56:59]
	v_mfma_f32_16x16x32_bf16 v[44:47], v[100:103], v[190:193], v[44:47]
	v_mfma_f32_16x16x32_bf16 v[40:43], v[124:127], v[190:193], v[40:43]
	v_mfma_f32_16x16x32_bf16 v[28:31], v[100:103], v[198:201], v[28:31]
	v_mfma_f32_16x16x32_bf16 v[24:27], v[124:127], v[198:201], v[24:27]
	v_mfma_f32_16x16x32_bf16 v[12:15], v[100:103], v[218:221], v[12:15]
	v_mfma_f32_16x16x32_bf16 v[8:11], v[124:127], v[218:221], v[8:11]
	v_mfma_f32_16x16x32_bf16 v[52:55], v[144:147], v[178:181], v[52:55]
	v_mfma_f32_16x16x32_bf16 v[48:51], v[152:155], v[178:181], v[48:51]
	v_mfma_f32_16x16x32_bf16 v[36:39], v[144:147], v[186:189], v[36:39]
	v_mfma_f32_16x16x32_bf16 v[32:35], v[152:155], v[186:189], v[32:35]
	v_mfma_f32_16x16x32_bf16 v[20:23], v[144:147], v[194:197], v[20:23]
	v_mfma_f32_16x16x32_bf16 v[16:19], v[152:155], v[194:197], v[16:19]
	v_mfma_f32_16x16x32_bf16 v[4:7], v[144:147], v[202:205], v[4:7]
	v_mfma_f32_16x16x32_bf16 v[0:3], v[152:155], v[202:205], v[0:3]
	v_mfma_f32_16x16x32_bf16 v[52:55], v[148:151], v[182:185], v[52:55]
	v_mfma_f32_16x16x32_bf16 v[48:51], v[156:159], v[182:185], v[48:51]
	v_mfma_f32_16x16x32_bf16 v[36:39], v[148:151], v[190:193], v[36:39]
	v_mfma_f32_16x16x32_bf16 v[32:35], v[156:159], v[190:193], v[32:35]
	s_setprio 2
	s_barrier
	v_mfma_f32_16x16x32_bf16 v[20:23], v[148:151], v[198:201], v[20:23]
	v_mfma_f32_16x16x32_bf16 v[16:19], v[156:159], v[198:201], v[16:19]
	v_mfma_f32_16x16x32_bf16 v[4:7], v[148:151], v[218:221], v[4:7]
	v_mfma_f32_16x16x32_bf16 v[0:3], v[156:159], v[218:221], v[0:3]
	s_setprio 0
	s_add_i32 s79, 0, 0x18000
	s_add_i32 s80, 0, 0x1c000
	v_add_u32_e32 v124, s79, v208
	v_add_u32_e32 v156, s80, v208
	ds_read_b128 v[96:99], v124
	ds_read_b128 v[100:103], v124 offset:1024
	ds_read_b128 v[120:123], v124 offset:2048
	ds_read_b128 v[124:127], v124 offset:3072
	ds_read_b128 v[144:147], v156
	ds_read_b128 v[148:151], v156 offset:1024
	ds_read_b128 v[152:155], v156 offset:2048
	ds_read_b128 v[156:159], v156 offset:3072
	s_add_u32 s50, s50, 0x40000
	s_addc_u32 s51, s51, 0
	s_mov_b32 m0, s63
	v_lshl_add_u64 v[228:229], s[50:51], 0, v[160:161]
	ds_read_b128 v[178:181], v211 offset:32768
	ds_read_b128 v[182:185], v211 offset:33792
	ds_read_b128 v[186:189], v211 offset:34816
	ds_read_b128 v[190:193], v211 offset:35840
	ds_read_b128 v[194:197], v211 offset:36864
	ds_read_b128 v[198:201], v211 offset:37888
	ds_read_b128 v[202:205], v211 offset:38912
	ds_read_b128 v[218:221], v211 offset:39936
	global_load_lds_dwordx4 v[228:229], off
	s_mov_b32 m0, s64
	v_lshl_add_u64 v[228:229], s[50:51], 0, v[164:165]
	global_load_lds_dwordx4 v[228:229], off
	s_waitcnt vmcnt(8) lgkmcnt(0)
	s_barrier
	s_setprio 1
	v_mfma_f32_16x16x32_bf16 v[140:143], v[96:99], v[178:181], v[140:143]
	v_mfma_f32_16x16x32_bf16 v[136:139], v[120:123], v[178:181], v[136:139]
	v_mfma_f32_16x16x32_bf16 v[116:119], v[96:99], v[186:189], v[116:119]
	v_mfma_f32_16x16x32_bf16 v[112:115], v[120:123], v[186:189], v[112:115]
	v_mfma_f32_16x16x32_bf16 v[92:95], v[96:99], v[194:197], v[92:95]
	v_mfma_f32_16x16x32_bf16 v[88:91], v[120:123], v[194:197], v[88:91]
	v_mfma_f32_16x16x32_bf16 v[76:79], v[96:99], v[202:205], v[76:79]
	v_mfma_f32_16x16x32_bf16 v[72:75], v[120:123], v[202:205], v[72:75]
	v_mfma_f32_16x16x32_bf16 v[140:143], v[100:103], v[182:185], v[140:143]
	v_mfma_f32_16x16x32_bf16 v[136:139], v[124:127], v[182:185], v[136:139]
	v_mfma_f32_16x16x32_bf16 v[116:119], v[100:103], v[190:193], v[116:119]
	v_mfma_f32_16x16x32_bf16 v[112:115], v[124:127], v[190:193], v[112:115]
	v_mfma_f32_16x16x32_bf16 v[92:95], v[100:103], v[198:201], v[92:95]
	v_mfma_f32_16x16x32_bf16 v[88:91], v[124:127], v[198:201], v[88:91]
	v_mfma_f32_16x16x32_bf16 v[76:79], v[100:103], v[218:221], v[76:79]
	v_mfma_f32_16x16x32_bf16 v[72:75], v[124:127], v[218:221], v[72:75]
	v_mfma_f32_16x16x32_bf16 v[132:135], v[144:147], v[178:181], v[132:135]
	v_mfma_f32_16x16x32_bf16 v[128:131], v[152:155], v[178:181], v[128:131]
	v_mfma_f32_16x16x32_bf16 v[108:111], v[144:147], v[186:189], v[108:111]
	v_mfma_f32_16x16x32_bf16 v[104:107], v[152:155], v[186:189], v[104:107]
	v_mfma_f32_16x16x32_bf16 v[84:87], v[144:147], v[194:197], v[84:87]
	v_mfma_f32_16x16x32_bf16 v[80:83], v[152:155], v[194:197], v[80:83]
	v_mfma_f32_16x16x32_bf16 v[68:71], v[144:147], v[202:205], v[68:71]
	v_mfma_f32_16x16x32_bf16 v[64:67], v[152:155], v[202:205], v[64:67]
	v_mfma_f32_16x16x32_bf16 v[132:135], v[148:151], v[182:185], v[132:135]
	v_mfma_f32_16x16x32_bf16 v[128:131], v[156:159], v[182:185], v[128:131]
	v_mfma_f32_16x16x32_bf16 v[108:111], v[148:151], v[190:193], v[108:111]
	v_mfma_f32_16x16x32_bf16 v[104:107], v[156:159], v[190:193], v[104:107]
	s_setprio 2
	s_barrier
	v_mfma_f32_16x16x32_bf16 v[84:87], v[148:151], v[198:201], v[84:87]
	v_mfma_f32_16x16x32_bf16 v[80:83], v[156:159], v[198:201], v[80:83]
	v_mfma_f32_16x16x32_bf16 v[68:71], v[148:151], v[218:221], v[68:71]
	v_mfma_f32_16x16x32_bf16 v[64:67], v[156:159], v[218:221], v[64:67]
	s_setprio 2
	s_add_i32 s50, s79, s61
	v_lshl_add_u64 v[206:207], v[206:207], 0, s[36:37]
	s_mov_b32 m0, s50
	ds_read_b128 v[178:181], v211 offset:49152
	ds_read_b128 v[182:185], v211 offset:50176
	ds_read_b128 v[186:189], v211 offset:51200
	ds_read_b128 v[190:193], v211 offset:52224
	ds_read_b128 v[194:197], v211 offset:53248
	ds_read_b128 v[198:201], v211 offset:54272
	ds_read_b128 v[202:205], v211 offset:55296
	ds_read_b128 v[218:221], v211 offset:56320
	global_load_lds_dwordx4 v[206:207], off
	s_add_i32 m0, s50, 0x2000
	s_add_u32 s8, s8, 0x40080
	v_lshl_add_u64 v[206:207], v[222:223], 0, s[36:37]
	s_addc_u32 s9, s9, 0
	s_add_i32 s50, s80, s61
	global_load_lds_dwordx4 v[206:207], off
	s_mov_b32 m0, s50
	v_lshl_add_u64 v[206:207], s[8:9], 0, v[162:163]
	global_load_lds_dwordx4 v[206:207], off
	s_add_i32 m0, s50, 0x2000
	v_lshl_add_u64 v[206:207], s[8:9], 0, v[166:167]
	global_load_lds_dwordx4 v[206:207], off
	s_mov_b32 m0, s68
	v_lshl_add_u64 v[206:207], v[224:225], 0, s[36:37]
	global_load_lds_dwordx4 v[206:207], off
	s_mov_b32 m0, s69
	v_lshl_add_u64 v[206:207], v[226:227], 0, s[36:37]
	global_load_lds_dwordx4 v[206:207], off
	s_waitcnt vmcnt(8) lgkmcnt(0)
	s_barrier
	s_setprio 1
	v_mfma_f32_16x16x32_bf16 v[60:63], v[96:99], v[178:181], v[60:63]
	v_mfma_f32_16x16x32_bf16 v[56:59], v[120:123], v[178:181], v[56:59]
	v_mfma_f32_16x16x32_bf16 v[44:47], v[96:99], v[186:189], v[44:47]
	v_mfma_f32_16x16x32_bf16 v[40:43], v[120:123], v[186:189], v[40:43]
	v_mfma_f32_16x16x32_bf16 v[28:31], v[96:99], v[194:197], v[28:31]
	v_mfma_f32_16x16x32_bf16 v[24:27], v[120:123], v[194:197], v[24:27]
	v_mfma_f32_16x16x32_bf16 v[12:15], v[96:99], v[202:205], v[12:15]
	v_mfma_f32_16x16x32_bf16 v[8:11], v[120:123], v[202:205], v[8:11]
	v_mfma_f32_16x16x32_bf16 v[60:63], v[100:103], v[182:185], v[60:63]
	v_mfma_f32_16x16x32_bf16 v[56:59], v[124:127], v[182:185], v[56:59]
	v_mfma_f32_16x16x32_bf16 v[44:47], v[100:103], v[190:193], v[44:47]
	v_mfma_f32_16x16x32_bf16 v[40:43], v[124:127], v[190:193], v[40:43]
	v_mfma_f32_16x16x32_bf16 v[28:31], v[100:103], v[198:201], v[28:31]
	v_mfma_f32_16x16x32_bf16 v[24:27], v[124:127], v[198:201], v[24:27]
	v_mfma_f32_16x16x32_bf16 v[12:15], v[100:103], v[218:221], v[12:15]
	v_mfma_f32_16x16x32_bf16 v[8:11], v[124:127], v[218:221], v[8:11]
	v_mfma_f32_16x16x32_bf16 v[52:55], v[144:147], v[178:181], v[52:55]
	v_mfma_f32_16x16x32_bf16 v[48:51], v[152:155], v[178:181], v[48:51]
	v_mfma_f32_16x16x32_bf16 v[36:39], v[144:147], v[186:189], v[36:39]
	v_mfma_f32_16x16x32_bf16 v[32:35], v[152:155], v[186:189], v[32:35]
	v_mfma_f32_16x16x32_bf16 v[20:23], v[144:147], v[194:197], v[20:23]
	v_mfma_f32_16x16x32_bf16 v[16:19], v[152:155], v[194:197], v[16:19]
	v_mfma_f32_16x16x32_bf16 v[4:7], v[144:147], v[202:205], v[4:7]
	v_mfma_f32_16x16x32_bf16 v[0:3], v[152:155], v[202:205], v[0:3]
	v_mfma_f32_16x16x32_bf16 v[52:55], v[148:151], v[182:185], v[52:55]
	v_mfma_f32_16x16x32_bf16 v[48:51], v[156:159], v[182:185], v[48:51]
	v_mfma_f32_16x16x32_bf16 v[36:39], v[148:151], v[190:193], v[36:39]
	v_mfma_f32_16x16x32_bf16 v[32:35], v[156:159], v[190:193], v[32:35]
	s_setprio 2
	s_barrier
	v_mfma_f32_16x16x32_bf16 v[20:23], v[148:151], v[198:201], v[20:23]
	v_mfma_f32_16x16x32_bf16 v[16:19], v[156:159], v[198:201], v[16:19]
	v_mfma_f32_16x16x32_bf16 v[4:7], v[148:151], v[218:221], v[4:7]
	v_mfma_f32_16x16x32_bf16 v[0:3], v[156:159], v[218:221], v[0:3]
	s_setprio 0
	s_add_i32 s78, s78, 2
	s_add_u32 s6, s6, 0x100
	s_addc_u32 s7, s7, 0
	s_add_u32 s56, s56, 0x100
	s_addc_u32 s57, s57, 0
	s_cmp_gt_u32 s78, 13
	s_cbranch_scc0 .LBB0_323

.LBB0_697:
	s_and_b32 s29, s69, 0x1000
	s_add_i32 s70, s66, s29
	s_ashr_i32 s29, s28, 31
	ds_read_b128 v[0:3], v195 offset:3072
	ds_read_b128 v[4:7], v195 offset:2048
	ds_read_b128 v[8:11], v195 offset:1024
	ds_read_b128 v[12:15], v195
	ds_read_b128 v[16:19], v203 offset:3072
	ds_read_b128 v[20:23], v203 offset:2048
	ds_read_b128 v[24:27], v203 offset:1024
	ds_read_b128 v[28:31], v203
	s_lshl_b64 s[36:37], s[28:29], 20
	s_add_u32 s36, s50, s36
	s_addc_u32 s37, s51, s37
	s_and_b64 s[38:39], s[4:5], exec
	s_cselect_b32 s29, s37, s45
	s_cselect_b32 s71, s36, s44
	s_ashr_i32 s31, s30, 31
	s_lshl_b64 s[38:39], s[30:31], 20
	s_add_u32 s38, s54, s38
	s_addc_u32 s39, s55, s39
	s_and_b64 s[48:49], s[4:5], exec
	s_cselect_b32 s31, s39, s47
	s_cselect_b32 s72, s38, s46
	s_add_u32 s48, s44, 0x80080
	s_addc_u32 s49, s45, 0
	s_add_i32 s73, s56, 0xc000
	v_lshl_add_u64 v[64:65], s[48:49], 0, v[176:177]
	s_mov_b32 m0, s73
	s_add_i32 s74, s56, 0xe000
	ds_read_b128 v[32:35], v211
	ds_read_b128 v[36:39], v211 offset:1024
	ds_read_b128 v[40:43], v211 offset:2048
	ds_read_b128 v[44:47], v211 offset:3072
	ds_read_b128 v[48:51], v211 offset:4096
	ds_read_b128 v[52:55], v211 offset:5120
	ds_read_b128 v[56:59], v211 offset:6144
	ds_read_b128 v[60:63], v211 offset:7168
	global_load_lds_dwordx4 v[64:65], off
	s_mov_b32 m0, s74
	v_lshl_add_u64 v[64:65], s[48:49], 0, v[178:179]
	global_load_lds_dwordx4 v[64:65], off
	s_waitcnt vmcnt(8) lgkmcnt(0)
	s_barrier
	s_setprio 1
	v_mfma_f32_16x16x32_bf16 v[88:91], v[28:31], v[56:59], 0
	v_mfma_f32_16x16x32_bf16 v[64:67], v[28:31], v[32:35], 0
	v_mfma_f32_16x16x32_bf16 v[68:71], v[20:23], v[32:35], 0
	v_mfma_f32_16x16x32_bf16 v[72:75], v[28:31], v[40:43], 0
	v_mfma_f32_16x16x32_bf16 v[76:79], v[20:23], v[40:43], 0
	v_mfma_f32_16x16x32_bf16 v[80:83], v[28:31], v[48:51], 0
	v_mfma_f32_16x16x32_bf16 v[84:87], v[20:23], v[48:51], 0
	v_mfma_f32_16x16x32_bf16 v[96:99], v[24:27], v[60:63], v[88:91]
	v_mfma_f32_16x16x32_bf16 v[88:91], v[20:23], v[56:59], 0
	v_mfma_f32_16x16x32_bf16 v[64:67], v[24:27], v[36:39], v[64:67]
	v_mfma_f32_16x16x32_bf16 v[68:71], v[16:19], v[36:39], v[68:71]
	v_mfma_f32_16x16x32_bf16 v[72:75], v[24:27], v[44:47], v[72:75]
	v_mfma_f32_16x16x32_bf16 v[76:79], v[16:19], v[44:47], v[76:79]
	v_mfma_f32_16x16x32_bf16 v[80:83], v[24:27], v[52:55], v[80:83]
	v_mfma_f32_16x16x32_bf16 v[84:87], v[16:19], v[52:55], v[84:87]
	v_mfma_f32_16x16x32_bf16 v[100:103], v[16:19], v[60:63], v[88:91]
	v_mfma_f32_16x16x32_bf16 v[88:91], v[12:15], v[32:35], 0
	v_mfma_f32_16x16x32_bf16 v[32:35], v[4:7], v[32:35], 0
	v_mfma_f32_16x16x32_bf16 v[112:115], v[8:11], v[36:39], v[88:91]
	v_mfma_f32_16x16x32_bf16 v[32:35], v[0:3], v[36:39], v[32:35]
	v_mfma_f32_16x16x32_bf16 v[36:39], v[12:15], v[40:43], 0
	v_mfma_f32_16x16x32_bf16 v[40:43], v[4:7], v[40:43], 0
	v_mfma_f32_16x16x32_bf16 v[36:39], v[8:11], v[44:47], v[36:39]
	v_mfma_f32_16x16x32_bf16 v[40:43], v[0:3], v[44:47], v[40:43]
	v_mfma_f32_16x16x32_bf16 v[44:47], v[12:15], v[48:51], 0
	v_mfma_f32_16x16x32_bf16 v[48:51], v[4:7], v[48:51], 0
	v_mfma_f32_16x16x32_bf16 v[44:47], v[8:11], v[52:55], v[44:47]
	v_mfma_f32_16x16x32_bf16 v[48:51], v[0:3], v[52:55], v[48:51]
	s_setprio 2
	s_barrier
	v_mfma_f32_16x16x32_bf16 v[52:55], v[12:15], v[56:59], 0
	v_mfma_f32_16x16x32_bf16 v[56:59], v[4:7], v[56:59], 0
	v_mfma_f32_16x16x32_bf16 v[52:55], v[8:11], v[60:63], v[52:55]
	v_mfma_f32_16x16x32_bf16 v[56:59], v[0:3], v[60:63], v[56:59]
	s_setprio 2
	s_add_i32 s75, s68, s43
	v_lshl_add_u64 v[174:175], s[46:47], 0, v[176:177]
	s_add_i32 s76, s75, 0x2000
	v_lshl_add_u64 v[128:129], v[174:175], 0, s[24:25]
	s_mov_b32 m0, s75
	v_lshl_add_u64 v[200:201], s[46:47], 0, v[178:179]
	s_add_u32 s48, s46, 0x80100
	ds_read_b128 v[60:63], v211 offset:16384
	ds_read_b128 v[88:91], v211 offset:17408
	ds_read_b128 v[92:95], v211 offset:18432
	ds_read_b128 v[104:107], v211 offset:19456
	ds_read_b128 v[108:111], v211 offset:20480
	ds_read_b128 v[116:119], v211 offset:21504
	ds_read_b128 v[120:123], v211 offset:22528
	ds_read_b128 v[124:127], v211 offset:23552
	global_load_lds_dwordx4 v[128:129], off
	v_lshl_add_u64 v[128:129], v[200:201], 0, s[24:25]
	s_mov_b32 m0, s76
	s_addc_u32 s49, s47, 0
	s_add_i32 s77, s67, s43
	global_load_lds_dwordx4 v[128:129], off
	v_lshl_add_u64 v[128:129], s[48:49], 0, v[176:177]
	s_mov_b32 m0, s77
	s_add_i32 s78, s77, 0x2000
	global_load_lds_dwordx4 v[128:129], off
	v_lshl_add_u64 v[128:129], s[48:49], 0, v[178:179]
	s_mov_b32 m0, s78
	v_lshl_add_u64 v[208:209], s[44:45], 0, v[176:177]
	global_load_lds_dwordx4 v[128:129], off
	v_lshl_add_u64 v[128:129], v[208:209], 0, s[24:25]
	s_mov_b32 m0, s56
	v_lshl_add_u64 v[252:253], s[44:45], 0, v[178:179]
	global_load_lds_dwordx4 v[128:129], off
	s_mov_b32 m0, s57
	v_lshl_add_u64 v[128:129], v[252:253], 0, s[24:25]
	global_load_lds_dwordx4 v[128:129], off
	s_waitcnt vmcnt(8) lgkmcnt(0)
	s_barrier
	s_setprio 1
	v_mfma_f32_16x16x32_bf16 v[134:137], v[20:23], v[60:63], 0
	v_mfma_f32_16x16x32_bf16 v[142:145], v[20:23], v[92:95], 0
	v_mfma_f32_16x16x32_bf16 v[150:153], v[20:23], v[108:111], 0
	v_mfma_f32_16x16x32_bf16 v[20:23], v[20:23], v[120:123], 0
	v_mfma_f32_16x16x32_bf16 v[128:131], v[28:31], v[60:63], 0
	v_mfma_f32_16x16x32_bf16 v[134:137], v[16:19], v[88:91], v[134:137]
	v_mfma_f32_16x16x32_bf16 v[138:141], v[28:31], v[92:95], 0
	v_mfma_f32_16x16x32_bf16 v[142:145], v[16:19], v[104:107], v[142:145]
	v_mfma_f32_16x16x32_bf16 v[146:149], v[28:31], v[108:111], 0
	v_mfma_f32_16x16x32_bf16 v[150:153], v[16:19], v[116:119], v[150:153]
	v_mfma_f32_16x16x32_bf16 v[28:31], v[28:31], v[120:123], 0
	v_mfma_f32_16x16x32_bf16 v[16:19], v[16:19], v[124:127], v[20:23]
	v_mfma_f32_16x16x32_bf16 v[130:133], v[24:27], v[88:91], v[128:131]
	v_mfma_f32_16x16x32_bf16 v[138:141], v[24:27], v[104:107], v[138:141]
	v_mfma_f32_16x16x32_bf16 v[146:149], v[24:27], v[116:119], v[146:149]
	v_mfma_f32_16x16x32_bf16 v[154:157], v[24:27], v[124:127], v[28:31]
	v_mfma_f32_16x16x32_bf16 v[24:27], v[4:7], v[60:63], 0
	v_mfma_f32_16x16x32_bf16 v[158:161], v[0:3], v[88:91], v[24:27]
	v_mfma_f32_16x16x32_bf16 v[24:27], v[12:15], v[92:95], 0
	v_mfma_f32_16x16x32_bf16 v[162:165], v[8:11], v[104:107], v[24:27]
	v_mfma_f32_16x16x32_bf16 v[24:27], v[4:7], v[92:95], 0
	v_mfma_f32_16x16x32_bf16 v[166:169], v[0:3], v[104:107], v[24:27]
	v_mfma_f32_16x16x32_bf16 v[24:27], v[12:15], v[108:111], 0
	v_mfma_f32_16x16x32_bf16 v[20:23], v[12:15], v[60:63], 0
	v_mfma_f32_16x16x32_bf16 v[170:173], v[8:11], v[116:119], v[24:27]
	v_mfma_f32_16x16x32_bf16 v[24:27], v[4:7], v[108:111], 0
	v_mfma_f32_16x16x32_bf16 v[4:7], v[4:7], v[120:123], 0
	v_mfma_f32_16x16x32_bf16 v[20:23], v[8:11], v[88:91], v[20:23]
	s_setprio 2
	s_barrier
	v_mfma_f32_16x16x32_bf16 v[190:193], v[0:3], v[116:119], v[24:27]
	v_mfma_f32_16x16x32_bf16 v[12:15], v[12:15], v[120:123], 0
	v_mfma_f32_16x16x32_bf16 v[0:3], v[0:3], v[124:127], v[4:7]
	v_mfma_f32_16x16x32_bf16 v[196:199], v[8:11], v[124:127], v[12:15]
	s_setprio 0
	s_add_i32 s79, 0, 0x18000
	s_add_i32 s81, 0, 0x1c000
	v_add_u32_e32 v128, s79, v189
	v_add_u32_e32 v129, s81, v189
	ds_read_b128 v[4:7], v128
	ds_read_b128 v[8:11], v128 offset:1024
	ds_read_b128 v[204:207], v128 offset:2048
	ds_read_b128 v[212:215], v128 offset:3072
	ds_read_b128 v[216:219], v129
	ds_read_b128 v[220:223], v129 offset:1024
	ds_read_b128 v[224:227], v129 offset:2048
	ds_read_b128 v[228:231], v129 offset:3072
	s_add_u32 s48, s44, 0x80100
	s_addc_u32 s49, s45, 0
	s_mov_b32 m0, s58
	v_lshl_add_u64 v[88:89], s[48:49], 0, v[176:177]
	ds_read_b128 v[12:15], v211 offset:32768
	ds_read_b128 v[24:27], v211 offset:33792
	ds_read_b128 v[28:31], v211 offset:34816
	ds_read_b128 v[60:63], v211 offset:35840
	ds_read_b128 v[232:235], v211 offset:36864
	ds_read_b128 v[236:239], v211 offset:37888
	ds_read_b128 v[240:243], v211 offset:38912
	ds_read_b128 v[244:247], v211 offset:39936
	global_load_lds_dwordx4 v[88:89], off
	s_mov_b32 m0, s59
	v_lshl_add_u64 v[88:89], s[48:49], 0, v[178:179]
	global_load_lds_dwordx4 v[88:89], off
	s_waitcnt vmcnt(8) lgkmcnt(0)
	s_barrier
	s_setprio 1
	v_mfma_f32_16x16x32_bf16 v[64:67], v[4:7], v[12:15], v[64:67]
	v_mfma_f32_16x16x32_bf16 v[124:127], v[8:11], v[24:27], v[64:67]
	v_mfma_f32_16x16x32_bf16 v[64:67], v[204:207], v[12:15], v[68:71]
	v_mfma_f32_16x16x32_bf16 v[120:123], v[212:215], v[24:27], v[64:67]
	v_mfma_f32_16x16x32_bf16 v[64:67], v[4:7], v[28:31], v[72:75]
	v_mfma_f32_16x16x32_bf16 v[108:111], v[8:11], v[60:63], v[64:67]
	v_mfma_f32_16x16x32_bf16 v[64:67], v[204:207], v[28:31], v[76:79]
	v_mfma_f32_16x16x32_bf16 v[104:107], v[212:215], v[60:63], v[64:67]
	v_mfma_f32_16x16x32_bf16 v[64:67], v[4:7], v[232:235], v[80:83]
	v_mfma_f32_16x16x32_bf16 v[92:95], v[8:11], v[236:239], v[64:67]
	v_mfma_f32_16x16x32_bf16 v[64:67], v[204:207], v[232:235], v[84:87]
	v_mfma_f32_16x16x32_bf16 v[88:91], v[212:215], v[236:239], v[64:67]
	v_mfma_f32_16x16x32_bf16 v[64:67], v[4:7], v[240:243], v[96:99]
	v_mfma_f32_16x16x32_bf16 v[76:79], v[8:11], v[244:247], v[64:67]
	v_mfma_f32_16x16x32_bf16 v[64:67], v[204:207], v[240:243], v[100:103]
	v_mfma_f32_16x16x32_bf16 v[72:75], v[212:215], v[244:247], v[64:67]
	v_mfma_f32_16x16x32_bf16 v[64:67], v[216:219], v[12:15], v[112:115]
	v_mfma_f32_16x16x32_bf16 v[12:15], v[224:227], v[12:15], v[32:35]
	v_mfma_f32_16x16x32_bf16 v[112:115], v[228:231], v[24:27], v[12:15]
	v_mfma_f32_16x16x32_bf16 v[12:15], v[216:219], v[28:31], v[36:39]
	v_mfma_f32_16x16x32_bf16 v[100:103], v[220:223], v[60:63], v[12:15]
	v_mfma_f32_16x16x32_bf16 v[12:15], v[224:227], v[28:31], v[40:43]
	v_mfma_f32_16x16x32_bf16 v[96:99], v[228:231], v[60:63], v[12:15]
	v_mfma_f32_16x16x32_bf16 v[12:15], v[216:219], v[232:235], v[44:47]
	v_mfma_f32_16x16x32_bf16 v[84:87], v[220:223], v[236:239], v[12:15]
	v_mfma_f32_16x16x32_bf16 v[12:15], v[224:227], v[232:235], v[48:51]
	v_mfma_f32_16x16x32_bf16 v[80:83], v[228:231], v[236:239], v[12:15]
	v_mfma_f32_16x16x32_bf16 v[12:15], v[216:219], v[240:243], v[52:55]
	s_setprio 2
	s_barrier
	v_mfma_f32_16x16x32_bf16 v[68:71], v[220:223], v[244:247], v[12:15]
	v_mfma_f32_16x16x32_bf16 v[12:15], v[224:227], v[240:243], v[56:59]
	v_mfma_f32_16x16x32_bf16 v[116:119], v[220:223], v[24:27], v[64:67]
	v_mfma_f32_16x16x32_bf16 v[64:67], v[228:231], v[244:247], v[12:15]
	s_setprio 2
	s_add_i32 s79, s79, s43
	s_add_i32 s80, s79, 0x2000
	s_nop 1
	v_lshl_add_u64 v[12:13], v[174:175], 0, s[26:27]
	s_mov_b32 m0, s79
	s_add_u32 s48, s46, 0x80180
	ds_read_b128 v[32:35], v211 offset:49152
	ds_read_b128 v[36:39], v211 offset:50176
	ds_read_b128 v[232:235], v211 offset:51200
	ds_read_b128 v[236:239], v211 offset:52224
	ds_read_b128 v[240:243], v211 offset:53248
	ds_read_b128 v[244:247], v211 offset:54272
	ds_read_b128 v[248:251], v211 offset:55296
	ds_read_b128 v[184:187], v211 offset:56320
	global_load_lds_dwordx4 v[12:13], off
	v_lshl_add_u64 v[12:13], v[200:201], 0, s[26:27]
	s_mov_b32 m0, s80
	s_addc_u32 s49, s47, 0
	s_add_i32 s81, s81, s43
	global_load_lds_dwordx4 v[12:13], off
	v_lshl_add_u64 v[12:13], s[48:49], 0, v[176:177]
	s_mov_b32 m0, s81
	s_add_i32 s82, s81, 0x2000
	global_load_lds_dwordx4 v[12:13], off
	s_mov_b32 m0, s82
	v_lshl_add_u64 v[12:13], s[48:49], 0, v[178:179]
	global_load_lds_dwordx4 v[12:13], off
	s_mov_b32 m0, s61
	v_lshl_add_u64 v[12:13], v[208:209], 0, s[26:27]
	global_load_lds_dwordx4 v[12:13], off
	s_mov_b32 m0, s62
	v_lshl_add_u64 v[12:13], v[252:253], 0, s[26:27]
	global_load_lds_dwordx4 v[12:13], off
	s_waitcnt vmcnt(8) lgkmcnt(0)
	s_barrier
	s_setprio 1
	v_mfma_f32_16x16x32_bf16 v[12:15], v[4:7], v[32:35], v[130:133]
	v_mfma_f32_16x16x32_bf16 v[60:63], v[8:11], v[36:39], v[12:15]
	v_mfma_f32_16x16x32_bf16 v[12:15], v[204:207], v[32:35], v[134:137]
	v_mfma_f32_16x16x32_bf16 v[56:59], v[212:215], v[36:39], v[12:15]
	v_mfma_f32_16x16x32_bf16 v[12:15], v[4:7], v[232:235], v[138:141]
	v_mfma_f32_16x16x32_bf16 v[44:47], v[8:11], v[236:239], v[12:15]
	v_mfma_f32_16x16x32_bf16 v[12:15], v[204:207], v[232:235], v[142:145]
	v_mfma_f32_16x16x32_bf16 v[40:43], v[212:215], v[236:239], v[12:15]
	v_mfma_f32_16x16x32_bf16 v[12:15], v[4:7], v[240:243], v[146:149]
	v_mfma_f32_16x16x32_bf16 v[28:31], v[8:11], v[244:247], v[12:15]
	v_mfma_f32_16x16x32_bf16 v[12:15], v[204:207], v[240:243], v[150:153]
	v_mfma_f32_16x16x32_bf16 v[4:7], v[4:7], v[248:251], v[154:157]
	v_mfma_f32_16x16x32_bf16 v[24:27], v[212:215], v[244:247], v[12:15]
	v_mfma_f32_16x16x32_bf16 v[12:15], v[8:11], v[184:187], v[4:7]
	v_mfma_f32_16x16x32_bf16 v[4:7], v[204:207], v[248:251], v[16:19]
	v_mfma_f32_16x16x32_bf16 v[8:11], v[212:215], v[184:187], v[4:7]
	v_mfma_f32_16x16x32_bf16 v[4:7], v[216:219], v[32:35], v[20:23]
	v_mfma_f32_16x16x32_bf16 v[52:55], v[220:223], v[36:39], v[4:7]
	v_mfma_f32_16x16x32_bf16 v[4:7], v[224:227], v[32:35], v[158:161]
	v_mfma_f32_16x16x32_bf16 v[48:51], v[228:231], v[36:39], v[4:7]
	v_mfma_f32_16x16x32_bf16 v[4:7], v[216:219], v[232:235], v[162:165]
	v_mfma_f32_16x16x32_bf16 v[36:39], v[220:223], v[236:239], v[4:7]
	v_mfma_f32_16x16x32_bf16 v[4:7], v[224:227], v[232:235], v[166:169]
	v_mfma_f32_16x16x32_bf16 v[32:35], v[228:231], v[236:239], v[4:7]
	v_mfma_f32_16x16x32_bf16 v[4:7], v[216:219], v[240:243], v[170:173]
	v_mfma_f32_16x16x32_bf16 v[20:23], v[220:223], v[244:247], v[4:7]
	v_mfma_f32_16x16x32_bf16 v[4:7], v[224:227], v[240:243], v[190:193]
	v_mfma_f32_16x16x32_bf16 v[16:19], v[228:231], v[244:247], v[4:7]
	s_setprio 2
	s_barrier
	v_mfma_f32_16x16x32_bf16 v[4:7], v[216:219], v[248:251], v[196:199]
	v_mfma_f32_16x16x32_bf16 v[0:3], v[224:227], v[248:251], v[0:3]
	v_mfma_f32_16x16x32_bf16 v[4:7], v[220:223], v[184:187], v[4:7]
	v_mfma_f32_16x16x32_bf16 v[0:3], v[228:231], v[184:187], v[0:3]
	s_setprio 0
	s_add_u32 s44, s44, 0x80180
	s_addc_u32 s45, s45, 0
	s_add_u32 s83, s46, 0x200
	s_addc_u32 s84, s47, 0
	s_mov_b32 s46, 0
	s_add_i32 s85, s46, 2
	s_and_b32 s47, s85, 6
	s_cmp_lg_u32 s47, 0
	s_cbranch_scc1 .LBB0_700
	s_branch .LBB0_699

.LBB0_700:
	ds_read_b128 v[130:133], v203
	ds_read_b128 v[134:137], v203 offset:1024
	ds_read_b128 v[138:141], v203 offset:2048
	ds_read_b128 v[142:145], v203 offset:3072
	ds_read_b128 v[146:149], v195
	ds_read_b128 v[150:153], v195 offset:1024
	ds_read_b128 v[154:157], v195 offset:2048
	ds_read_b128 v[158:161], v195 offset:3072
	s_add_u32 s47, s44, 0xfff80080
	s_addc_u32 s48, s45, -1
	s_cmp_eq_u32 s46, 28
	s_cselect_b32 s49, s29, s48
	s_cselect_b32 s48, s71, s47
	s_cselect_b32 s47, s31, s84
	s_cselect_b32 s46, s72, s83
	s_mov_b32 m0, s73
	v_lshl_add_u64 v[174:175], s[44:45], 0, v[180:181]
	ds_read_b128 v[162:165], v211
	ds_read_b128 v[166:169], v211 offset:1024
	ds_read_b128 v[170:173], v211 offset:2048
	ds_read_b128 v[184:187], v211 offset:3072
	ds_read_b128 v[190:193], v211 offset:4096
	ds_read_b128 v[196:199], v211 offset:5120
	ds_read_b128 v[204:207], v211 offset:6144
	ds_read_b128 v[212:215], v211 offset:7168
	global_load_lds_dwordx4 v[174:175], off
	s_mov_b32 m0, s74
	v_lshl_add_u64 v[174:175], s[44:45], 0, v[182:183]
	global_load_lds_dwordx4 v[174:175], off
	s_waitcnt vmcnt(8) lgkmcnt(0)
	s_barrier
	s_setprio 1
	v_mfma_f32_16x16x32_bf16 v[124:127], v[130:133], v[162:165], v[124:127]
	v_mfma_f32_16x16x32_bf16 v[120:123], v[138:141], v[162:165], v[120:123]
	v_mfma_f32_16x16x32_bf16 v[108:111], v[130:133], v[170:173], v[108:111]
	v_mfma_f32_16x16x32_bf16 v[104:107], v[138:141], v[170:173], v[104:107]
	v_mfma_f32_16x16x32_bf16 v[92:95], v[130:133], v[190:193], v[92:95]
	v_mfma_f32_16x16x32_bf16 v[88:91], v[138:141], v[190:193], v[88:91]
	v_mfma_f32_16x16x32_bf16 v[76:79], v[130:133], v[204:207], v[76:79]
	v_mfma_f32_16x16x32_bf16 v[72:75], v[138:141], v[204:207], v[72:75]
	v_mfma_f32_16x16x32_bf16 v[124:127], v[134:137], v[166:169], v[124:127]
	v_mfma_f32_16x16x32_bf16 v[120:123], v[142:145], v[166:169], v[120:123]
	v_mfma_f32_16x16x32_bf16 v[108:111], v[134:137], v[184:187], v[108:111]
	v_mfma_f32_16x16x32_bf16 v[104:107], v[142:145], v[184:187], v[104:107]
	v_mfma_f32_16x16x32_bf16 v[92:95], v[134:137], v[196:199], v[92:95]
	v_mfma_f32_16x16x32_bf16 v[88:91], v[142:145], v[196:199], v[88:91]
	v_mfma_f32_16x16x32_bf16 v[76:79], v[134:137], v[212:215], v[76:79]
	v_mfma_f32_16x16x32_bf16 v[72:75], v[142:145], v[212:215], v[72:75]
	v_mfma_f32_16x16x32_bf16 v[116:119], v[146:149], v[162:165], v[116:119]
	v_mfma_f32_16x16x32_bf16 v[112:115], v[154:157], v[162:165], v[112:115]
	v_mfma_f32_16x16x32_bf16 v[100:103], v[146:149], v[170:173], v[100:103]
	v_mfma_f32_16x16x32_bf16 v[96:99], v[154:157], v[170:173], v[96:99]
	v_mfma_f32_16x16x32_bf16 v[84:87], v[146:149], v[190:193], v[84:87]
	v_mfma_f32_16x16x32_bf16 v[80:83], v[154:157], v[190:193], v[80:83]
	v_mfma_f32_16x16x32_bf16 v[68:71], v[146:149], v[204:207], v[68:71]
	v_mfma_f32_16x16x32_bf16 v[64:67], v[154:157], v[204:207], v[64:67]
	v_mfma_f32_16x16x32_bf16 v[116:119], v[150:153], v[166:169], v[116:119]
	v_mfma_f32_16x16x32_bf16 v[112:115], v[158:161], v[166:169], v[112:115]
	v_mfma_f32_16x16x32_bf16 v[100:103], v[150:153], v[184:187], v[100:103]
	v_mfma_f32_16x16x32_bf16 v[96:99], v[158:161], v[184:187], v[96:99]
	s_setprio 2
	s_barrier
	v_mfma_f32_16x16x32_bf16 v[84:87], v[150:153], v[196:199], v[84:87]
	v_mfma_f32_16x16x32_bf16 v[80:83], v[158:161], v[196:199], v[80:83]
	v_mfma_f32_16x16x32_bf16 v[68:71], v[150:153], v[212:215], v[68:71]
	v_mfma_f32_16x16x32_bf16 v[64:67], v[158:161], v[212:215], v[64:67]
	s_setprio 2
	s_mov_b32 m0, s75
	v_lshl_add_u64 v[174:175], s[46:47], 0, v[176:177]
	s_add_u32 s86, s46, 0x80000
	ds_read_b128 v[162:165], v211 offset:16384
	ds_read_b128 v[166:169], v211 offset:17408
	ds_read_b128 v[170:173], v211 offset:18432
	ds_read_b128 v[184:187], v211 offset:19456
	ds_read_b128 v[190:193], v211 offset:20480
	ds_read_b128 v[196:199], v211 offset:21504
	ds_read_b128 v[204:207], v211 offset:22528
	ds_read_b128 v[212:215], v211 offset:23552
	global_load_lds_dwordx4 v[174:175], off
	v_lshl_add_u64 v[200:201], s[46:47], 0, v[178:179]
	s_mov_b32 m0, s76
	s_addc_u32 s87, s47, 0
	global_load_lds_dwordx4 v[200:201], off
	v_lshl_add_u64 v[208:209], s[86:87], 0, v[176:177]
	s_mov_b32 m0, s77
	v_lshl_add_u64 v[216:217], s[48:49], 0, v[178:179]
	global_load_lds_dwordx4 v[208:209], off
	s_mov_b32 m0, s78
	v_lshl_add_u64 v[208:209], s[86:87], 0, v[178:179]
	global_load_lds_dwordx4 v[208:209], off
	s_mov_b32 m0, s56
	v_lshl_add_u64 v[208:209], s[48:49], 0, v[176:177]
	global_load_lds_dwordx4 v[208:209], off
	s_mov_b32 m0, s57
	s_nop 0
	global_load_lds_dwordx4 v[216:217], off
	s_waitcnt vmcnt(8) lgkmcnt(0)
	s_barrier
	s_setprio 1
	v_mfma_f32_16x16x32_bf16 v[60:63], v[130:133], v[162:165], v[60:63]
	v_mfma_f32_16x16x32_bf16 v[56:59], v[138:141], v[162:165], v[56:59]
	v_mfma_f32_16x16x32_bf16 v[44:47], v[130:133], v[170:173], v[44:47]
	v_mfma_f32_16x16x32_bf16 v[40:43], v[138:141], v[170:173], v[40:43]
	v_mfma_f32_16x16x32_bf16 v[28:31], v[130:133], v[190:193], v[28:31]
	v_mfma_f32_16x16x32_bf16 v[24:27], v[138:141], v[190:193], v[24:27]
	v_mfma_f32_16x16x32_bf16 v[12:15], v[130:133], v[204:207], v[12:15]
	v_mfma_f32_16x16x32_bf16 v[8:11], v[138:141], v[204:207], v[8:11]
	v_mfma_f32_16x16x32_bf16 v[60:63], v[134:137], v[166:169], v[60:63]
	v_mfma_f32_16x16x32_bf16 v[56:59], v[142:145], v[166:169], v[56:59]
	v_mfma_f32_16x16x32_bf16 v[44:47], v[134:137], v[184:187], v[44:47]
	v_mfma_f32_16x16x32_bf16 v[40:43], v[142:145], v[184:187], v[40:43]
	v_mfma_f32_16x16x32_bf16 v[28:31], v[134:137], v[196:199], v[28:31]
	v_mfma_f32_16x16x32_bf16 v[24:27], v[142:145], v[196:199], v[24:27]
	v_mfma_f32_16x16x32_bf16 v[12:15], v[134:137], v[212:215], v[12:15]
	v_mfma_f32_16x16x32_bf16 v[8:11], v[142:145], v[212:215], v[8:11]
	v_mfma_f32_16x16x32_bf16 v[52:55], v[146:149], v[162:165], v[52:55]
	v_mfma_f32_16x16x32_bf16 v[48:51], v[154:157], v[162:165], v[48:51]
	v_mfma_f32_16x16x32_bf16 v[36:39], v[146:149], v[170:173], v[36:39]
	v_mfma_f32_16x16x32_bf16 v[32:35], v[154:157], v[170:173], v[32:35]
	v_mfma_f32_16x16x32_bf16 v[20:23], v[146:149], v[190:193], v[20:23]
	v_mfma_f32_16x16x32_bf16 v[16:19], v[154:157], v[190:193], v[16:19]
	v_mfma_f32_16x16x32_bf16 v[4:7], v[146:149], v[204:207], v[4:7]
	v_mfma_f32_16x16x32_bf16 v[0:3], v[154:157], v[204:207], v[0:3]
	v_mfma_f32_16x16x32_bf16 v[52:55], v[150:153], v[166:169], v[52:55]
	v_mfma_f32_16x16x32_bf16 v[48:51], v[158:161], v[166:169], v[48:51]
	v_mfma_f32_16x16x32_bf16 v[36:39], v[150:153], v[184:187], v[36:39]
	v_mfma_f32_16x16x32_bf16 v[32:35], v[158:161], v[184:187], v[32:35]
	s_setprio 2
	s_barrier
	v_mfma_f32_16x16x32_bf16 v[20:23], v[150:153], v[196:199], v[20:23]
	v_mfma_f32_16x16x32_bf16 v[16:19], v[158:161], v[196:199], v[16:19]
	v_mfma_f32_16x16x32_bf16 v[4:7], v[150:153], v[212:215], v[4:7]
	v_mfma_f32_16x16x32_bf16 v[0:3], v[158:161], v[212:215], v[0:3]
	s_setprio 0
	ds_read_b128 v[130:133], v128
	ds_read_b128 v[134:137], v128 offset:1024
	ds_read_b128 v[138:141], v128 offset:2048
	ds_read_b128 v[142:145], v128 offset:3072
	ds_read_b128 v[146:149], v129
	ds_read_b128 v[150:153], v129 offset:1024
	ds_read_b128 v[154:157], v129 offset:2048
	ds_read_b128 v[158:161], v129 offset:3072
	s_add_u32 s48, s48, 0x80000
	s_addc_u32 s49, s49, 0
	s_mov_b32 m0, s58
	v_lshl_add_u64 v[218:219], s[48:49], 0, v[176:177]
	ds_read_b128 v[162:165], v211 offset:32768
	ds_read_b128 v[166:169], v211 offset:33792
	ds_read_b128 v[170:173], v211 offset:34816
	ds_read_b128 v[184:187], v211 offset:35840
	ds_read_b128 v[190:193], v211 offset:36864
	ds_read_b128 v[196:199], v211 offset:37888
	ds_read_b128 v[204:207], v211 offset:38912
	ds_read_b128 v[212:215], v211 offset:39936
	global_load_lds_dwordx4 v[218:219], off
	s_mov_b32 m0, s59
	v_lshl_add_u64 v[218:219], s[48:49], 0, v[178:179]
	global_load_lds_dwordx4 v[218:219], off
	s_waitcnt vmcnt(8) lgkmcnt(0)
	s_barrier
	s_setprio 1
	v_mfma_f32_16x16x32_bf16 v[124:127], v[130:133], v[162:165], v[124:127]
	v_mfma_f32_16x16x32_bf16 v[120:123], v[138:141], v[162:165], v[120:123]
	v_mfma_f32_16x16x32_bf16 v[108:111], v[130:133], v[170:173], v[108:111]
	v_mfma_f32_16x16x32_bf16 v[104:107], v[138:141], v[170:173], v[104:107]
	v_mfma_f32_16x16x32_bf16 v[92:95], v[130:133], v[190:193], v[92:95]
	v_mfma_f32_16x16x32_bf16 v[88:91], v[138:141], v[190:193], v[88:91]
	v_mfma_f32_16x16x32_bf16 v[76:79], v[130:133], v[204:207], v[76:79]
	v_mfma_f32_16x16x32_bf16 v[72:75], v[138:141], v[204:207], v[72:75]
	v_mfma_f32_16x16x32_bf16 v[124:127], v[134:137], v[166:169], v[124:127]
	v_mfma_f32_16x16x32_bf16 v[120:123], v[142:145], v[166:169], v[120:123]
	v_mfma_f32_16x16x32_bf16 v[108:111], v[134:137], v[184:187], v[108:111]
	v_mfma_f32_16x16x32_bf16 v[104:107], v[142:145], v[184:187], v[104:107]
	v_mfma_f32_16x16x32_bf16 v[92:95], v[134:137], v[196:199], v[92:95]
	v_mfma_f32_16x16x32_bf16 v[88:91], v[142:145], v[196:199], v[88:91]
	v_mfma_f32_16x16x32_bf16 v[76:79], v[134:137], v[212:215], v[76:79]
	v_mfma_f32_16x16x32_bf16 v[72:75], v[142:145], v[212:215], v[72:75]
	v_mfma_f32_16x16x32_bf16 v[116:119], v[146:149], v[162:165], v[116:119]
	v_mfma_f32_16x16x32_bf16 v[112:115], v[154:157], v[162:165], v[112:115]
	v_mfma_f32_16x16x32_bf16 v[100:103], v[146:149], v[170:173], v[100:103]
	v_mfma_f32_16x16x32_bf16 v[96:99], v[154:157], v[170:173], v[96:99]
	v_mfma_f32_16x16x32_bf16 v[84:87], v[146:149], v[190:193], v[84:87]
	v_mfma_f32_16x16x32_bf16 v[80:83], v[154:157], v[190:193], v[80:83]
	v_mfma_f32_16x16x32_bf16 v[68:71], v[146:149], v[204:207], v[68:71]
	v_mfma_f32_16x16x32_bf16 v[64:67], v[154:157], v[204:207], v[64:67]
	v_mfma_f32_16x16x32_bf16 v[116:119], v[150:153], v[166:169], v[116:119]
	v_mfma_f32_16x16x32_bf16 v[112:115], v[158:161], v[166:169], v[112:115]
	v_mfma_f32_16x16x32_bf16 v[100:103], v[150:153], v[184:187], v[100:103]
	v_mfma_f32_16x16x32_bf16 v[96:99], v[158:161], v[184:187], v[96:99]
	s_setprio 2
	s_barrier
	v_mfma_f32_16x16x32_bf16 v[84:87], v[150:153], v[196:199], v[84:87]
	v_mfma_f32_16x16x32_bf16 v[80:83], v[158:161], v[196:199], v[80:83]
	v_mfma_f32_16x16x32_bf16 v[68:71], v[150:153], v[212:215], v[68:71]
	v_mfma_f32_16x16x32_bf16 v[64:67], v[158:161], v[212:215], v[64:67]
	s_setprio 2
	s_mov_b32 m0, s79
	v_lshl_add_u64 v[174:175], v[174:175], 0, s[20:21]
	s_add_u32 s46, s46, 0x80080
	ds_read_b128 v[162:165], v211 offset:49152
	ds_read_b128 v[166:169], v211 offset:50176
	ds_read_b128 v[170:173], v211 offset:51200
	ds_read_b128 v[184:187], v211 offset:52224
	ds_read_b128 v[190:193], v211 offset:53248
	ds_read_b128 v[196:199], v211 offset:54272
	ds_read_b128 v[204:207], v211 offset:55296
	ds_read_b128 v[212:215], v211 offset:56320
	global_load_lds_dwordx4 v[174:175], off
	v_lshl_add_u64 v[174:175], v[200:201], 0, s[20:21]
	s_mov_b32 m0, s80
	s_addc_u32 s47, s47, 0
	global_load_lds_dwordx4 v[174:175], off
	s_mov_b32 m0, s81
	v_lshl_add_u64 v[174:175], s[46:47], 0, v[176:177]
	global_load_lds_dwordx4 v[174:175], off
	s_mov_b32 m0, s82
	v_lshl_add_u64 v[174:175], s[46:47], 0, v[178:179]
	global_load_lds_dwordx4 v[174:175], off
	s_mov_b32 m0, s61
	v_lshl_add_u64 v[174:175], v[208:209], 0, s[20:21]
	global_load_lds_dwordx4 v[174:175], off
	s_mov_b32 m0, s62
	v_lshl_add_u64 v[174:175], v[216:217], 0, s[20:21]
	global_load_lds_dwordx4 v[174:175], off
	s_waitcnt vmcnt(8) lgkmcnt(0)
	s_barrier
	s_setprio 1
	v_mfma_f32_16x16x32_bf16 v[60:63], v[130:133], v[162:165], v[60:63]
	v_mfma_f32_16x16x32_bf16 v[56:59], v[138:141], v[162:165], v[56:59]
	v_mfma_f32_16x16x32_bf16 v[44:47], v[130:133], v[170:173], v[44:47]
	v_mfma_f32_16x16x32_bf16 v[40:43], v[138:141], v[170:173], v[40:43]
	v_mfma_f32_16x16x32_bf16 v[28:31], v[130:133], v[190:193], v[28:31]
	v_mfma_f32_16x16x32_bf16 v[24:27], v[138:141], v[190:193], v[24:27]
	v_mfma_f32_16x16x32_bf16 v[12:15], v[130:133], v[204:207], v[12:15]
	v_mfma_f32_16x16x32_bf16 v[8:11], v[138:141], v[204:207], v[8:11]
	v_mfma_f32_16x16x32_bf16 v[60:63], v[134:137], v[166:169], v[60:63]
	v_mfma_f32_16x16x32_bf16 v[56:59], v[142:145], v[166:169], v[56:59]
	v_mfma_f32_16x16x32_bf16 v[44:47], v[134:137], v[184:187], v[44:47]
	v_mfma_f32_16x16x32_bf16 v[40:43], v[142:145], v[184:187], v[40:43]
	v_mfma_f32_16x16x32_bf16 v[28:31], v[134:137], v[196:199], v[28:31]
	v_mfma_f32_16x16x32_bf16 v[24:27], v[142:145], v[196:199], v[24:27]
	v_mfma_f32_16x16x32_bf16 v[12:15], v[134:137], v[212:215], v[12:15]
	v_mfma_f32_16x16x32_bf16 v[8:11], v[142:145], v[212:215], v[8:11]
	v_mfma_f32_16x16x32_bf16 v[52:55], v[146:149], v[162:165], v[52:55]
	v_mfma_f32_16x16x32_bf16 v[48:51], v[154:157], v[162:165], v[48:51]
	v_mfma_f32_16x16x32_bf16 v[36:39], v[146:149], v[170:173], v[36:39]
	v_mfma_f32_16x16x32_bf16 v[32:35], v[154:157], v[170:173], v[32:35]
	v_mfma_f32_16x16x32_bf16 v[20:23], v[146:149], v[190:193], v[20:23]
	v_mfma_f32_16x16x32_bf16 v[16:19], v[154:157], v[190:193], v[16:19]
	v_mfma_f32_16x16x32_bf16 v[4:7], v[146:149], v[204:207], v[4:7]
	v_mfma_f32_16x16x32_bf16 v[0:3], v[154:157], v[204:207], v[0:3]
	v_mfma_f32_16x16x32_bf16 v[52:55], v[150:153], v[166:169], v[52:55]
	v_mfma_f32_16x16x32_bf16 v[48:51], v[158:161], v[166:169], v[48:51]
	v_mfma_f32_16x16x32_bf16 v[36:39], v[150:153], v[184:187], v[36:39]
	v_mfma_f32_16x16x32_bf16 v[32:35], v[158:161], v[184:187], v[32:35]
	s_setprio 2
	s_barrier
	v_mfma_f32_16x16x32_bf16 v[20:23], v[150:153], v[196:199], v[20:23]
	v_mfma_f32_16x16x32_bf16 v[16:19], v[158:161], v[196:199], v[16:19]
	v_mfma_f32_16x16x32_bf16 v[4:7], v[150:153], v[212:215], v[4:7]
	v_mfma_f32_16x16x32_bf16 v[0:3], v[158:161], v[212:215], v[0:3]
	s_setprio 0
	s_add_i32 s70, s70, 1
	s_add_u32 s44, s44, 0x100
	s_addc_u32 s45, s45, 0
	s_add_u32 s83, s83, 0x100
	s_addc_u32 s84, s84, 0
	s_cmp_gt_u32 s85, 29
	s_cbranch_scc0 .LBB0_698
	s_lshl_b32 s29, s41, 12
	s_and_b32 s29, s29, 0x1000
	s_add_i32 s29, s29, 0
	v_mbcnt_lo_u32_b32 v128, -1, 0
	v_mbcnt_hi_u32_b32 v128, -1, v128
	s_add_i32 s29, s29, s63
	v_lshlrev_b32_e32 v128, 4, v128
	s_add_i32 s29, s29, 0x20400
	v_and_b32_e32 v128, 0xf0, v128
	v_add_u32_e32 v128, s29, v128
	ds_read2_b32 v[214:215], v128 offset0:3 offset1:67
	ds_read2_b32 v[206:207], v128 offset0:131 offset1:195
	v_add_u32_e32 v128, 12, v128
	ds_read2st64_b32 v[196:197], v128 offset0:8 offset1:9
	ds_read2st64_b32 v[190:191], v128 offset0:10 offset1:11
	s_and_b64 vcc, exec, s[22:23]
	s_waitcnt lgkmcnt(0)
	v_mov_b32_e32 v210, v215
	v_mov_b32_e32 v202, v207
	v_mov_b32_e32 v194, v197
	v_mov_b32_e32 v188, v191
	s_cbranch_vccz .LBB0_703
	s_barrier

.LBB0_783:
	s_ashr_i32 s23, s22, 31
	s_lshl_b64 s[26:27], s[22:23], 19
	s_add_u32 s26, s43, s26
	s_addc_u32 s27, s44, s27
	s_and_b64 s[28:29], s[4:5], exec
	s_cselect_b32 s23, s27, s37
	s_cselect_b32 s31, s26, s36
	s_ashr_i32 s25, s24, 31
	s_lshl_b64 s[28:29], s[24:25], 19
	s_add_u32 s28, s45, s28
	s_addc_u32 s29, s46, s29
	s_and_b64 s[40:41], s[4:5], exec
	s_cselect_b32 s25, s29, s39
	s_cselect_b32 s62, s28, s38
	s_add_u32 s36, s36, 0x40080
	s_addc_u32 s37, s37, 0
	s_add_u32 s63, s38, 0x100
	s_addc_u32 s64, s39, 0
	s_mov_b32 s65, -2
	ds_read_b128 v[144:147], v163
	ds_read_b128 v[148:151], v163 offset:1024
	ds_read_b128 v[152:155], v163 offset:2048
	ds_read_b128 v[156:159], v163 offset:3072
	ds_read_b128 v[168:171], v164
	ds_read_b128 v[172:175], v164 offset:1024
	ds_read_b128 v[176:179], v164 offset:2048
	ds_read_b128 v[180:183], v164 offset:3072
	s_add_u32 s38, s36, 0xfffc0080
	s_addc_u32 s39, s37, -1
	s_cmp_eq_u32 s65, 12
	s_cselect_b32 s41, s23, s39
	s_cselect_b32 s40, s31, s38
	s_cselect_b32 s39, s25, s64
	s_cselect_b32 s38, s62, s63
	v_lshl_add_u64 v[160:161], s[36:37], 0, v[136:137]
	s_add_i32 m0, s50, 0xc000
	ds_read_b128 v[184:187], v165
	ds_read_b128 v[188:191], v165 offset:1024
	ds_read_b128 v[192:195], v165 offset:2048
	ds_read_b128 v[196:199], v165 offset:3072
	ds_read_b128 v[200:203], v165 offset:4096
	ds_read_b128 v[204:207], v165 offset:5120
	ds_read_b128 v[208:211], v165 offset:6144
	ds_read_b128 v[212:215], v165 offset:7168
	global_load_lds_dwordx4 v[160:161], off
	s_add_i32 m0, s50, 0xe000
	v_lshl_add_u64 v[160:161], s[36:37], 0, v[138:139]
	global_load_lds_dwordx4 v[160:161], off
	s_waitcnt vmcnt(8) lgkmcnt(0)
	s_barrier
	s_setprio 1
	v_mfma_f32_16x16x32_bf16 v[124:127], v[144:147], v[184:187], 0
	v_mfma_f32_16x16x32_bf16 v[120:123], v[152:155], v[184:187], 0
	v_mfma_f32_16x16x32_bf16 v[108:111], v[144:147], v[192:195], 0
	v_mfma_f32_16x16x32_bf16 v[104:107], v[152:155], v[192:195], 0
	v_mfma_f32_16x16x32_bf16 v[92:95], v[144:147], v[200:203], 0
	v_mfma_f32_16x16x32_bf16 v[88:91], v[152:155], v[200:203], 0
	v_mfma_f32_16x16x32_bf16 v[76:79], v[144:147], v[208:211], 0
	v_mfma_f32_16x16x32_bf16 v[72:75], v[152:155], v[208:211], 0
	v_mfma_f32_16x16x32_bf16 v[124:127], v[148:151], v[188:191], v[124:127]
	v_mfma_f32_16x16x32_bf16 v[120:123], v[156:159], v[188:191], v[120:123]
	v_mfma_f32_16x16x32_bf16 v[108:111], v[148:151], v[196:199], v[108:111]
	v_mfma_f32_16x16x32_bf16 v[104:107], v[156:159], v[196:199], v[104:107]
	v_mfma_f32_16x16x32_bf16 v[92:95], v[148:151], v[204:207], v[92:95]
	v_mfma_f32_16x16x32_bf16 v[88:91], v[156:159], v[204:207], v[88:91]
	v_mfma_f32_16x16x32_bf16 v[76:79], v[148:151], v[212:215], v[76:79]
	v_mfma_f32_16x16x32_bf16 v[72:75], v[156:159], v[212:215], v[72:75]
	v_mfma_f32_16x16x32_bf16 v[116:119], v[168:171], v[184:187], 0
	v_mfma_f32_16x16x32_bf16 v[112:115], v[176:179], v[184:187], 0
	v_mfma_f32_16x16x32_bf16 v[100:103], v[168:171], v[192:195], 0
	v_mfma_f32_16x16x32_bf16 v[96:99], v[176:179], v[192:195], 0
	v_mfma_f32_16x16x32_bf16 v[84:87], v[168:171], v[200:203], 0
	v_mfma_f32_16x16x32_bf16 v[80:83], v[176:179], v[200:203], 0
	v_mfma_f32_16x16x32_bf16 v[68:71], v[168:171], v[208:211], 0
	v_mfma_f32_16x16x32_bf16 v[64:67], v[176:179], v[208:211], 0
	v_mfma_f32_16x16x32_bf16 v[116:119], v[172:175], v[188:191], v[116:119]
	v_mfma_f32_16x16x32_bf16 v[112:115], v[180:183], v[188:191], v[112:115]
	v_mfma_f32_16x16x32_bf16 v[100:103], v[172:175], v[196:199], v[100:103]
	v_mfma_f32_16x16x32_bf16 v[96:99], v[180:183], v[196:199], v[96:99]
	s_setprio 2
	s_barrier
	v_mfma_f32_16x16x32_bf16 v[84:87], v[172:175], v[204:207], v[84:87]
	v_mfma_f32_16x16x32_bf16 v[80:83], v[180:183], v[204:207], v[80:83]
	v_mfma_f32_16x16x32_bf16 v[68:71], v[172:175], v[212:215], v[68:71]
	v_mfma_f32_16x16x32_bf16 v[64:67], v[180:183], v[212:215], v[64:67]
	s_setprio 2
	s_add_i32 s66, s59, s47
	v_lshl_add_u64 v[160:161], s[38:39], 0, v[132:133]
	s_mov_b32 m0, s66
	ds_read_b128 v[184:187], v165 offset:16384
	ds_read_b128 v[188:191], v165 offset:17408
	ds_read_b128 v[192:195], v165 offset:18432
	ds_read_b128 v[196:199], v165 offset:19456
	ds_read_b128 v[200:203], v165 offset:20480
	ds_read_b128 v[204:207], v165 offset:21504
	ds_read_b128 v[208:211], v165 offset:22528
	ds_read_b128 v[212:215], v165 offset:23552
	global_load_lds_dwordx4 v[160:161], off
	s_add_i32 m0, s66, 0x2000
	s_add_u32 s66, s38, 0x40000
	v_lshl_add_u64 v[216:217], s[38:39], 0, v[128:129]
	s_addc_u32 s67, s39, 0
	s_add_i32 s68, s60, s47
	global_load_lds_dwordx4 v[216:217], off
	v_lshl_add_u64 v[218:219], s[66:67], 0, v[132:133]
	s_mov_b32 m0, s68
	v_lshl_add_u64 v[220:221], s[40:41], 0, v[130:131]
	global_load_lds_dwordx4 v[218:219], off
	s_add_i32 m0, s68, 0x2000
	v_lshl_add_u64 v[218:219], s[66:67], 0, v[128:129]
	global_load_lds_dwordx4 v[218:219], off
	s_mov_b32 m0, s50
	v_lshl_add_u64 v[218:219], s[40:41], 0, v[134:135]
	global_load_lds_dwordx4 v[218:219], off
	s_mov_b32 m0, s51
	s_nop 0
	global_load_lds_dwordx4 v[220:221], off
	s_waitcnt vmcnt(8) lgkmcnt(0)
	s_barrier
	s_setprio 1
	v_mfma_f32_16x16x32_bf16 v[60:63], v[144:147], v[184:187], 0
	v_mfma_f32_16x16x32_bf16 v[56:59], v[152:155], v[184:187], 0
	v_mfma_f32_16x16x32_bf16 v[44:47], v[144:147], v[192:195], 0
	v_mfma_f32_16x16x32_bf16 v[40:43], v[152:155], v[192:195], 0
	v_mfma_f32_16x16x32_bf16 v[28:31], v[144:147], v[200:203], 0
	v_mfma_f32_16x16x32_bf16 v[24:27], v[152:155], v[200:203], 0
	v_mfma_f32_16x16x32_bf16 v[12:15], v[144:147], v[208:211], 0
	v_mfma_f32_16x16x32_bf16 v[8:11], v[152:155], v[208:211], 0
	v_mfma_f32_16x16x32_bf16 v[60:63], v[148:151], v[188:191], v[60:63]
	v_mfma_f32_16x16x32_bf16 v[56:59], v[156:159], v[188:191], v[56:59]
	v_mfma_f32_16x16x32_bf16 v[44:47], v[148:151], v[196:199], v[44:47]
	v_mfma_f32_16x16x32_bf16 v[40:43], v[156:159], v[196:199], v[40:43]
	v_mfma_f32_16x16x32_bf16 v[28:31], v[148:151], v[204:207], v[28:31]
	v_mfma_f32_16x16x32_bf16 v[24:27], v[156:159], v[204:207], v[24:27]
	v_mfma_f32_16x16x32_bf16 v[12:15], v[148:151], v[212:215], v[12:15]
	v_mfma_f32_16x16x32_bf16 v[8:11], v[156:159], v[212:215], v[8:11]
	v_mfma_f32_16x16x32_bf16 v[52:55], v[168:171], v[184:187], 0
	v_mfma_f32_16x16x32_bf16 v[48:51], v[176:179], v[184:187], 0
	v_mfma_f32_16x16x32_bf16 v[36:39], v[168:171], v[192:195], 0
	v_mfma_f32_16x16x32_bf16 v[32:35], v[176:179], v[192:195], 0
	v_mfma_f32_16x16x32_bf16 v[20:23], v[168:171], v[200:203], 0
	v_mfma_f32_16x16x32_bf16 v[16:19], v[176:179], v[200:203], 0
	v_mfma_f32_16x16x32_bf16 v[4:7], v[168:171], v[208:211], 0
	v_mfma_f32_16x16x32_bf16 v[0:3], v[176:179], v[208:211], 0
	v_mfma_f32_16x16x32_bf16 v[52:55], v[172:175], v[188:191], v[52:55]
	v_mfma_f32_16x16x32_bf16 v[48:51], v[180:183], v[188:191], v[48:51]
	v_mfma_f32_16x16x32_bf16 v[36:39], v[172:175], v[196:199], v[36:39]
	v_mfma_f32_16x16x32_bf16 v[32:35], v[180:183], v[196:199], v[32:35]
	s_setprio 2
	s_barrier
	v_mfma_f32_16x16x32_bf16 v[20:23], v[172:175], v[204:207], v[20:23]
	v_mfma_f32_16x16x32_bf16 v[16:19], v[180:183], v[204:207], v[16:19]
	v_mfma_f32_16x16x32_bf16 v[4:7], v[172:175], v[212:215], v[4:7]
	v_mfma_f32_16x16x32_bf16 v[0:3], v[180:183], v[212:215], v[0:3]
	s_setprio 0
	s_add_i32 s66, 0, 0x18000
	s_add_i32 s67, 0, 0x1c000
	v_add_u32_e32 v156, s66, v162
	v_add_u32_e32 v167, s67, v162
	ds_read_b128 v[144:147], v156
	ds_read_b128 v[148:151], v156 offset:1024
	ds_read_b128 v[152:155], v156 offset:2048
	ds_read_b128 v[156:159], v156 offset:3072
	ds_read_b128 v[168:171], v167
	ds_read_b128 v[172:175], v167 offset:1024
	ds_read_b128 v[176:179], v167 offset:2048
	ds_read_b128 v[180:183], v167 offset:3072
	s_add_u32 s40, s40, 0x40000
	s_addc_u32 s41, s41, 0
	s_mov_b32 m0, s54
	v_lshl_add_u64 v[222:223], s[40:41], 0, v[134:135]
	ds_read_b128 v[184:187], v165 offset:32768
	ds_read_b128 v[188:191], v165 offset:33792
	ds_read_b128 v[192:195], v165 offset:34816
	ds_read_b128 v[196:199], v165 offset:35840
	ds_read_b128 v[200:203], v165 offset:36864
	ds_read_b128 v[204:207], v165 offset:37888
	ds_read_b128 v[208:211], v165 offset:38912
	ds_read_b128 v[212:215], v165 offset:39936
	global_load_lds_dwordx4 v[222:223], off
	s_mov_b32 m0, s55
	v_lshl_add_u64 v[222:223], s[40:41], 0, v[130:131]
	global_load_lds_dwordx4 v[222:223], off
	s_waitcnt vmcnt(8) lgkmcnt(0)
	s_barrier
	s_setprio 1
	v_mfma_f32_16x16x32_bf16 v[124:127], v[144:147], v[184:187], v[124:127]
	v_mfma_f32_16x16x32_bf16 v[120:123], v[152:155], v[184:187], v[120:123]
	v_mfma_f32_16x16x32_bf16 v[108:111], v[144:147], v[192:195], v[108:111]
	v_mfma_f32_16x16x32_bf16 v[104:107], v[152:155], v[192:195], v[104:107]
	v_mfma_f32_16x16x32_bf16 v[92:95], v[144:147], v[200:203], v[92:95]
	v_mfma_f32_16x16x32_bf16 v[88:91], v[152:155], v[200:203], v[88:91]
	v_mfma_f32_16x16x32_bf16 v[76:79], v[144:147], v[208:211], v[76:79]
	v_mfma_f32_16x16x32_bf16 v[72:75], v[152:155], v[208:211], v[72:75]
	v_mfma_f32_16x16x32_bf16 v[124:127], v[148:151], v[188:191], v[124:127]
	v_mfma_f32_16x16x32_bf16 v[120:123], v[156:159], v[188:191], v[120:123]
	v_mfma_f32_16x16x32_bf16 v[108:111], v[148:151], v[196:199], v[108:111]
	v_mfma_f32_16x16x32_bf16 v[104:107], v[156:159], v[196:199], v[104:107]
	v_mfma_f32_16x16x32_bf16 v[92:95], v[148:151], v[204:207], v[92:95]
	v_mfma_f32_16x16x32_bf16 v[88:91], v[156:159], v[204:207], v[88:91]
	v_mfma_f32_16x16x32_bf16 v[76:79], v[148:151], v[212:215], v[76:79]
	v_mfma_f32_16x16x32_bf16 v[72:75], v[156:159], v[212:215], v[72:75]
	v_mfma_f32_16x16x32_bf16 v[116:119], v[168:171], v[184:187], v[116:119]
	v_mfma_f32_16x16x32_bf16 v[112:115], v[176:179], v[184:187], v[112:115]
	v_mfma_f32_16x16x32_bf16 v[100:103], v[168:171], v[192:195], v[100:103]
	v_mfma_f32_16x16x32_bf16 v[96:99], v[176:179], v[192:195], v[96:99]
	v_mfma_f32_16x16x32_bf16 v[84:87], v[168:171], v[200:203], v[84:87]
	v_mfma_f32_16x16x32_bf16 v[80:83], v[176:179], v[200:203], v[80:83]
	v_mfma_f32_16x16x32_bf16 v[68:71], v[168:171], v[208:211], v[68:71]
	v_mfma_f32_16x16x32_bf16 v[64:67], v[176:179], v[208:211], v[64:67]
	v_mfma_f32_16x16x32_bf16 v[116:119], v[172:175], v[188:191], v[116:119]
	v_mfma_f32_16x16x32_bf16 v[112:115], v[180:183], v[188:191], v[112:115]
	v_mfma_f32_16x16x32_bf16 v[100:103], v[172:175], v[196:199], v[100:103]
	v_mfma_f32_16x16x32_bf16 v[96:99], v[180:183], v[196:199], v[96:99]
	s_setprio 2
	s_barrier
	v_mfma_f32_16x16x32_bf16 v[84:87], v[172:175], v[204:207], v[84:87]
	v_mfma_f32_16x16x32_bf16 v[80:83], v[180:183], v[204:207], v[80:83]
	v_mfma_f32_16x16x32_bf16 v[68:71], v[172:175], v[212:215], v[68:71]
	v_mfma_f32_16x16x32_bf16 v[64:67], v[180:183], v[212:215], v[64:67]
	s_setprio 2
	s_add_i32 s40, s66, s47
	v_lshl_add_u64 v[160:161], v[160:161], 0, s[16:17]
	s_mov_b32 m0, s40
	ds_read_b128 v[184:187], v165 offset:49152
	ds_read_b128 v[188:191], v165 offset:50176
	ds_read_b128 v[192:195], v165 offset:51200
	ds_read_b128 v[196:199], v165 offset:52224
	ds_read_b128 v[200:203], v165 offset:53248
	ds_read_b128 v[204:207], v165 offset:54272
	ds_read_b128 v[208:211], v165 offset:55296
	ds_read_b128 v[212:215], v165 offset:56320
	global_load_lds_dwordx4 v[160:161], off
	s_add_i32 m0, s40, 0x2000
	s_add_u32 s38, s38, 0x40080
	v_lshl_add_u64 v[160:161], v[216:217], 0, s[16:17]
	s_addc_u32 s39, s39, 0
	s_add_i32 s40, s67, s47
	global_load_lds_dwordx4 v[160:161], off
	s_mov_b32 m0, s40
	v_lshl_add_u64 v[160:161], s[38:39], 0, v[132:133]
	global_load_lds_dwordx4 v[160:161], off
	s_add_i32 m0, s40, 0x2000
	v_lshl_add_u64 v[160:161], s[38:39], 0, v[128:129]
	global_load_lds_dwordx4 v[160:161], off
	s_mov_b32 m0, s57
	v_lshl_add_u64 v[160:161], v[218:219], 0, s[16:17]
	global_load_lds_dwordx4 v[160:161], off
	s_mov_b32 m0, s58
	v_lshl_add_u64 v[160:161], v[220:221], 0, s[16:17]
	global_load_lds_dwordx4 v[160:161], off
	s_waitcnt vmcnt(8) lgkmcnt(0)
	s_barrier
	s_setprio 1
	v_mfma_f32_16x16x32_bf16 v[60:63], v[144:147], v[184:187], v[60:63]
	v_mfma_f32_16x16x32_bf16 v[56:59], v[152:155], v[184:187], v[56:59]
	v_mfma_f32_16x16x32_bf16 v[44:47], v[144:147], v[192:195], v[44:47]
	v_mfma_f32_16x16x32_bf16 v[40:43], v[152:155], v[192:195], v[40:43]
	v_mfma_f32_16x16x32_bf16 v[28:31], v[144:147], v[200:203], v[28:31]
	v_mfma_f32_16x16x32_bf16 v[24:27], v[152:155], v[200:203], v[24:27]
	v_mfma_f32_16x16x32_bf16 v[12:15], v[144:147], v[208:211], v[12:15]
	v_mfma_f32_16x16x32_bf16 v[8:11], v[152:155], v[208:211], v[8:11]
	v_mfma_f32_16x16x32_bf16 v[60:63], v[148:151], v[188:191], v[60:63]
	v_mfma_f32_16x16x32_bf16 v[56:59], v[156:159], v[188:191], v[56:59]
	v_mfma_f32_16x16x32_bf16 v[44:47], v[148:151], v[196:199], v[44:47]
	v_mfma_f32_16x16x32_bf16 v[40:43], v[156:159], v[196:199], v[40:43]
	v_mfma_f32_16x16x32_bf16 v[28:31], v[148:151], v[204:207], v[28:31]
	v_mfma_f32_16x16x32_bf16 v[24:27], v[156:159], v[204:207], v[24:27]
	v_mfma_f32_16x16x32_bf16 v[12:15], v[148:151], v[212:215], v[12:15]
	v_mfma_f32_16x16x32_bf16 v[8:11], v[156:159], v[212:215], v[8:11]
	v_mfma_f32_16x16x32_bf16 v[52:55], v[168:171], v[184:187], v[52:55]
	v_mfma_f32_16x16x32_bf16 v[48:51], v[176:179], v[184:187], v[48:51]
	v_mfma_f32_16x16x32_bf16 v[36:39], v[168:171], v[192:195], v[36:39]
	v_mfma_f32_16x16x32_bf16 v[32:35], v[176:179], v[192:195], v[32:35]
	v_mfma_f32_16x16x32_bf16 v[20:23], v[168:171], v[200:203], v[20:23]
	v_mfma_f32_16x16x32_bf16 v[16:19], v[176:179], v[200:203], v[16:19]
	v_mfma_f32_16x16x32_bf16 v[4:7], v[168:171], v[208:211], v[4:7]
	v_mfma_f32_16x16x32_bf16 v[0:3], v[176:179], v[208:211], v[0:3]
	v_mfma_f32_16x16x32_bf16 v[52:55], v[172:175], v[188:191], v[52:55]
	v_mfma_f32_16x16x32_bf16 v[48:51], v[180:183], v[188:191], v[48:51]
	v_mfma_f32_16x16x32_bf16 v[36:39], v[172:175], v[196:199], v[36:39]
	v_mfma_f32_16x16x32_bf16 v[32:35], v[180:183], v[196:199], v[32:35]
	s_setprio 2
	s_barrier
	v_mfma_f32_16x16x32_bf16 v[20:23], v[172:175], v[204:207], v[20:23]
	v_mfma_f32_16x16x32_bf16 v[16:19], v[180:183], v[204:207], v[16:19]
	v_mfma_f32_16x16x32_bf16 v[4:7], v[172:175], v[212:215], v[4:7]
	v_mfma_f32_16x16x32_bf16 v[0:3], v[180:183], v[212:215], v[0:3]
	s_setprio 0
	s_add_i32 s65, s65, 2
	s_add_u32 s36, s36, 0x100
	s_addc_u32 s37, s37, 0
	s_add_u32 s63, s63, 0x100
	s_addc_u32 s64, s64, 0
	s_cmp_gt_u32 s65, 13
.LBB0_784:
	ds_read_b128 v[144:147], v163
	ds_read_b128 v[148:151], v163 offset:1024
	ds_read_b128 v[152:155], v163 offset:2048
	ds_read_b128 v[156:159], v163 offset:3072
	ds_read_b128 v[168:171], v164
	ds_read_b128 v[172:175], v164 offset:1024
	ds_read_b128 v[176:179], v164 offset:2048
	ds_read_b128 v[180:183], v164 offset:3072
	s_add_u32 s38, s36, 0xfffc0080
	s_addc_u32 s39, s37, -1
	s_cmp_eq_u32 s65, 12
	s_cselect_b32 s41, s23, s39
	s_cselect_b32 s40, s31, s38
	s_cselect_b32 s39, s25, s64
	s_cselect_b32 s38, s62, s63
	v_lshl_add_u64 v[160:161], s[36:37], 0, v[136:137]
	s_add_i32 m0, s50, 0xc000
	ds_read_b128 v[184:187], v165
	ds_read_b128 v[188:191], v165 offset:1024
	ds_read_b128 v[192:195], v165 offset:2048
	ds_read_b128 v[196:199], v165 offset:3072
	ds_read_b128 v[200:203], v165 offset:4096
	ds_read_b128 v[204:207], v165 offset:5120
	ds_read_b128 v[208:211], v165 offset:6144
	ds_read_b128 v[212:215], v165 offset:7168
	global_load_lds_dwordx4 v[160:161], off
	s_add_i32 m0, s50, 0xe000
	v_lshl_add_u64 v[160:161], s[36:37], 0, v[138:139]
	global_load_lds_dwordx4 v[160:161], off
	s_waitcnt vmcnt(8) lgkmcnt(0)
	s_barrier
	s_setprio 1
	v_mfma_f32_16x16x32_bf16 v[124:127], v[144:147], v[184:187], v[124:127]
	v_mfma_f32_16x16x32_bf16 v[120:123], v[152:155], v[184:187], v[120:123]
	v_mfma_f32_16x16x32_bf16 v[108:111], v[144:147], v[192:195], v[108:111]
	v_mfma_f32_16x16x32_bf16 v[104:107], v[152:155], v[192:195], v[104:107]
	v_mfma_f32_16x16x32_bf16 v[92:95], v[144:147], v[200:203], v[92:95]
	v_mfma_f32_16x16x32_bf16 v[88:91], v[152:155], v[200:203], v[88:91]
	v_mfma_f32_16x16x32_bf16 v[76:79], v[144:147], v[208:211], v[76:79]
	v_mfma_f32_16x16x32_bf16 v[72:75], v[152:155], v[208:211], v[72:75]
	v_mfma_f32_16x16x32_bf16 v[124:127], v[148:151], v[188:191], v[124:127]
	v_mfma_f32_16x16x32_bf16 v[120:123], v[156:159], v[188:191], v[120:123]
	v_mfma_f32_16x16x32_bf16 v[108:111], v[148:151], v[196:199], v[108:111]
	v_mfma_f32_16x16x32_bf16 v[104:107], v[156:159], v[196:199], v[104:107]
	v_mfma_f32_16x16x32_bf16 v[92:95], v[148:151], v[204:207], v[92:95]
	v_mfma_f32_16x16x32_bf16 v[88:91], v[156:159], v[204:207], v[88:91]
	v_mfma_f32_16x16x32_bf16 v[76:79], v[148:151], v[212:215], v[76:79]
	v_mfma_f32_16x16x32_bf16 v[72:75], v[156:159], v[212:215], v[72:75]
	v_mfma_f32_16x16x32_bf16 v[116:119], v[168:171], v[184:187], v[116:119]
	v_mfma_f32_16x16x32_bf16 v[112:115], v[176:179], v[184:187], v[112:115]
	v_mfma_f32_16x16x32_bf16 v[100:103], v[168:171], v[192:195], v[100:103]
	v_mfma_f32_16x16x32_bf16 v[96:99], v[176:179], v[192:195], v[96:99]
	v_mfma_f32_16x16x32_bf16 v[84:87], v[168:171], v[200:203], v[84:87]
	v_mfma_f32_16x16x32_bf16 v[80:83], v[176:179], v[200:203], v[80:83]
	v_mfma_f32_16x16x32_bf16 v[68:71], v[168:171], v[208:211], v[68:71]
	v_mfma_f32_16x16x32_bf16 v[64:67], v[176:179], v[208:211], v[64:67]
	v_mfma_f32_16x16x32_bf16 v[116:119], v[172:175], v[188:191], v[116:119]
	v_mfma_f32_16x16x32_bf16 v[112:115], v[180:183], v[188:191], v[112:115]
	v_mfma_f32_16x16x32_bf16 v[100:103], v[172:175], v[196:199], v[100:103]
	v_mfma_f32_16x16x32_bf16 v[96:99], v[180:183], v[196:199], v[96:99]
	s_setprio 2
	s_barrier
	v_mfma_f32_16x16x32_bf16 v[84:87], v[172:175], v[204:207], v[84:87]
	v_mfma_f32_16x16x32_bf16 v[80:83], v[180:183], v[204:207], v[80:83]
	v_mfma_f32_16x16x32_bf16 v[68:71], v[172:175], v[212:215], v[68:71]
	v_mfma_f32_16x16x32_bf16 v[64:67], v[180:183], v[212:215], v[64:67]
	s_setprio 2
	s_add_i32 s66, s59, s47
	v_lshl_add_u64 v[160:161], s[38:39], 0, v[132:133]
	s_mov_b32 m0, s66
	ds_read_b128 v[184:187], v165 offset:16384
	ds_read_b128 v[188:191], v165 offset:17408
	ds_read_b128 v[192:195], v165 offset:18432
	ds_read_b128 v[196:199], v165 offset:19456
	ds_read_b128 v[200:203], v165 offset:20480
	ds_read_b128 v[204:207], v165 offset:21504
	ds_read_b128 v[208:211], v165 offset:22528
	ds_read_b128 v[212:215], v165 offset:23552
	global_load_lds_dwordx4 v[160:161], off
	s_add_i32 m0, s66, 0x2000
	s_add_u32 s66, s38, 0x40000
	v_lshl_add_u64 v[216:217], s[38:39], 0, v[128:129]
	s_addc_u32 s67, s39, 0
	s_add_i32 s68, s60, s47
	global_load_lds_dwordx4 v[216:217], off
	v_lshl_add_u64 v[218:219], s[66:67], 0, v[132:133]
	s_mov_b32 m0, s68
	v_lshl_add_u64 v[220:221], s[40:41], 0, v[130:131]
	global_load_lds_dwordx4 v[218:219], off
	s_add_i32 m0, s68, 0x2000
	v_lshl_add_u64 v[218:219], s[66:67], 0, v[128:129]
	global_load_lds_dwordx4 v[218:219], off
	s_mov_b32 m0, s50
	v_lshl_add_u64 v[218:219], s[40:41], 0, v[134:135]
	global_load_lds_dwordx4 v[218:219], off
	s_mov_b32 m0, s51
	s_nop 0
	global_load_lds_dwordx4 v[220:221], off
	s_waitcnt vmcnt(8) lgkmcnt(0)
	s_barrier
	s_setprio 1
	v_mfma_f32_16x16x32_bf16 v[60:63], v[144:147], v[184:187], v[60:63]
	v_mfma_f32_16x16x32_bf16 v[56:59], v[152:155], v[184:187], v[56:59]
	v_mfma_f32_16x16x32_bf16 v[44:47], v[144:147], v[192:195], v[44:47]
	v_mfma_f32_16x16x32_bf16 v[40:43], v[152:155], v[192:195], v[40:43]
	v_mfma_f32_16x16x32_bf16 v[28:31], v[144:147], v[200:203], v[28:31]
	v_mfma_f32_16x16x32_bf16 v[24:27], v[152:155], v[200:203], v[24:27]
	v_mfma_f32_16x16x32_bf16 v[12:15], v[144:147], v[208:211], v[12:15]
	v_mfma_f32_16x16x32_bf16 v[8:11], v[152:155], v[208:211], v[8:11]
	v_mfma_f32_16x16x32_bf16 v[60:63], v[148:151], v[188:191], v[60:63]
	v_mfma_f32_16x16x32_bf16 v[56:59], v[156:159], v[188:191], v[56:59]
	v_mfma_f32_16x16x32_bf16 v[44:47], v[148:151], v[196:199], v[44:47]
	v_mfma_f32_16x16x32_bf16 v[40:43], v[156:159], v[196:199], v[40:43]
	v_mfma_f32_16x16x32_bf16 v[28:31], v[148:151], v[204:207], v[28:31]
	v_mfma_f32_16x16x32_bf16 v[24:27], v[156:159], v[204:207], v[24:27]
	v_mfma_f32_16x16x32_bf16 v[12:15], v[148:151], v[212:215], v[12:15]
	v_mfma_f32_16x16x32_bf16 v[8:11], v[156:159], v[212:215], v[8:11]
	v_mfma_f32_16x16x32_bf16 v[52:55], v[168:171], v[184:187], v[52:55]
	v_mfma_f32_16x16x32_bf16 v[48:51], v[176:179], v[184:187], v[48:51]
	v_mfma_f32_16x16x32_bf16 v[36:39], v[168:171], v[192:195], v[36:39]
	v_mfma_f32_16x16x32_bf16 v[32:35], v[176:179], v[192:195], v[32:35]
	v_mfma_f32_16x16x32_bf16 v[20:23], v[168:171], v[200:203], v[20:23]
	v_mfma_f32_16x16x32_bf16 v[16:19], v[176:179], v[200:203], v[16:19]
	v_mfma_f32_16x16x32_bf16 v[4:7], v[168:171], v[208:211], v[4:7]
	v_mfma_f32_16x16x32_bf16 v[0:3], v[176:179], v[208:211], v[0:3]
	v_mfma_f32_16x16x32_bf16 v[52:55], v[172:175], v[188:191], v[52:55]
	v_mfma_f32_16x16x32_bf16 v[48:51], v[180:183], v[188:191], v[48:51]
	v_mfma_f32_16x16x32_bf16 v[36:39], v[172:175], v[196:199], v[36:39]
	v_mfma_f32_16x16x32_bf16 v[32:35], v[180:183], v[196:199], v[32:35]
	s_setprio 2
	s_barrier
	v_mfma_f32_16x16x32_bf16 v[20:23], v[172:175], v[204:207], v[20:23]
	v_mfma_f32_16x16x32_bf16 v[16:19], v[180:183], v[204:207], v[16:19]
	v_mfma_f32_16x16x32_bf16 v[4:7], v[172:175], v[212:215], v[4:7]
	v_mfma_f32_16x16x32_bf16 v[0:3], v[180:183], v[212:215], v[0:3]
	s_setprio 0
	s_add_i32 s66, 0, 0x18000
	s_add_i32 s67, 0, 0x1c000
	v_add_u32_e32 v156, s66, v162
	v_add_u32_e32 v167, s67, v162
	ds_read_b128 v[144:147], v156
	ds_read_b128 v[148:151], v156 offset:1024
	ds_read_b128 v[152:155], v156 offset:2048
	ds_read_b128 v[156:159], v156 offset:3072
	ds_read_b128 v[168:171], v167
	ds_read_b128 v[172:175], v167 offset:1024
	ds_read_b128 v[176:179], v167 offset:2048
	ds_read_b128 v[180:183], v167 offset:3072
	s_add_u32 s40, s40, 0x40000
	s_addc_u32 s41, s41, 0
	s_mov_b32 m0, s54
	v_lshl_add_u64 v[222:223], s[40:41], 0, v[134:135]
	ds_read_b128 v[184:187], v165 offset:32768
	ds_read_b128 v[188:191], v165 offset:33792
	ds_read_b128 v[192:195], v165 offset:34816
	ds_read_b128 v[196:199], v165 offset:35840
	ds_read_b128 v[200:203], v165 offset:36864
	ds_read_b128 v[204:207], v165 offset:37888
	ds_read_b128 v[208:211], v165 offset:38912
	ds_read_b128 v[212:215], v165 offset:39936
	global_load_lds_dwordx4 v[222:223], off
	s_mov_b32 m0, s55
	v_lshl_add_u64 v[222:223], s[40:41], 0, v[130:131]
	global_load_lds_dwordx4 v[222:223], off
	s_waitcnt vmcnt(8) lgkmcnt(0)
	s_barrier
	s_setprio 1
	v_mfma_f32_16x16x32_bf16 v[124:127], v[144:147], v[184:187], v[124:127]
	v_mfma_f32_16x16x32_bf16 v[120:123], v[152:155], v[184:187], v[120:123]
	v_mfma_f32_16x16x32_bf16 v[108:111], v[144:147], v[192:195], v[108:111]
	v_mfma_f32_16x16x32_bf16 v[104:107], v[152:155], v[192:195], v[104:107]
	v_mfma_f32_16x16x32_bf16 v[92:95], v[144:147], v[200:203], v[92:95]
	v_mfma_f32_16x16x32_bf16 v[88:91], v[152:155], v[200:203], v[88:91]
	v_mfma_f32_16x16x32_bf16 v[76:79], v[144:147], v[208:211], v[76:79]
	v_mfma_f32_16x16x32_bf16 v[72:75], v[152:155], v[208:211], v[72:75]
	v_mfma_f32_16x16x32_bf16 v[124:127], v[148:151], v[188:191], v[124:127]
	v_mfma_f32_16x16x32_bf16 v[120:123], v[156:159], v[188:191], v[120:123]
	v_mfma_f32_16x16x32_bf16 v[108:111], v[148:151], v[196:199], v[108:111]
	v_mfma_f32_16x16x32_bf16 v[104:107], v[156:159], v[196:199], v[104:107]
	v_mfma_f32_16x16x32_bf16 v[92:95], v[148:151], v[204:207], v[92:95]
	v_mfma_f32_16x16x32_bf16 v[88:91], v[156:159], v[204:207], v[88:91]
	v_mfma_f32_16x16x32_bf16 v[76:79], v[148:151], v[212:215], v[76:79]
	v_mfma_f32_16x16x32_bf16 v[72:75], v[156:159], v[212:215], v[72:75]
	v_mfma_f32_16x16x32_bf16 v[116:119], v[168:171], v[184:187], v[116:119]
	v_mfma_f32_16x16x32_bf16 v[112:115], v[176:179], v[184:187], v[112:115]
	v_mfma_f32_16x16x32_bf16 v[100:103], v[168:171], v[192:195], v[100:103]
	v_mfma_f32_16x16x32_bf16 v[96:99], v[176:179], v[192:195], v[96:99]
	v_mfma_f32_16x16x32_bf16 v[84:87], v[168:171], v[200:203], v[84:87]
	v_mfma_f32_16x16x32_bf16 v[80:83], v[176:179], v[200:203], v[80:83]
	v_mfma_f32_16x16x32_bf16 v[68:71], v[168:171], v[208:211], v[68:71]
	v_mfma_f32_16x16x32_bf16 v[64:67], v[176:179], v[208:211], v[64:67]
	v_mfma_f32_16x16x32_bf16 v[116:119], v[172:175], v[188:191], v[116:119]
	v_mfma_f32_16x16x32_bf16 v[112:115], v[180:183], v[188:191], v[112:115]
	v_mfma_f32_16x16x32_bf16 v[100:103], v[172:175], v[196:199], v[100:103]
	v_mfma_f32_16x16x32_bf16 v[96:99], v[180:183], v[196:199], v[96:99]
	s_setprio 2
	s_barrier
	v_mfma_f32_16x16x32_bf16 v[84:87], v[172:175], v[204:207], v[84:87]
	v_mfma_f32_16x16x32_bf16 v[80:83], v[180:183], v[204:207], v[80:83]
	v_mfma_f32_16x16x32_bf16 v[68:71], v[172:175], v[212:215], v[68:71]
	v_mfma_f32_16x16x32_bf16 v[64:67], v[180:183], v[212:215], v[64:67]
	s_setprio 2
	s_add_i32 s40, s66, s47
	v_lshl_add_u64 v[160:161], v[160:161], 0, s[16:17]
	s_mov_b32 m0, s40
	ds_read_b128 v[184:187], v165 offset:49152
	ds_read_b128 v[188:191], v165 offset:50176
	ds_read_b128 v[192:195], v165 offset:51200
	ds_read_b128 v[196:199], v165 offset:52224
	ds_read_b128 v[200:203], v165 offset:53248
	ds_read_b128 v[204:207], v165 offset:54272
	ds_read_b128 v[208:211], v165 offset:55296
	ds_read_b128 v[212:215], v165 offset:56320
	global_load_lds_dwordx4 v[160:161], off
	s_add_i32 m0, s40, 0x2000
	s_add_u32 s38, s38, 0x40080
	v_lshl_add_u64 v[160:161], v[216:217], 0, s[16:17]
	s_addc_u32 s39, s39, 0
	s_add_i32 s40, s67, s47
	global_load_lds_dwordx4 v[160:161], off
	s_mov_b32 m0, s40
	v_lshl_add_u64 v[160:161], s[38:39], 0, v[132:133]
	global_load_lds_dwordx4 v[160:161], off
	s_add_i32 m0, s40, 0x2000
	v_lshl_add_u64 v[160:161], s[38:39], 0, v[128:129]
	global_load_lds_dwordx4 v[160:161], off
	s_mov_b32 m0, s57
	v_lshl_add_u64 v[160:161], v[218:219], 0, s[16:17]
	global_load_lds_dwordx4 v[160:161], off
	s_mov_b32 m0, s58
	v_lshl_add_u64 v[160:161], v[220:221], 0, s[16:17]
	global_load_lds_dwordx4 v[160:161], off
	s_waitcnt vmcnt(8) lgkmcnt(0)
	s_barrier
	s_setprio 1
	v_mfma_f32_16x16x32_bf16 v[60:63], v[144:147], v[184:187], v[60:63]
	v_mfma_f32_16x16x32_bf16 v[56:59], v[152:155], v[184:187], v[56:59]
	v_mfma_f32_16x16x32_bf16 v[44:47], v[144:147], v[192:195], v[44:47]
	v_mfma_f32_16x16x32_bf16 v[40:43], v[152:155], v[192:195], v[40:43]
	v_mfma_f32_16x16x32_bf16 v[28:31], v[144:147], v[200:203], v[28:31]
	v_mfma_f32_16x16x32_bf16 v[24:27], v[152:155], v[200:203], v[24:27]
	v_mfma_f32_16x16x32_bf16 v[12:15], v[144:147], v[208:211], v[12:15]
	v_mfma_f32_16x16x32_bf16 v[8:11], v[152:155], v[208:211], v[8:11]
	v_mfma_f32_16x16x32_bf16 v[60:63], v[148:151], v[188:191], v[60:63]
	v_mfma_f32_16x16x32_bf16 v[56:59], v[156:159], v[188:191], v[56:59]
	v_mfma_f32_16x16x32_bf16 v[44:47], v[148:151], v[196:199], v[44:47]
	v_mfma_f32_16x16x32_bf16 v[40:43], v[156:159], v[196:199], v[40:43]
	v_mfma_f32_16x16x32_bf16 v[28:31], v[148:151], v[204:207], v[28:31]
	v_mfma_f32_16x16x32_bf16 v[24:27], v[156:159], v[204:207], v[24:27]
	v_mfma_f32_16x16x32_bf16 v[12:15], v[148:151], v[212:215], v[12:15]
	v_mfma_f32_16x16x32_bf16 v[8:11], v[156:159], v[212:215], v[8:11]
	v_mfma_f32_16x16x32_bf16 v[52:55], v[168:171], v[184:187], v[52:55]
	v_mfma_f32_16x16x32_bf16 v[48:51], v[176:179], v[184:187], v[48:51]
	v_mfma_f32_16x16x32_bf16 v[36:39], v[168:171], v[192:195], v[36:39]
	v_mfma_f32_16x16x32_bf16 v[32:35], v[176:179], v[192:195], v[32:35]
	v_mfma_f32_16x16x32_bf16 v[20:23], v[168:171], v[200:203], v[20:23]
	v_mfma_f32_16x16x32_bf16 v[16:19], v[176:179], v[200:203], v[16:19]
	v_mfma_f32_16x16x32_bf16 v[4:7], v[168:171], v[208:211], v[4:7]
	v_mfma_f32_16x16x32_bf16 v[0:3], v[176:179], v[208:211], v[0:3]
	v_mfma_f32_16x16x32_bf16 v[52:55], v[172:175], v[188:191], v[52:55]
	v_mfma_f32_16x16x32_bf16 v[48:51], v[180:183], v[188:191], v[48:51]
	v_mfma_f32_16x16x32_bf16 v[36:39], v[172:175], v[196:199], v[36:39]
	v_mfma_f32_16x16x32_bf16 v[32:35], v[180:183], v[196:199], v[32:35]
	s_setprio 2
	s_barrier
	v_mfma_f32_16x16x32_bf16 v[20:23], v[172:175], v[204:207], v[20:23]
	v_mfma_f32_16x16x32_bf16 v[16:19], v[180:183], v[204:207], v[16:19]
	v_mfma_f32_16x16x32_bf16 v[4:7], v[172:175], v[212:215], v[4:7]
	v_mfma_f32_16x16x32_bf16 v[0:3], v[180:183], v[212:215], v[0:3]
	s_setprio 0
	s_add_i32 s65, s65, 2
	s_add_u32 s36, s36, 0x100
	s_addc_u32 s37, s37, 0
	s_add_u32 s63, s63, 0x100
	s_addc_u32 s64, s64, 0
	s_cmp_gt_u32 s65, 13
	s_cbranch_scc0 .LBB0_784

.LBB0_865:
	s_add_u32 s62, s28, 0x100
	s_addc_u32 s63, s29, 0
	s_mov_b32 s64, -2
	ds_read_b128 v[120:123], v233
	ds_read_b128 v[124:127], v233 offset:1024
	ds_read_b128 v[136:139], v233 offset:2048
	ds_read_b128 v[140:143], v233 offset:3072
	ds_read_b128 v[144:147], v234
	ds_read_b128 v[148:151], v234 offset:1024
	ds_read_b128 v[152:155], v234 offset:2048
	ds_read_b128 v[156:159], v234 offset:3072
	s_add_u32 s28, s26, 0x100
	s_addc_u32 s29, s27, 0
	s_cmp_eq_u32 s64, 40
	s_cselect_b32 s37, s7, s29
	s_cselect_b32 s36, s6, s28
	s_cselect_b32 s31, s25, s63
	s_cselect_b32 s30, s24, s62
	v_lshl_add_u64 v[208:209], s[26:27], 0, v[192:193]
	s_add_i32 m0, s44, 0xc000
	ds_read_b128 v[160:163], v235
	ds_read_b128 v[164:167], v235 offset:1024
	ds_read_b128 v[168:171], v235 offset:2048
	ds_read_b128 v[172:175], v235 offset:3072
	ds_read_b128 v[176:179], v235 offset:4096
	ds_read_b128 v[180:183], v235 offset:5120
	ds_read_b128 v[200:203], v235 offset:6144
	ds_read_b128 v[204:207], v235 offset:7168
	global_load_lds_dwordx4 v[208:209], off
	s_add_i32 m0, s44, 0xe000
	v_lshl_add_u64 v[208:209], s[26:27], 0, v[194:195]
	global_load_lds_dwordx4 v[208:209], off
	s_waitcnt vmcnt(8) lgkmcnt(0)
	s_barrier
	s_setprio 1
	v_mfma_f32_16x16x32_bf16 v[132:135], v[120:123], v[160:163], 0
	v_mfma_f32_16x16x32_bf16 v[128:131], v[136:139], v[160:163], 0
	v_mfma_f32_16x16x32_bf16 v[108:111], v[120:123], v[168:171], 0
	v_mfma_f32_16x16x32_bf16 v[104:107], v[136:139], v[168:171], 0
	v_mfma_f32_16x16x32_bf16 v[92:95], v[120:123], v[176:179], 0
	v_mfma_f32_16x16x32_bf16 v[88:91], v[136:139], v[176:179], 0
	v_mfma_f32_16x16x32_bf16 v[76:79], v[120:123], v[200:203], 0
	v_mfma_f32_16x16x32_bf16 v[72:75], v[136:139], v[200:203], 0
	v_mfma_f32_16x16x32_bf16 v[132:135], v[124:127], v[164:167], v[132:135]
	v_mfma_f32_16x16x32_bf16 v[128:131], v[140:143], v[164:167], v[128:131]
	v_mfma_f32_16x16x32_bf16 v[108:111], v[124:127], v[172:175], v[108:111]
	v_mfma_f32_16x16x32_bf16 v[104:107], v[140:143], v[172:175], v[104:107]
	v_mfma_f32_16x16x32_bf16 v[92:95], v[124:127], v[180:183], v[92:95]
	v_mfma_f32_16x16x32_bf16 v[88:91], v[140:143], v[180:183], v[88:91]
	v_mfma_f32_16x16x32_bf16 v[76:79], v[124:127], v[204:207], v[76:79]
	v_mfma_f32_16x16x32_bf16 v[72:75], v[140:143], v[204:207], v[72:75]
	v_mfma_f32_16x16x32_bf16 v[116:119], v[144:147], v[160:163], 0
	v_mfma_f32_16x16x32_bf16 v[112:115], v[152:155], v[160:163], 0
	v_mfma_f32_16x16x32_bf16 v[100:103], v[144:147], v[168:171], 0
	v_mfma_f32_16x16x32_bf16 v[96:99], v[152:155], v[168:171], 0
	v_mfma_f32_16x16x32_bf16 v[84:87], v[144:147], v[176:179], 0
	v_mfma_f32_16x16x32_bf16 v[80:83], v[152:155], v[176:179], 0
	v_mfma_f32_16x16x32_bf16 v[68:71], v[144:147], v[200:203], 0
	v_mfma_f32_16x16x32_bf16 v[64:67], v[152:155], v[200:203], 0
	v_mfma_f32_16x16x32_bf16 v[116:119], v[148:151], v[164:167], v[116:119]
	v_mfma_f32_16x16x32_bf16 v[112:115], v[156:159], v[164:167], v[112:115]
	v_mfma_f32_16x16x32_bf16 v[100:103], v[148:151], v[172:175], v[100:103]
	v_mfma_f32_16x16x32_bf16 v[96:99], v[156:159], v[172:175], v[96:99]
	s_setprio 2
	s_barrier
	v_mfma_f32_16x16x32_bf16 v[84:87], v[148:151], v[180:183], v[84:87]
	v_mfma_f32_16x16x32_bf16 v[80:83], v[156:159], v[180:183], v[80:83]
	v_mfma_f32_16x16x32_bf16 v[68:71], v[148:151], v[204:207], v[68:71]
	v_mfma_f32_16x16x32_bf16 v[64:67], v[156:159], v[204:207], v[64:67]
	s_setprio 2
	s_add_i32 s26, s56, s43
	v_lshl_add_u64 v[208:209], s[30:31], 0, v[186:187]
	s_mov_b32 m0, s26
	ds_read_b128 v[160:163], v235 offset:16384
	ds_read_b128 v[164:167], v235 offset:17408
	ds_read_b128 v[168:171], v235 offset:18432
	ds_read_b128 v[172:175], v235 offset:19456
	ds_read_b128 v[176:179], v235 offset:20480
	ds_read_b128 v[180:183], v235 offset:21504
	ds_read_b128 v[200:203], v235 offset:22528
	ds_read_b128 v[204:207], v235 offset:23552
	global_load_lds_dwordx4 v[208:209], off
	s_add_i32 m0, s26, 0x2000
	s_add_u32 s26, s30, 0xb0000
	v_lshl_add_u64 v[210:211], s[30:31], 0, v[190:191]
	s_addc_u32 s27, s31, 0
	s_add_i32 s65, s57, s43
	global_load_lds_dwordx4 v[210:211], off
	v_lshl_add_u64 v[212:213], s[26:27], 0, v[186:187]
	s_mov_b32 m0, s65
	v_lshl_add_u64 v[214:215], s[36:37], 0, v[188:189]
	global_load_lds_dwordx4 v[212:213], off
	s_add_i32 m0, s65, 0x2000
	v_lshl_add_u64 v[212:213], s[26:27], 0, v[190:191]
	global_load_lds_dwordx4 v[212:213], off
	s_mov_b32 m0, s44
	v_lshl_add_u64 v[212:213], s[36:37], 0, v[184:185]
	global_load_lds_dwordx4 v[212:213], off
	s_mov_b32 m0, s45
	s_nop 0
	global_load_lds_dwordx4 v[214:215], off
	s_waitcnt vmcnt(8) lgkmcnt(0)
	s_barrier
	s_setprio 1
	v_mfma_f32_16x16x32_bf16 v[60:63], v[120:123], v[160:163], 0
	v_mfma_f32_16x16x32_bf16 v[56:59], v[136:139], v[160:163], 0
	v_mfma_f32_16x16x32_bf16 v[44:47], v[120:123], v[168:171], 0
	v_mfma_f32_16x16x32_bf16 v[40:43], v[136:139], v[168:171], 0
	v_mfma_f32_16x16x32_bf16 v[28:31], v[120:123], v[176:179], 0
	v_mfma_f32_16x16x32_bf16 v[24:27], v[136:139], v[176:179], 0
	v_mfma_f32_16x16x32_bf16 v[12:15], v[120:123], v[200:203], 0
	v_mfma_f32_16x16x32_bf16 v[8:11], v[136:139], v[200:203], 0
	v_mfma_f32_16x16x32_bf16 v[60:63], v[124:127], v[164:167], v[60:63]
	v_mfma_f32_16x16x32_bf16 v[56:59], v[140:143], v[164:167], v[56:59]
	v_mfma_f32_16x16x32_bf16 v[44:47], v[124:127], v[172:175], v[44:47]
	v_mfma_f32_16x16x32_bf16 v[40:43], v[140:143], v[172:175], v[40:43]
	v_mfma_f32_16x16x32_bf16 v[28:31], v[124:127], v[180:183], v[28:31]
	v_mfma_f32_16x16x32_bf16 v[24:27], v[140:143], v[180:183], v[24:27]
	v_mfma_f32_16x16x32_bf16 v[12:15], v[124:127], v[204:207], v[12:15]
	v_mfma_f32_16x16x32_bf16 v[8:11], v[140:143], v[204:207], v[8:11]
	v_mfma_f32_16x16x32_bf16 v[52:55], v[144:147], v[160:163], 0
	v_mfma_f32_16x16x32_bf16 v[48:51], v[152:155], v[160:163], 0
	v_mfma_f32_16x16x32_bf16 v[36:39], v[144:147], v[168:171], 0
	v_mfma_f32_16x16x32_bf16 v[32:35], v[152:155], v[168:171], 0
	v_mfma_f32_16x16x32_bf16 v[20:23], v[144:147], v[176:179], 0
	v_mfma_f32_16x16x32_bf16 v[16:19], v[152:155], v[176:179], 0
	v_mfma_f32_16x16x32_bf16 v[4:7], v[144:147], v[200:203], 0
	v_mfma_f32_16x16x32_bf16 v[0:3], v[152:155], v[200:203], 0
	v_mfma_f32_16x16x32_bf16 v[52:55], v[148:151], v[164:167], v[52:55]
	v_mfma_f32_16x16x32_bf16 v[48:51], v[156:159], v[164:167], v[48:51]
	v_mfma_f32_16x16x32_bf16 v[36:39], v[148:151], v[172:175], v[36:39]
	v_mfma_f32_16x16x32_bf16 v[32:35], v[156:159], v[172:175], v[32:35]
	s_setprio 2
	s_barrier
	v_mfma_f32_16x16x32_bf16 v[20:23], v[148:151], v[180:183], v[20:23]
	v_mfma_f32_16x16x32_bf16 v[16:19], v[156:159], v[180:183], v[16:19]
	v_mfma_f32_16x16x32_bf16 v[4:7], v[148:151], v[204:207], v[4:7]
	v_mfma_f32_16x16x32_bf16 v[0:3], v[156:159], v[204:207], v[0:3]
	s_setprio 0
	s_add_i32 s65, 0, 0x18000
	s_add_i32 s66, 0, 0x1c000
	v_add_u32_e32 v140, s65, v232
	v_add_u32_e32 v156, s66, v232
	ds_read_b128 v[120:123], v140
	ds_read_b128 v[124:127], v140 offset:1024
	ds_read_b128 v[136:139], v140 offset:2048
	ds_read_b128 v[140:143], v140 offset:3072
	ds_read_b128 v[144:147], v156
	ds_read_b128 v[148:151], v156 offset:1024
	ds_read_b128 v[152:155], v156 offset:2048
	ds_read_b128 v[156:159], v156 offset:3072
	s_add_u32 s26, s36, 0xb0000
	s_addc_u32 s27, s37, 0
	s_mov_b32 m0, s46
	v_lshl_add_u64 v[216:217], s[26:27], 0, v[184:185]
	ds_read_b128 v[160:163], v235 offset:32768
	ds_read_b128 v[164:167], v235 offset:33792
	ds_read_b128 v[168:171], v235 offset:34816
	ds_read_b128 v[172:175], v235 offset:35840
	ds_read_b128 v[176:179], v235 offset:36864
	ds_read_b128 v[180:183], v235 offset:37888
	ds_read_b128 v[200:203], v235 offset:38912
	ds_read_b128 v[204:207], v235 offset:39936
	global_load_lds_dwordx4 v[216:217], off
	s_mov_b32 m0, s47
	v_lshl_add_u64 v[216:217], s[26:27], 0, v[188:189]
	global_load_lds_dwordx4 v[216:217], off
	s_waitcnt vmcnt(8) lgkmcnt(0)
	s_barrier
	s_setprio 1
	v_mfma_f32_16x16x32_bf16 v[132:135], v[120:123], v[160:163], v[132:135]
	v_mfma_f32_16x16x32_bf16 v[128:131], v[136:139], v[160:163], v[128:131]
	v_mfma_f32_16x16x32_bf16 v[108:111], v[120:123], v[168:171], v[108:111]
	v_mfma_f32_16x16x32_bf16 v[104:107], v[136:139], v[168:171], v[104:107]
	v_mfma_f32_16x16x32_bf16 v[92:95], v[120:123], v[176:179], v[92:95]
	v_mfma_f32_16x16x32_bf16 v[88:91], v[136:139], v[176:179], v[88:91]
	v_mfma_f32_16x16x32_bf16 v[76:79], v[120:123], v[200:203], v[76:79]
	v_mfma_f32_16x16x32_bf16 v[72:75], v[136:139], v[200:203], v[72:75]
	v_mfma_f32_16x16x32_bf16 v[132:135], v[124:127], v[164:167], v[132:135]
	v_mfma_f32_16x16x32_bf16 v[128:131], v[140:143], v[164:167], v[128:131]
	v_mfma_f32_16x16x32_bf16 v[108:111], v[124:127], v[172:175], v[108:111]
	v_mfma_f32_16x16x32_bf16 v[104:107], v[140:143], v[172:175], v[104:107]
	v_mfma_f32_16x16x32_bf16 v[92:95], v[124:127], v[180:183], v[92:95]
	v_mfma_f32_16x16x32_bf16 v[88:91], v[140:143], v[180:183], v[88:91]
	v_mfma_f32_16x16x32_bf16 v[76:79], v[124:127], v[204:207], v[76:79]
	v_mfma_f32_16x16x32_bf16 v[72:75], v[140:143], v[204:207], v[72:75]
	v_mfma_f32_16x16x32_bf16 v[116:119], v[144:147], v[160:163], v[116:119]
	v_mfma_f32_16x16x32_bf16 v[112:115], v[152:155], v[160:163], v[112:115]
	v_mfma_f32_16x16x32_bf16 v[100:103], v[144:147], v[168:171], v[100:103]
	v_mfma_f32_16x16x32_bf16 v[96:99], v[152:155], v[168:171], v[96:99]
	v_mfma_f32_16x16x32_bf16 v[84:87], v[144:147], v[176:179], v[84:87]
	v_mfma_f32_16x16x32_bf16 v[80:83], v[152:155], v[176:179], v[80:83]
	v_mfma_f32_16x16x32_bf16 v[68:71], v[144:147], v[200:203], v[68:71]
	v_mfma_f32_16x16x32_bf16 v[64:67], v[152:155], v[200:203], v[64:67]
	v_mfma_f32_16x16x32_bf16 v[116:119], v[148:151], v[164:167], v[116:119]
	v_mfma_f32_16x16x32_bf16 v[112:115], v[156:159], v[164:167], v[112:115]
	v_mfma_f32_16x16x32_bf16 v[100:103], v[148:151], v[172:175], v[100:103]
	v_mfma_f32_16x16x32_bf16 v[96:99], v[156:159], v[172:175], v[96:99]
	s_setprio 2
	s_barrier
	v_mfma_f32_16x16x32_bf16 v[84:87], v[148:151], v[180:183], v[84:87]
	v_mfma_f32_16x16x32_bf16 v[80:83], v[156:159], v[180:183], v[80:83]
	v_mfma_f32_16x16x32_bf16 v[68:71], v[148:151], v[204:207], v[68:71]
	v_mfma_f32_16x16x32_bf16 v[64:67], v[156:159], v[204:207], v[64:67]
	s_setprio 2
	s_add_i32 s26, s65, s43
	v_lshl_add_u64 v[208:209], v[208:209], 0, s[20:21]
	s_mov_b32 m0, s26
	ds_read_b128 v[160:163], v235 offset:49152
	ds_read_b128 v[164:167], v235 offset:50176
	ds_read_b128 v[168:171], v235 offset:51200
	ds_read_b128 v[172:175], v235 offset:52224
	ds_read_b128 v[176:179], v235 offset:53248
	ds_read_b128 v[180:183], v235 offset:54272
	ds_read_b128 v[200:203], v235 offset:55296
	ds_read_b128 v[204:207], v235 offset:56320
	global_load_lds_dwordx4 v[208:209], off
	s_add_i32 m0, s26, 0x2000
	s_add_u32 s26, s30, 0xb0080
	v_lshl_add_u64 v[208:209], v[210:211], 0, s[20:21]
	s_addc_u32 s27, s31, 0
	s_add_i32 s30, s66, s43
	global_load_lds_dwordx4 v[208:209], off
	s_mov_b32 m0, s30
	v_lshl_add_u64 v[208:209], s[26:27], 0, v[186:187]
	global_load_lds_dwordx4 v[208:209], off
	s_add_i32 m0, s30, 0x2000
	v_lshl_add_u64 v[208:209], s[26:27], 0, v[190:191]
	global_load_lds_dwordx4 v[208:209], off
	s_mov_b32 m0, s49
	v_lshl_add_u64 v[208:209], v[212:213], 0, s[20:21]
	global_load_lds_dwordx4 v[208:209], off
	s_mov_b32 m0, s50
	v_lshl_add_u64 v[208:209], v[214:215], 0, s[20:21]
	global_load_lds_dwordx4 v[208:209], off
	s_waitcnt vmcnt(8) lgkmcnt(0)
	s_barrier
	s_setprio 1
	v_mfma_f32_16x16x32_bf16 v[60:63], v[120:123], v[160:163], v[60:63]
	v_mfma_f32_16x16x32_bf16 v[56:59], v[136:139], v[160:163], v[56:59]
	v_mfma_f32_16x16x32_bf16 v[44:47], v[120:123], v[168:171], v[44:47]
	v_mfma_f32_16x16x32_bf16 v[40:43], v[136:139], v[168:171], v[40:43]
	v_mfma_f32_16x16x32_bf16 v[28:31], v[120:123], v[176:179], v[28:31]
	v_mfma_f32_16x16x32_bf16 v[24:27], v[136:139], v[176:179], v[24:27]
	v_mfma_f32_16x16x32_bf16 v[12:15], v[120:123], v[200:203], v[12:15]
	v_mfma_f32_16x16x32_bf16 v[8:11], v[136:139], v[200:203], v[8:11]
	v_mfma_f32_16x16x32_bf16 v[60:63], v[124:127], v[164:167], v[60:63]
	v_mfma_f32_16x16x32_bf16 v[56:59], v[140:143], v[164:167], v[56:59]
	v_mfma_f32_16x16x32_bf16 v[44:47], v[124:127], v[172:175], v[44:47]
	v_mfma_f32_16x16x32_bf16 v[40:43], v[140:143], v[172:175], v[40:43]
	v_mfma_f32_16x16x32_bf16 v[28:31], v[124:127], v[180:183], v[28:31]
	v_mfma_f32_16x16x32_bf16 v[24:27], v[140:143], v[180:183], v[24:27]
	v_mfma_f32_16x16x32_bf16 v[12:15], v[124:127], v[204:207], v[12:15]
	v_mfma_f32_16x16x32_bf16 v[8:11], v[140:143], v[204:207], v[8:11]
	v_mfma_f32_16x16x32_bf16 v[52:55], v[144:147], v[160:163], v[52:55]
	v_mfma_f32_16x16x32_bf16 v[48:51], v[152:155], v[160:163], v[48:51]
	v_mfma_f32_16x16x32_bf16 v[36:39], v[144:147], v[168:171], v[36:39]
	v_mfma_f32_16x16x32_bf16 v[32:35], v[152:155], v[168:171], v[32:35]
	v_mfma_f32_16x16x32_bf16 v[20:23], v[144:147], v[176:179], v[20:23]
	v_mfma_f32_16x16x32_bf16 v[16:19], v[152:155], v[176:179], v[16:19]
	v_mfma_f32_16x16x32_bf16 v[4:7], v[144:147], v[200:203], v[4:7]
	v_mfma_f32_16x16x32_bf16 v[0:3], v[152:155], v[200:203], v[0:3]
	v_mfma_f32_16x16x32_bf16 v[52:55], v[148:151], v[164:167], v[52:55]
	v_mfma_f32_16x16x32_bf16 v[48:51], v[156:159], v[164:167], v[48:51]
	v_mfma_f32_16x16x32_bf16 v[36:39], v[148:151], v[172:175], v[36:39]
	v_mfma_f32_16x16x32_bf16 v[32:35], v[156:159], v[172:175], v[32:35]
	s_setprio 2
	s_barrier
	v_mfma_f32_16x16x32_bf16 v[20:23], v[148:151], v[180:183], v[20:23]
	v_mfma_f32_16x16x32_bf16 v[16:19], v[156:159], v[180:183], v[16:19]
	v_mfma_f32_16x16x32_bf16 v[4:7], v[148:151], v[204:207], v[4:7]
	v_mfma_f32_16x16x32_bf16 v[0:3], v[156:159], v[204:207], v[0:3]
	s_setprio 0
	s_add_i32 s64, s64, 2
	s_add_u32 s62, s62, 0x100
	s_addc_u32 s63, s63, 0
	s_cmp_gt_u32 s64, 41
	s_mov_b64 s[26:27], s[28:29]
.LBB0_866:
	ds_read_b128 v[120:123], v233
	ds_read_b128 v[124:127], v233 offset:1024
	ds_read_b128 v[136:139], v233 offset:2048
	ds_read_b128 v[140:143], v233 offset:3072
	ds_read_b128 v[144:147], v234
	ds_read_b128 v[148:151], v234 offset:1024
	ds_read_b128 v[152:155], v234 offset:2048
	ds_read_b128 v[156:159], v234 offset:3072
	s_add_u32 s28, s26, 0x100
	s_addc_u32 s29, s27, 0
	s_cmp_eq_u32 s64, 40
	s_cselect_b32 s37, s7, s29
	s_cselect_b32 s36, s6, s28
	s_cselect_b32 s31, s25, s63
	s_cselect_b32 s30, s24, s62
	v_lshl_add_u64 v[208:209], s[26:27], 0, v[192:193]
	s_add_i32 m0, s44, 0xc000
	ds_read_b128 v[160:163], v235
	ds_read_b128 v[164:167], v235 offset:1024
	ds_read_b128 v[168:171], v235 offset:2048
	ds_read_b128 v[172:175], v235 offset:3072
	ds_read_b128 v[176:179], v235 offset:4096
	ds_read_b128 v[180:183], v235 offset:5120
	ds_read_b128 v[200:203], v235 offset:6144
	ds_read_b128 v[204:207], v235 offset:7168
	global_load_lds_dwordx4 v[208:209], off
	s_add_i32 m0, s44, 0xe000
	v_lshl_add_u64 v[208:209], s[26:27], 0, v[194:195]
	global_load_lds_dwordx4 v[208:209], off
	s_waitcnt vmcnt(8) lgkmcnt(0)
	s_barrier
	s_setprio 1
	v_mfma_f32_16x16x32_bf16 v[132:135], v[120:123], v[160:163], v[132:135]
	v_mfma_f32_16x16x32_bf16 v[128:131], v[136:139], v[160:163], v[128:131]
	v_mfma_f32_16x16x32_bf16 v[108:111], v[120:123], v[168:171], v[108:111]
	v_mfma_f32_16x16x32_bf16 v[104:107], v[136:139], v[168:171], v[104:107]
	v_mfma_f32_16x16x32_bf16 v[92:95], v[120:123], v[176:179], v[92:95]
	v_mfma_f32_16x16x32_bf16 v[88:91], v[136:139], v[176:179], v[88:91]
	v_mfma_f32_16x16x32_bf16 v[76:79], v[120:123], v[200:203], v[76:79]
	v_mfma_f32_16x16x32_bf16 v[72:75], v[136:139], v[200:203], v[72:75]
	v_mfma_f32_16x16x32_bf16 v[132:135], v[124:127], v[164:167], v[132:135]
	v_mfma_f32_16x16x32_bf16 v[128:131], v[140:143], v[164:167], v[128:131]
	v_mfma_f32_16x16x32_bf16 v[108:111], v[124:127], v[172:175], v[108:111]
	v_mfma_f32_16x16x32_bf16 v[104:107], v[140:143], v[172:175], v[104:107]
	v_mfma_f32_16x16x32_bf16 v[92:95], v[124:127], v[180:183], v[92:95]
	v_mfma_f32_16x16x32_bf16 v[88:91], v[140:143], v[180:183], v[88:91]
	v_mfma_f32_16x16x32_bf16 v[76:79], v[124:127], v[204:207], v[76:79]
	v_mfma_f32_16x16x32_bf16 v[72:75], v[140:143], v[204:207], v[72:75]
	v_mfma_f32_16x16x32_bf16 v[116:119], v[144:147], v[160:163], v[116:119]
	v_mfma_f32_16x16x32_bf16 v[112:115], v[152:155], v[160:163], v[112:115]
	v_mfma_f32_16x16x32_bf16 v[100:103], v[144:147], v[168:171], v[100:103]
	v_mfma_f32_16x16x32_bf16 v[96:99], v[152:155], v[168:171], v[96:99]
	v_mfma_f32_16x16x32_bf16 v[84:87], v[144:147], v[176:179], v[84:87]
	v_mfma_f32_16x16x32_bf16 v[80:83], v[152:155], v[176:179], v[80:83]
	v_mfma_f32_16x16x32_bf16 v[68:71], v[144:147], v[200:203], v[68:71]
	v_mfma_f32_16x16x32_bf16 v[64:67], v[152:155], v[200:203], v[64:67]
	v_mfma_f32_16x16x32_bf16 v[116:119], v[148:151], v[164:167], v[116:119]
	v_mfma_f32_16x16x32_bf16 v[112:115], v[156:159], v[164:167], v[112:115]
	v_mfma_f32_16x16x32_bf16 v[100:103], v[148:151], v[172:175], v[100:103]
	v_mfma_f32_16x16x32_bf16 v[96:99], v[156:159], v[172:175], v[96:99]
	s_setprio 2
	s_barrier
	v_mfma_f32_16x16x32_bf16 v[84:87], v[148:151], v[180:183], v[84:87]
	v_mfma_f32_16x16x32_bf16 v[80:83], v[156:159], v[180:183], v[80:83]
	v_mfma_f32_16x16x32_bf16 v[68:71], v[148:151], v[204:207], v[68:71]
	v_mfma_f32_16x16x32_bf16 v[64:67], v[156:159], v[204:207], v[64:67]
	s_setprio 2
	s_add_i32 s26, s56, s43
	v_lshl_add_u64 v[208:209], s[30:31], 0, v[186:187]
	s_mov_b32 m0, s26
	ds_read_b128 v[160:163], v235 offset:16384
	ds_read_b128 v[164:167], v235 offset:17408
	ds_read_b128 v[168:171], v235 offset:18432
	ds_read_b128 v[172:175], v235 offset:19456
	ds_read_b128 v[176:179], v235 offset:20480
	ds_read_b128 v[180:183], v235 offset:21504
	ds_read_b128 v[200:203], v235 offset:22528
	ds_read_b128 v[204:207], v235 offset:23552
	global_load_lds_dwordx4 v[208:209], off
	s_add_i32 m0, s26, 0x2000
	s_add_u32 s26, s30, 0xb0000
	v_lshl_add_u64 v[210:211], s[30:31], 0, v[190:191]
	s_addc_u32 s27, s31, 0
	s_add_i32 s65, s57, s43
	global_load_lds_dwordx4 v[210:211], off
	v_lshl_add_u64 v[212:213], s[26:27], 0, v[186:187]
	s_mov_b32 m0, s65
	v_lshl_add_u64 v[214:215], s[36:37], 0, v[188:189]
	global_load_lds_dwordx4 v[212:213], off
	s_add_i32 m0, s65, 0x2000
	v_lshl_add_u64 v[212:213], s[26:27], 0, v[190:191]
	global_load_lds_dwordx4 v[212:213], off
	s_mov_b32 m0, s44
	v_lshl_add_u64 v[212:213], s[36:37], 0, v[184:185]
	global_load_lds_dwordx4 v[212:213], off
	s_mov_b32 m0, s45
	s_nop 0
	global_load_lds_dwordx4 v[214:215], off
	s_waitcnt vmcnt(8) lgkmcnt(0)
	s_barrier
	s_setprio 1
	v_mfma_f32_16x16x32_bf16 v[60:63], v[120:123], v[160:163], v[60:63]
	v_mfma_f32_16x16x32_bf16 v[56:59], v[136:139], v[160:163], v[56:59]
	v_mfma_f32_16x16x32_bf16 v[44:47], v[120:123], v[168:171], v[44:47]
	v_mfma_f32_16x16x32_bf16 v[40:43], v[136:139], v[168:171], v[40:43]
	v_mfma_f32_16x16x32_bf16 v[28:31], v[120:123], v[176:179], v[28:31]
	v_mfma_f32_16x16x32_bf16 v[24:27], v[136:139], v[176:179], v[24:27]
	v_mfma_f32_16x16x32_bf16 v[12:15], v[120:123], v[200:203], v[12:15]
	v_mfma_f32_16x16x32_bf16 v[8:11], v[136:139], v[200:203], v[8:11]
	v_mfma_f32_16x16x32_bf16 v[60:63], v[124:127], v[164:167], v[60:63]
	v_mfma_f32_16x16x32_bf16 v[56:59], v[140:143], v[164:167], v[56:59]
	v_mfma_f32_16x16x32_bf16 v[44:47], v[124:127], v[172:175], v[44:47]
	v_mfma_f32_16x16x32_bf16 v[40:43], v[140:143], v[172:175], v[40:43]
	v_mfma_f32_16x16x32_bf16 v[28:31], v[124:127], v[180:183], v[28:31]
	v_mfma_f32_16x16x32_bf16 v[24:27], v[140:143], v[180:183], v[24:27]
	v_mfma_f32_16x16x32_bf16 v[12:15], v[124:127], v[204:207], v[12:15]
	v_mfma_f32_16x16x32_bf16 v[8:11], v[140:143], v[204:207], v[8:11]
	v_mfma_f32_16x16x32_bf16 v[52:55], v[144:147], v[160:163], v[52:55]
	v_mfma_f32_16x16x32_bf16 v[48:51], v[152:155], v[160:163], v[48:51]
	v_mfma_f32_16x16x32_bf16 v[36:39], v[144:147], v[168:171], v[36:39]
	v_mfma_f32_16x16x32_bf16 v[32:35], v[152:155], v[168:171], v[32:35]
	v_mfma_f32_16x16x32_bf16 v[20:23], v[144:147], v[176:179], v[20:23]
	v_mfma_f32_16x16x32_bf16 v[16:19], v[152:155], v[176:179], v[16:19]
	v_mfma_f32_16x16x32_bf16 v[4:7], v[144:147], v[200:203], v[4:7]
	v_mfma_f32_16x16x32_bf16 v[0:3], v[152:155], v[200:203], v[0:3]
	v_mfma_f32_16x16x32_bf16 v[52:55], v[148:151], v[164:167], v[52:55]
	v_mfma_f32_16x16x32_bf16 v[48:51], v[156:159], v[164:167], v[48:51]
	v_mfma_f32_16x16x32_bf16 v[36:39], v[148:151], v[172:175], v[36:39]
	v_mfma_f32_16x16x32_bf16 v[32:35], v[156:159], v[172:175], v[32:35]
	s_setprio 2
	s_barrier
	v_mfma_f32_16x16x32_bf16 v[20:23], v[148:151], v[180:183], v[20:23]
	v_mfma_f32_16x16x32_bf16 v[16:19], v[156:159], v[180:183], v[16:19]
	v_mfma_f32_16x16x32_bf16 v[4:7], v[148:151], v[204:207], v[4:7]
	v_mfma_f32_16x16x32_bf16 v[0:3], v[156:159], v[204:207], v[0:3]
	s_setprio 0
	s_add_i32 s65, 0, 0x18000
	s_add_i32 s66, 0, 0x1c000
	v_add_u32_e32 v140, s65, v232
	v_add_u32_e32 v156, s66, v232
	ds_read_b128 v[120:123], v140
	ds_read_b128 v[124:127], v140 offset:1024
	ds_read_b128 v[136:139], v140 offset:2048
	ds_read_b128 v[140:143], v140 offset:3072
	ds_read_b128 v[144:147], v156
	ds_read_b128 v[148:151], v156 offset:1024
	ds_read_b128 v[152:155], v156 offset:2048
	ds_read_b128 v[156:159], v156 offset:3072
	s_add_u32 s26, s36, 0xb0000
	s_addc_u32 s27, s37, 0
	s_mov_b32 m0, s46
	v_lshl_add_u64 v[216:217], s[26:27], 0, v[184:185]
	ds_read_b128 v[160:163], v235 offset:32768
	ds_read_b128 v[164:167], v235 offset:33792
	ds_read_b128 v[168:171], v235 offset:34816
	ds_read_b128 v[172:175], v235 offset:35840
	ds_read_b128 v[176:179], v235 offset:36864
	ds_read_b128 v[180:183], v235 offset:37888
	ds_read_b128 v[200:203], v235 offset:38912
	ds_read_b128 v[204:207], v235 offset:39936
	global_load_lds_dwordx4 v[216:217], off
	s_mov_b32 m0, s47
	v_lshl_add_u64 v[216:217], s[26:27], 0, v[188:189]
	global_load_lds_dwordx4 v[216:217], off
	s_waitcnt vmcnt(8) lgkmcnt(0)
	s_barrier
	s_setprio 1
	v_mfma_f32_16x16x32_bf16 v[132:135], v[120:123], v[160:163], v[132:135]
	v_mfma_f32_16x16x32_bf16 v[128:131], v[136:139], v[160:163], v[128:131]
	v_mfma_f32_16x16x32_bf16 v[108:111], v[120:123], v[168:171], v[108:111]
	v_mfma_f32_16x16x32_bf16 v[104:107], v[136:139], v[168:171], v[104:107]
	v_mfma_f32_16x16x32_bf16 v[92:95], v[120:123], v[176:179], v[92:95]
	v_mfma_f32_16x16x32_bf16 v[88:91], v[136:139], v[176:179], v[88:91]
	v_mfma_f32_16x16x32_bf16 v[76:79], v[120:123], v[200:203], v[76:79]
	v_mfma_f32_16x16x32_bf16 v[72:75], v[136:139], v[200:203], v[72:75]
	v_mfma_f32_16x16x32_bf16 v[132:135], v[124:127], v[164:167], v[132:135]
	v_mfma_f32_16x16x32_bf16 v[128:131], v[140:143], v[164:167], v[128:131]
	v_mfma_f32_16x16x32_bf16 v[108:111], v[124:127], v[172:175], v[108:111]
	v_mfma_f32_16x16x32_bf16 v[104:107], v[140:143], v[172:175], v[104:107]
	v_mfma_f32_16x16x32_bf16 v[92:95], v[124:127], v[180:183], v[92:95]
	v_mfma_f32_16x16x32_bf16 v[88:91], v[140:143], v[180:183], v[88:91]
	v_mfma_f32_16x16x32_bf16 v[76:79], v[124:127], v[204:207], v[76:79]
	v_mfma_f32_16x16x32_bf16 v[72:75], v[140:143], v[204:207], v[72:75]
	v_mfma_f32_16x16x32_bf16 v[116:119], v[144:147], v[160:163], v[116:119]
	v_mfma_f32_16x16x32_bf16 v[112:115], v[152:155], v[160:163], v[112:115]
	v_mfma_f32_16x16x32_bf16 v[100:103], v[144:147], v[168:171], v[100:103]
	v_mfma_f32_16x16x32_bf16 v[96:99], v[152:155], v[168:171], v[96:99]
	v_mfma_f32_16x16x32_bf16 v[84:87], v[144:147], v[176:179], v[84:87]
	v_mfma_f32_16x16x32_bf16 v[80:83], v[152:155], v[176:179], v[80:83]
	v_mfma_f32_16x16x32_bf16 v[68:71], v[144:147], v[200:203], v[68:71]
	v_mfma_f32_16x16x32_bf16 v[64:67], v[152:155], v[200:203], v[64:67]
	v_mfma_f32_16x16x32_bf16 v[116:119], v[148:151], v[164:167], v[116:119]
	v_mfma_f32_16x16x32_bf16 v[112:115], v[156:159], v[164:167], v[112:115]
	v_mfma_f32_16x16x32_bf16 v[100:103], v[148:151], v[172:175], v[100:103]
	v_mfma_f32_16x16x32_bf16 v[96:99], v[156:159], v[172:175], v[96:99]
	s_setprio 2
	s_barrier
	v_mfma_f32_16x16x32_bf16 v[84:87], v[148:151], v[180:183], v[84:87]
	v_mfma_f32_16x16x32_bf16 v[80:83], v[156:159], v[180:183], v[80:83]
	v_mfma_f32_16x16x32_bf16 v[68:71], v[148:151], v[204:207], v[68:71]
	v_mfma_f32_16x16x32_bf16 v[64:67], v[156:159], v[204:207], v[64:67]
	s_setprio 2
	s_add_i32 s26, s65, s43
	v_lshl_add_u64 v[208:209], v[208:209], 0, s[20:21]
	s_mov_b32 m0, s26
	ds_read_b128 v[160:163], v235 offset:49152
	ds_read_b128 v[164:167], v235 offset:50176
	ds_read_b128 v[168:171], v235 offset:51200
	ds_read_b128 v[172:175], v235 offset:52224
	ds_read_b128 v[176:179], v235 offset:53248
	ds_read_b128 v[180:183], v235 offset:54272
	ds_read_b128 v[200:203], v235 offset:55296
	ds_read_b128 v[204:207], v235 offset:56320
	global_load_lds_dwordx4 v[208:209], off
	s_add_i32 m0, s26, 0x2000
	s_add_u32 s26, s30, 0xb0080
	v_lshl_add_u64 v[208:209], v[210:211], 0, s[20:21]
	s_addc_u32 s27, s31, 0
	s_add_i32 s30, s66, s43
	global_load_lds_dwordx4 v[208:209], off
	s_mov_b32 m0, s30
	v_lshl_add_u64 v[208:209], s[26:27], 0, v[186:187]
	global_load_lds_dwordx4 v[208:209], off
	s_add_i32 m0, s30, 0x2000
	v_lshl_add_u64 v[208:209], s[26:27], 0, v[190:191]
	global_load_lds_dwordx4 v[208:209], off
	s_mov_b32 m0, s49
	v_lshl_add_u64 v[208:209], v[212:213], 0, s[20:21]
	global_load_lds_dwordx4 v[208:209], off
	s_mov_b32 m0, s50
	v_lshl_add_u64 v[208:209], v[214:215], 0, s[20:21]
	global_load_lds_dwordx4 v[208:209], off
	s_waitcnt vmcnt(8) lgkmcnt(0)
	s_barrier
	s_setprio 1
	v_mfma_f32_16x16x32_bf16 v[60:63], v[120:123], v[160:163], v[60:63]
	v_mfma_f32_16x16x32_bf16 v[56:59], v[136:139], v[160:163], v[56:59]
	v_mfma_f32_16x16x32_bf16 v[44:47], v[120:123], v[168:171], v[44:47]
	v_mfma_f32_16x16x32_bf16 v[40:43], v[136:139], v[168:171], v[40:43]
	v_mfma_f32_16x16x32_bf16 v[28:31], v[120:123], v[176:179], v[28:31]
	v_mfma_f32_16x16x32_bf16 v[24:27], v[136:139], v[176:179], v[24:27]
	v_mfma_f32_16x16x32_bf16 v[12:15], v[120:123], v[200:203], v[12:15]
	v_mfma_f32_16x16x32_bf16 v[8:11], v[136:139], v[200:203], v[8:11]
	v_mfma_f32_16x16x32_bf16 v[60:63], v[124:127], v[164:167], v[60:63]
	v_mfma_f32_16x16x32_bf16 v[56:59], v[140:143], v[164:167], v[56:59]
	v_mfma_f32_16x16x32_bf16 v[44:47], v[124:127], v[172:175], v[44:47]
	v_mfma_f32_16x16x32_bf16 v[40:43], v[140:143], v[172:175], v[40:43]
	v_mfma_f32_16x16x32_bf16 v[28:31], v[124:127], v[180:183], v[28:31]
	v_mfma_f32_16x16x32_bf16 v[24:27], v[140:143], v[180:183], v[24:27]
	v_mfma_f32_16x16x32_bf16 v[12:15], v[124:127], v[204:207], v[12:15]
	v_mfma_f32_16x16x32_bf16 v[8:11], v[140:143], v[204:207], v[8:11]
	v_mfma_f32_16x16x32_bf16 v[52:55], v[144:147], v[160:163], v[52:55]
	v_mfma_f32_16x16x32_bf16 v[48:51], v[152:155], v[160:163], v[48:51]
	v_mfma_f32_16x16x32_bf16 v[36:39], v[144:147], v[168:171], v[36:39]
	v_mfma_f32_16x16x32_bf16 v[32:35], v[152:155], v[168:171], v[32:35]
	v_mfma_f32_16x16x32_bf16 v[20:23], v[144:147], v[176:179], v[20:23]
	v_mfma_f32_16x16x32_bf16 v[16:19], v[152:155], v[176:179], v[16:19]
	v_mfma_f32_16x16x32_bf16 v[4:7], v[144:147], v[200:203], v[4:7]
	v_mfma_f32_16x16x32_bf16 v[0:3], v[152:155], v[200:203], v[0:3]
	v_mfma_f32_16x16x32_bf16 v[52:55], v[148:151], v[164:167], v[52:55]
	v_mfma_f32_16x16x32_bf16 v[48:51], v[156:159], v[164:167], v[48:51]
	v_mfma_f32_16x16x32_bf16 v[36:39], v[148:151], v[172:175], v[36:39]
	v_mfma_f32_16x16x32_bf16 v[32:35], v[156:159], v[172:175], v[32:35]
	s_setprio 2
	s_barrier
	v_mfma_f32_16x16x32_bf16 v[20:23], v[148:151], v[180:183], v[20:23]
	v_mfma_f32_16x16x32_bf16 v[16:19], v[156:159], v[180:183], v[16:19]
	v_mfma_f32_16x16x32_bf16 v[4:7], v[148:151], v[204:207], v[4:7]
	v_mfma_f32_16x16x32_bf16 v[0:3], v[156:159], v[204:207], v[0:3]
	s_setprio 0
	s_add_i32 s64, s64, 2
	s_add_u32 s62, s62, 0x100
	s_addc_u32 s63, s63, 0
	s_cmp_gt_u32 s64, 41
	s_mov_b64 s[26:27], s[28:29]
	s_cbranch_scc0 .LBB0_866

.LBB0_951:
	s_ashr_i32 s27, s26, 31
	s_lshl_b64 s[30:31], s[26:27], 19
	s_add_u32 s30, s47, s30
	s_addc_u32 s31, s48, s31
	s_and_b64 s[36:37], s[4:5], exec
	s_cselect_b32 s27, s31, s7
	s_cselect_b32 s39, s30, s6
	s_ashr_i32 s29, s28, 31
	s_lshl_b64 s[36:37], s[28:29], 19
	s_add_u32 s36, s49, s36
	s_addc_u32 s37, s50, s37
	s_and_b64 s[44:45], s[4:5], exec
	s_cselect_b32 s29, s37, s41
	s_cselect_b32 s43, s36, s40
	s_add_u32 s6, s6, 0x40080
	s_addc_u32 s7, s7, 0
	s_add_u32 s71, s40, 0x100
	s_addc_u32 s72, s41, 0
	s_mov_b32 s73, -2
	ds_read_b128 v[144:147], v179
	ds_read_b128 v[148:151], v179 offset:1024
	ds_read_b128 v[152:155], v179 offset:2048
	ds_read_b128 v[156:159], v179 offset:3072
	ds_read_b128 v[160:163], v180
	ds_read_b128 v[164:167], v180 offset:1024
	ds_read_b128 v[168:171], v180 offset:2048
	ds_read_b128 v[172:175], v180 offset:3072
	s_add_u32 s40, s6, 0xfffc0080
	s_addc_u32 s41, s7, -1
	s_cmp_eq_u32 s73, 12
	s_cselect_b32 s45, s27, s41
	s_cselect_b32 s44, s39, s40
	s_cselect_b32 s41, s29, s72
	s_cselect_b32 s40, s43, s71
	v_lshl_add_u64 v[176:177], s[6:7], 0, v[136:137]
	s_add_i32 m0, s54, 0xc000
	ds_read_b128 v[184:187], v181
	ds_read_b128 v[188:191], v181 offset:1024
	ds_read_b128 v[192:195], v181 offset:2048
	ds_read_b128 v[196:199], v181 offset:3072
	ds_read_b128 v[200:203], v181 offset:4096
	ds_read_b128 v[204:207], v181 offset:5120
	ds_read_b128 v[208:211], v181 offset:6144
	ds_read_b128 v[212:215], v181 offset:7168
	global_load_lds_dwordx4 v[176:177], off
	s_add_i32 m0, s54, 0xe000
	v_lshl_add_u64 v[176:177], s[6:7], 0, v[138:139]
	global_load_lds_dwordx4 v[176:177], off
	s_waitcnt vmcnt(8) lgkmcnt(0)
	s_barrier
	s_setprio 1
	v_mfma_f32_16x16x32_bf16 v[124:127], v[144:147], v[184:187], 0
	v_mfma_f32_16x16x32_bf16 v[120:123], v[152:155], v[184:187], 0
	v_mfma_f32_16x16x32_bf16 v[108:111], v[144:147], v[192:195], 0
	v_mfma_f32_16x16x32_bf16 v[104:107], v[152:155], v[192:195], 0
	v_mfma_f32_16x16x32_bf16 v[92:95], v[144:147], v[200:203], 0
	v_mfma_f32_16x16x32_bf16 v[88:91], v[152:155], v[200:203], 0
	v_mfma_f32_16x16x32_bf16 v[76:79], v[144:147], v[208:211], 0
	v_mfma_f32_16x16x32_bf16 v[72:75], v[152:155], v[208:211], 0
	v_mfma_f32_16x16x32_bf16 v[124:127], v[148:151], v[188:191], v[124:127]
	v_mfma_f32_16x16x32_bf16 v[120:123], v[156:159], v[188:191], v[120:123]
	v_mfma_f32_16x16x32_bf16 v[108:111], v[148:151], v[196:199], v[108:111]
	v_mfma_f32_16x16x32_bf16 v[104:107], v[156:159], v[196:199], v[104:107]
	v_mfma_f32_16x16x32_bf16 v[92:95], v[148:151], v[204:207], v[92:95]
	v_mfma_f32_16x16x32_bf16 v[88:91], v[156:159], v[204:207], v[88:91]
	v_mfma_f32_16x16x32_bf16 v[76:79], v[148:151], v[212:215], v[76:79]
	v_mfma_f32_16x16x32_bf16 v[72:75], v[156:159], v[212:215], v[72:75]
	v_mfma_f32_16x16x32_bf16 v[116:119], v[160:163], v[184:187], 0
	v_mfma_f32_16x16x32_bf16 v[112:115], v[168:171], v[184:187], 0
	v_mfma_f32_16x16x32_bf16 v[100:103], v[160:163], v[192:195], 0
	v_mfma_f32_16x16x32_bf16 v[96:99], v[168:171], v[192:195], 0
	v_mfma_f32_16x16x32_bf16 v[84:87], v[160:163], v[200:203], 0
	v_mfma_f32_16x16x32_bf16 v[80:83], v[168:171], v[200:203], 0
	v_mfma_f32_16x16x32_bf16 v[68:71], v[160:163], v[208:211], 0
	v_mfma_f32_16x16x32_bf16 v[64:67], v[168:171], v[208:211], 0
	v_mfma_f32_16x16x32_bf16 v[116:119], v[164:167], v[188:191], v[116:119]
	v_mfma_f32_16x16x32_bf16 v[112:115], v[172:175], v[188:191], v[112:115]
	v_mfma_f32_16x16x32_bf16 v[100:103], v[164:167], v[196:199], v[100:103]
	v_mfma_f32_16x16x32_bf16 v[96:99], v[172:175], v[196:199], v[96:99]
	s_setprio 2
	s_barrier
	v_mfma_f32_16x16x32_bf16 v[84:87], v[164:167], v[204:207], v[84:87]
	v_mfma_f32_16x16x32_bf16 v[80:83], v[172:175], v[204:207], v[80:83]
	v_mfma_f32_16x16x32_bf16 v[68:71], v[164:167], v[212:215], v[68:71]
	v_mfma_f32_16x16x32_bf16 v[64:67], v[172:175], v[212:215], v[64:67]
	s_setprio 2
	s_add_i32 s74, s69, s51
	v_lshl_add_u64 v[176:177], s[40:41], 0, v[130:131]
	s_mov_b32 m0, s74
	ds_read_b128 v[184:187], v181 offset:16384
	ds_read_b128 v[188:191], v181 offset:17408
	ds_read_b128 v[192:195], v181 offset:18432
	ds_read_b128 v[196:199], v181 offset:19456
	ds_read_b128 v[200:203], v181 offset:20480
	ds_read_b128 v[204:207], v181 offset:21504
	ds_read_b128 v[208:211], v181 offset:22528
	ds_read_b128 v[212:215], v181 offset:23552
	global_load_lds_dwordx4 v[176:177], off
	s_add_i32 m0, s74, 0x2000
	s_add_u32 s74, s40, 0x40000
	v_lshl_add_u64 v[216:217], s[40:41], 0, v[134:135]
	s_addc_u32 s75, s41, 0
	s_add_i32 s76, s70, s51
	global_load_lds_dwordx4 v[216:217], off
	v_lshl_add_u64 v[218:219], s[74:75], 0, v[130:131]
	s_mov_b32 m0, s76
	v_lshl_add_u64 v[220:221], s[44:45], 0, v[132:133]
	global_load_lds_dwordx4 v[218:219], off
	s_add_i32 m0, s76, 0x2000
	v_lshl_add_u64 v[218:219], s[74:75], 0, v[134:135]
	global_load_lds_dwordx4 v[218:219], off
	s_mov_b32 m0, s54
	v_lshl_add_u64 v[218:219], s[44:45], 0, v[128:129]
	global_load_lds_dwordx4 v[218:219], off
	s_mov_b32 m0, s55
	s_nop 0
	global_load_lds_dwordx4 v[220:221], off
	s_waitcnt vmcnt(8) lgkmcnt(0)
	s_barrier
	s_setprio 1
	v_mfma_f32_16x16x32_bf16 v[60:63], v[144:147], v[184:187], 0
	v_mfma_f32_16x16x32_bf16 v[56:59], v[152:155], v[184:187], 0
	v_mfma_f32_16x16x32_bf16 v[44:47], v[144:147], v[192:195], 0
	v_mfma_f32_16x16x32_bf16 v[40:43], v[152:155], v[192:195], 0
	v_mfma_f32_16x16x32_bf16 v[28:31], v[144:147], v[200:203], 0
	v_mfma_f32_16x16x32_bf16 v[24:27], v[152:155], v[200:203], 0
	v_mfma_f32_16x16x32_bf16 v[12:15], v[144:147], v[208:211], 0
	v_mfma_f32_16x16x32_bf16 v[8:11], v[152:155], v[208:211], 0
	v_mfma_f32_16x16x32_bf16 v[60:63], v[148:151], v[188:191], v[60:63]
	v_mfma_f32_16x16x32_bf16 v[56:59], v[156:159], v[188:191], v[56:59]
	v_mfma_f32_16x16x32_bf16 v[44:47], v[148:151], v[196:199], v[44:47]
	v_mfma_f32_16x16x32_bf16 v[40:43], v[156:159], v[196:199], v[40:43]
	v_mfma_f32_16x16x32_bf16 v[28:31], v[148:151], v[204:207], v[28:31]
	v_mfma_f32_16x16x32_bf16 v[24:27], v[156:159], v[204:207], v[24:27]
	v_mfma_f32_16x16x32_bf16 v[12:15], v[148:151], v[212:215], v[12:15]
	v_mfma_f32_16x16x32_bf16 v[8:11], v[156:159], v[212:215], v[8:11]
	v_mfma_f32_16x16x32_bf16 v[52:55], v[160:163], v[184:187], 0
	v_mfma_f32_16x16x32_bf16 v[48:51], v[168:171], v[184:187], 0
	v_mfma_f32_16x16x32_bf16 v[36:39], v[160:163], v[192:195], 0
	v_mfma_f32_16x16x32_bf16 v[32:35], v[168:171], v[192:195], 0
	v_mfma_f32_16x16x32_bf16 v[20:23], v[160:163], v[200:203], 0
	v_mfma_f32_16x16x32_bf16 v[16:19], v[168:171], v[200:203], 0
	v_mfma_f32_16x16x32_bf16 v[4:7], v[160:163], v[208:211], 0
	v_mfma_f32_16x16x32_bf16 v[0:3], v[168:171], v[208:211], 0
	v_mfma_f32_16x16x32_bf16 v[52:55], v[164:167], v[188:191], v[52:55]
	v_mfma_f32_16x16x32_bf16 v[48:51], v[172:175], v[188:191], v[48:51]
	v_mfma_f32_16x16x32_bf16 v[36:39], v[164:167], v[196:199], v[36:39]
	v_mfma_f32_16x16x32_bf16 v[32:35], v[172:175], v[196:199], v[32:35]
	s_setprio 2
	s_barrier
	v_mfma_f32_16x16x32_bf16 v[20:23], v[164:167], v[204:207], v[20:23]
	v_mfma_f32_16x16x32_bf16 v[16:19], v[172:175], v[204:207], v[16:19]
	v_mfma_f32_16x16x32_bf16 v[4:7], v[164:167], v[212:215], v[4:7]
	v_mfma_f32_16x16x32_bf16 v[0:3], v[172:175], v[212:215], v[0:3]
	s_setprio 0
	s_add_i32 s74, 0, 0x18000
	s_add_i32 s75, 0, 0x1c000
	v_add_u32_e32 v156, s74, v178
	v_add_u32_e32 v172, s75, v178
	ds_read_b128 v[144:147], v156
	ds_read_b128 v[148:151], v156 offset:1024
	ds_read_b128 v[152:155], v156 offset:2048
	ds_read_b128 v[156:159], v156 offset:3072
	ds_read_b128 v[160:163], v172
	ds_read_b128 v[164:167], v172 offset:1024
	ds_read_b128 v[168:171], v172 offset:2048
	ds_read_b128 v[172:175], v172 offset:3072
	s_add_u32 s44, s44, 0x40000
	s_addc_u32 s45, s45, 0
	s_mov_b32 m0, s56
	v_lshl_add_u64 v[222:223], s[44:45], 0, v[128:129]
	ds_read_b128 v[184:187], v181 offset:32768
	ds_read_b128 v[188:191], v181 offset:33792
	ds_read_b128 v[192:195], v181 offset:34816
	ds_read_b128 v[196:199], v181 offset:35840
	ds_read_b128 v[200:203], v181 offset:36864
	ds_read_b128 v[204:207], v181 offset:37888
	ds_read_b128 v[208:211], v181 offset:38912
	ds_read_b128 v[212:215], v181 offset:39936
	global_load_lds_dwordx4 v[222:223], off
	s_mov_b32 m0, s57
	v_lshl_add_u64 v[222:223], s[44:45], 0, v[132:133]
	global_load_lds_dwordx4 v[222:223], off
	s_waitcnt vmcnt(8) lgkmcnt(0)
	s_barrier
	s_setprio 1
	v_mfma_f32_16x16x32_bf16 v[124:127], v[144:147], v[184:187], v[124:127]
	v_mfma_f32_16x16x32_bf16 v[120:123], v[152:155], v[184:187], v[120:123]
	v_mfma_f32_16x16x32_bf16 v[108:111], v[144:147], v[192:195], v[108:111]
	v_mfma_f32_16x16x32_bf16 v[104:107], v[152:155], v[192:195], v[104:107]
	v_mfma_f32_16x16x32_bf16 v[92:95], v[144:147], v[200:203], v[92:95]
	v_mfma_f32_16x16x32_bf16 v[88:91], v[152:155], v[200:203], v[88:91]
	v_mfma_f32_16x16x32_bf16 v[76:79], v[144:147], v[208:211], v[76:79]
	v_mfma_f32_16x16x32_bf16 v[72:75], v[152:155], v[208:211], v[72:75]
	v_mfma_f32_16x16x32_bf16 v[124:127], v[148:151], v[188:191], v[124:127]
	v_mfma_f32_16x16x32_bf16 v[120:123], v[156:159], v[188:191], v[120:123]
	v_mfma_f32_16x16x32_bf16 v[108:111], v[148:151], v[196:199], v[108:111]
	v_mfma_f32_16x16x32_bf16 v[104:107], v[156:159], v[196:199], v[104:107]
	v_mfma_f32_16x16x32_bf16 v[92:95], v[148:151], v[204:207], v[92:95]
	v_mfma_f32_16x16x32_bf16 v[88:91], v[156:159], v[204:207], v[88:91]
	v_mfma_f32_16x16x32_bf16 v[76:79], v[148:151], v[212:215], v[76:79]
	v_mfma_f32_16x16x32_bf16 v[72:75], v[156:159], v[212:215], v[72:75]
	v_mfma_f32_16x16x32_bf16 v[116:119], v[160:163], v[184:187], v[116:119]
	v_mfma_f32_16x16x32_bf16 v[112:115], v[168:171], v[184:187], v[112:115]
	v_mfma_f32_16x16x32_bf16 v[100:103], v[160:163], v[192:195], v[100:103]
	v_mfma_f32_16x16x32_bf16 v[96:99], v[168:171], v[192:195], v[96:99]
	v_mfma_f32_16x16x32_bf16 v[84:87], v[160:163], v[200:203], v[84:87]
	v_mfma_f32_16x16x32_bf16 v[80:83], v[168:171], v[200:203], v[80:83]
	v_mfma_f32_16x16x32_bf16 v[68:71], v[160:163], v[208:211], v[68:71]
	v_mfma_f32_16x16x32_bf16 v[64:67], v[168:171], v[208:211], v[64:67]
	v_mfma_f32_16x16x32_bf16 v[116:119], v[164:167], v[188:191], v[116:119]
	v_mfma_f32_16x16x32_bf16 v[112:115], v[172:175], v[188:191], v[112:115]
	v_mfma_f32_16x16x32_bf16 v[100:103], v[164:167], v[196:199], v[100:103]
	v_mfma_f32_16x16x32_bf16 v[96:99], v[172:175], v[196:199], v[96:99]
	s_setprio 2
	s_barrier
	v_mfma_f32_16x16x32_bf16 v[84:87], v[164:167], v[204:207], v[84:87]
	v_mfma_f32_16x16x32_bf16 v[80:83], v[172:175], v[204:207], v[80:83]
	v_mfma_f32_16x16x32_bf16 v[68:71], v[164:167], v[212:215], v[68:71]
	v_mfma_f32_16x16x32_bf16 v[64:67], v[172:175], v[212:215], v[64:67]
	s_setprio 2
	s_add_i32 s44, s74, s51
	v_lshl_add_u64 v[176:177], v[176:177], 0, s[22:23]
	s_mov_b32 m0, s44
	ds_read_b128 v[184:187], v181 offset:49152
	ds_read_b128 v[188:191], v181 offset:50176
	ds_read_b128 v[192:195], v181 offset:51200
	ds_read_b128 v[196:199], v181 offset:52224
	ds_read_b128 v[200:203], v181 offset:53248
	ds_read_b128 v[204:207], v181 offset:54272
	ds_read_b128 v[208:211], v181 offset:55296
	ds_read_b128 v[212:215], v181 offset:56320
	global_load_lds_dwordx4 v[176:177], off
	s_add_i32 m0, s44, 0x2000
	s_add_u32 s40, s40, 0x40080
	v_lshl_add_u64 v[176:177], v[216:217], 0, s[22:23]
	s_addc_u32 s41, s41, 0
	s_add_i32 s44, s75, s51
	global_load_lds_dwordx4 v[176:177], off
	s_mov_b32 m0, s44
	v_lshl_add_u64 v[176:177], s[40:41], 0, v[130:131]
	global_load_lds_dwordx4 v[176:177], off
	s_add_i32 m0, s44, 0x2000
	v_lshl_add_u64 v[176:177], s[40:41], 0, v[134:135]
	global_load_lds_dwordx4 v[176:177], off
	s_mov_b32 m0, s64
	v_lshl_add_u64 v[176:177], v[218:219], 0, s[22:23]
	global_load_lds_dwordx4 v[176:177], off
	s_mov_b32 m0, s65
	v_lshl_add_u64 v[176:177], v[220:221], 0, s[22:23]
	global_load_lds_dwordx4 v[176:177], off
	s_waitcnt vmcnt(8) lgkmcnt(0)
	s_barrier
	s_setprio 1
	v_mfma_f32_16x16x32_bf16 v[60:63], v[144:147], v[184:187], v[60:63]
	v_mfma_f32_16x16x32_bf16 v[56:59], v[152:155], v[184:187], v[56:59]
	v_mfma_f32_16x16x32_bf16 v[44:47], v[144:147], v[192:195], v[44:47]
	v_mfma_f32_16x16x32_bf16 v[40:43], v[152:155], v[192:195], v[40:43]
	v_mfma_f32_16x16x32_bf16 v[28:31], v[144:147], v[200:203], v[28:31]
	v_mfma_f32_16x16x32_bf16 v[24:27], v[152:155], v[200:203], v[24:27]
	v_mfma_f32_16x16x32_bf16 v[12:15], v[144:147], v[208:211], v[12:15]
	v_mfma_f32_16x16x32_bf16 v[8:11], v[152:155], v[208:211], v[8:11]
	v_mfma_f32_16x16x32_bf16 v[60:63], v[148:151], v[188:191], v[60:63]
	v_mfma_f32_16x16x32_bf16 v[56:59], v[156:159], v[188:191], v[56:59]
	v_mfma_f32_16x16x32_bf16 v[44:47], v[148:151], v[196:199], v[44:47]
	v_mfma_f32_16x16x32_bf16 v[40:43], v[156:159], v[196:199], v[40:43]
	v_mfma_f32_16x16x32_bf16 v[28:31], v[148:151], v[204:207], v[28:31]
	v_mfma_f32_16x16x32_bf16 v[24:27], v[156:159], v[204:207], v[24:27]
	v_mfma_f32_16x16x32_bf16 v[12:15], v[148:151], v[212:215], v[12:15]
	v_mfma_f32_16x16x32_bf16 v[8:11], v[156:159], v[212:215], v[8:11]
	v_mfma_f32_16x16x32_bf16 v[52:55], v[160:163], v[184:187], v[52:55]
	v_mfma_f32_16x16x32_bf16 v[48:51], v[168:171], v[184:187], v[48:51]
	v_mfma_f32_16x16x32_bf16 v[36:39], v[160:163], v[192:195], v[36:39]
	v_mfma_f32_16x16x32_bf16 v[32:35], v[168:171], v[192:195], v[32:35]
	v_mfma_f32_16x16x32_bf16 v[20:23], v[160:163], v[200:203], v[20:23]
	v_mfma_f32_16x16x32_bf16 v[16:19], v[168:171], v[200:203], v[16:19]
	v_mfma_f32_16x16x32_bf16 v[4:7], v[160:163], v[208:211], v[4:7]
	v_mfma_f32_16x16x32_bf16 v[0:3], v[168:171], v[208:211], v[0:3]
	v_mfma_f32_16x16x32_bf16 v[52:55], v[164:167], v[188:191], v[52:55]
	v_mfma_f32_16x16x32_bf16 v[48:51], v[172:175], v[188:191], v[48:51]
	v_mfma_f32_16x16x32_bf16 v[36:39], v[164:167], v[196:199], v[36:39]
	v_mfma_f32_16x16x32_bf16 v[32:35], v[172:175], v[196:199], v[32:35]
	s_setprio 2
	s_barrier
	v_mfma_f32_16x16x32_bf16 v[20:23], v[164:167], v[204:207], v[20:23]
	v_mfma_f32_16x16x32_bf16 v[16:19], v[172:175], v[204:207], v[16:19]
	v_mfma_f32_16x16x32_bf16 v[4:7], v[164:167], v[212:215], v[4:7]
	v_mfma_f32_16x16x32_bf16 v[0:3], v[172:175], v[212:215], v[0:3]
	s_setprio 0
	s_add_i32 s73, s73, 2
	s_add_u32 s6, s6, 0x100
	s_addc_u32 s7, s7, 0
	s_add_u32 s71, s71, 0x100
	s_addc_u32 s72, s72, 0
	s_cmp_gt_u32 s73, 13
.LBB0_952:
	ds_read_b128 v[144:147], v179
	ds_read_b128 v[148:151], v179 offset:1024
	ds_read_b128 v[152:155], v179 offset:2048
	ds_read_b128 v[156:159], v179 offset:3072
	ds_read_b128 v[160:163], v180
	ds_read_b128 v[164:167], v180 offset:1024
	ds_read_b128 v[168:171], v180 offset:2048
	ds_read_b128 v[172:175], v180 offset:3072
	s_add_u32 s40, s6, 0xfffc0080
	s_addc_u32 s41, s7, -1
	s_cmp_eq_u32 s73, 12
	s_cselect_b32 s45, s27, s41
	s_cselect_b32 s44, s39, s40
	s_cselect_b32 s41, s29, s72
	s_cselect_b32 s40, s43, s71
	v_lshl_add_u64 v[176:177], s[6:7], 0, v[136:137]
	s_add_i32 m0, s54, 0xc000
	ds_read_b128 v[184:187], v181
	ds_read_b128 v[188:191], v181 offset:1024
	ds_read_b128 v[192:195], v181 offset:2048
	ds_read_b128 v[196:199], v181 offset:3072
	ds_read_b128 v[200:203], v181 offset:4096
	ds_read_b128 v[204:207], v181 offset:5120
	ds_read_b128 v[208:211], v181 offset:6144
	ds_read_b128 v[212:215], v181 offset:7168
	global_load_lds_dwordx4 v[176:177], off
	s_add_i32 m0, s54, 0xe000
	v_lshl_add_u64 v[176:177], s[6:7], 0, v[138:139]
	global_load_lds_dwordx4 v[176:177], off
	s_waitcnt vmcnt(8) lgkmcnt(0)
	s_barrier
	s_setprio 1
	v_mfma_f32_16x16x32_bf16 v[124:127], v[144:147], v[184:187], v[124:127]
	v_mfma_f32_16x16x32_bf16 v[120:123], v[152:155], v[184:187], v[120:123]
	v_mfma_f32_16x16x32_bf16 v[108:111], v[144:147], v[192:195], v[108:111]
	v_mfma_f32_16x16x32_bf16 v[104:107], v[152:155], v[192:195], v[104:107]
	v_mfma_f32_16x16x32_bf16 v[92:95], v[144:147], v[200:203], v[92:95]
	v_mfma_f32_16x16x32_bf16 v[88:91], v[152:155], v[200:203], v[88:91]
	v_mfma_f32_16x16x32_bf16 v[76:79], v[144:147], v[208:211], v[76:79]
	v_mfma_f32_16x16x32_bf16 v[72:75], v[152:155], v[208:211], v[72:75]
	v_mfma_f32_16x16x32_bf16 v[124:127], v[148:151], v[188:191], v[124:127]
	v_mfma_f32_16x16x32_bf16 v[120:123], v[156:159], v[188:191], v[120:123]
	v_mfma_f32_16x16x32_bf16 v[108:111], v[148:151], v[196:199], v[108:111]
	v_mfma_f32_16x16x32_bf16 v[104:107], v[156:159], v[196:199], v[104:107]
	v_mfma_f32_16x16x32_bf16 v[92:95], v[148:151], v[204:207], v[92:95]
	v_mfma_f32_16x16x32_bf16 v[88:91], v[156:159], v[204:207], v[88:91]
	v_mfma_f32_16x16x32_bf16 v[76:79], v[148:151], v[212:215], v[76:79]
	v_mfma_f32_16x16x32_bf16 v[72:75], v[156:159], v[212:215], v[72:75]
	v_mfma_f32_16x16x32_bf16 v[116:119], v[160:163], v[184:187], v[116:119]
	v_mfma_f32_16x16x32_bf16 v[112:115], v[168:171], v[184:187], v[112:115]
	v_mfma_f32_16x16x32_bf16 v[100:103], v[160:163], v[192:195], v[100:103]
	v_mfma_f32_16x16x32_bf16 v[96:99], v[168:171], v[192:195], v[96:99]
	v_mfma_f32_16x16x32_bf16 v[84:87], v[160:163], v[200:203], v[84:87]
	v_mfma_f32_16x16x32_bf16 v[80:83], v[168:171], v[200:203], v[80:83]
	v_mfma_f32_16x16x32_bf16 v[68:71], v[160:163], v[208:211], v[68:71]
	v_mfma_f32_16x16x32_bf16 v[64:67], v[168:171], v[208:211], v[64:67]
	v_mfma_f32_16x16x32_bf16 v[116:119], v[164:167], v[188:191], v[116:119]
	v_mfma_f32_16x16x32_bf16 v[112:115], v[172:175], v[188:191], v[112:115]
	v_mfma_f32_16x16x32_bf16 v[100:103], v[164:167], v[196:199], v[100:103]
	v_mfma_f32_16x16x32_bf16 v[96:99], v[172:175], v[196:199], v[96:99]
	s_setprio 2
	s_barrier
	v_mfma_f32_16x16x32_bf16 v[84:87], v[164:167], v[204:207], v[84:87]
	v_mfma_f32_16x16x32_bf16 v[80:83], v[172:175], v[204:207], v[80:83]
	v_mfma_f32_16x16x32_bf16 v[68:71], v[164:167], v[212:215], v[68:71]
	v_mfma_f32_16x16x32_bf16 v[64:67], v[172:175], v[212:215], v[64:67]
	s_setprio 2
	s_add_i32 s74, s69, s51
	v_lshl_add_u64 v[176:177], s[40:41], 0, v[130:131]
	s_mov_b32 m0, s74
	ds_read_b128 v[184:187], v181 offset:16384
	ds_read_b128 v[188:191], v181 offset:17408
	ds_read_b128 v[192:195], v181 offset:18432
	ds_read_b128 v[196:199], v181 offset:19456
	ds_read_b128 v[200:203], v181 offset:20480
	ds_read_b128 v[204:207], v181 offset:21504
	ds_read_b128 v[208:211], v181 offset:22528
	ds_read_b128 v[212:215], v181 offset:23552
	global_load_lds_dwordx4 v[176:177], off
	s_add_i32 m0, s74, 0x2000
	s_add_u32 s74, s40, 0x40000
	v_lshl_add_u64 v[216:217], s[40:41], 0, v[134:135]
	s_addc_u32 s75, s41, 0
	s_add_i32 s76, s70, s51
	global_load_lds_dwordx4 v[216:217], off
	v_lshl_add_u64 v[218:219], s[74:75], 0, v[130:131]
	s_mov_b32 m0, s76
	v_lshl_add_u64 v[220:221], s[44:45], 0, v[132:133]
	global_load_lds_dwordx4 v[218:219], off
	s_add_i32 m0, s76, 0x2000
	v_lshl_add_u64 v[218:219], s[74:75], 0, v[134:135]
	global_load_lds_dwordx4 v[218:219], off
	s_mov_b32 m0, s54
	v_lshl_add_u64 v[218:219], s[44:45], 0, v[128:129]
	global_load_lds_dwordx4 v[218:219], off
	s_mov_b32 m0, s55
	s_nop 0
	global_load_lds_dwordx4 v[220:221], off
	s_waitcnt vmcnt(8) lgkmcnt(0)
	s_barrier
	s_setprio 1
	v_mfma_f32_16x16x32_bf16 v[60:63], v[144:147], v[184:187], v[60:63]
	v_mfma_f32_16x16x32_bf16 v[56:59], v[152:155], v[184:187], v[56:59]
	v_mfma_f32_16x16x32_bf16 v[44:47], v[144:147], v[192:195], v[44:47]
	v_mfma_f32_16x16x32_bf16 v[40:43], v[152:155], v[192:195], v[40:43]
	v_mfma_f32_16x16x32_bf16 v[28:31], v[144:147], v[200:203], v[28:31]
	v_mfma_f32_16x16x32_bf16 v[24:27], v[152:155], v[200:203], v[24:27]
	v_mfma_f32_16x16x32_bf16 v[12:15], v[144:147], v[208:211], v[12:15]
	v_mfma_f32_16x16x32_bf16 v[8:11], v[152:155], v[208:211], v[8:11]
	v_mfma_f32_16x16x32_bf16 v[60:63], v[148:151], v[188:191], v[60:63]
	v_mfma_f32_16x16x32_bf16 v[56:59], v[156:159], v[188:191], v[56:59]
	v_mfma_f32_16x16x32_bf16 v[44:47], v[148:151], v[196:199], v[44:47]
	v_mfma_f32_16x16x32_bf16 v[40:43], v[156:159], v[196:199], v[40:43]
	v_mfma_f32_16x16x32_bf16 v[28:31], v[148:151], v[204:207], v[28:31]
	v_mfma_f32_16x16x32_bf16 v[24:27], v[156:159], v[204:207], v[24:27]
	v_mfma_f32_16x16x32_bf16 v[12:15], v[148:151], v[212:215], v[12:15]
	v_mfma_f32_16x16x32_bf16 v[8:11], v[156:159], v[212:215], v[8:11]
	v_mfma_f32_16x16x32_bf16 v[52:55], v[160:163], v[184:187], v[52:55]
	v_mfma_f32_16x16x32_bf16 v[48:51], v[168:171], v[184:187], v[48:51]
	v_mfma_f32_16x16x32_bf16 v[36:39], v[160:163], v[192:195], v[36:39]
	v_mfma_f32_16x16x32_bf16 v[32:35], v[168:171], v[192:195], v[32:35]
	v_mfma_f32_16x16x32_bf16 v[20:23], v[160:163], v[200:203], v[20:23]
	v_mfma_f32_16x16x32_bf16 v[16:19], v[168:171], v[200:203], v[16:19]
	v_mfma_f32_16x16x32_bf16 v[4:7], v[160:163], v[208:211], v[4:7]
	v_mfma_f32_16x16x32_bf16 v[0:3], v[168:171], v[208:211], v[0:3]
	v_mfma_f32_16x16x32_bf16 v[52:55], v[164:167], v[188:191], v[52:55]
	v_mfma_f32_16x16x32_bf16 v[48:51], v[172:175], v[188:191], v[48:51]
	v_mfma_f32_16x16x32_bf16 v[36:39], v[164:167], v[196:199], v[36:39]
	v_mfma_f32_16x16x32_bf16 v[32:35], v[172:175], v[196:199], v[32:35]
	s_setprio 2
	s_barrier
	v_mfma_f32_16x16x32_bf16 v[20:23], v[164:167], v[204:207], v[20:23]
	v_mfma_f32_16x16x32_bf16 v[16:19], v[172:175], v[204:207], v[16:19]
	v_mfma_f32_16x16x32_bf16 v[4:7], v[164:167], v[212:215], v[4:7]
	v_mfma_f32_16x16x32_bf16 v[0:3], v[172:175], v[212:215], v[0:3]
	s_setprio 0
	s_add_i32 s74, 0, 0x18000
	s_add_i32 s75, 0, 0x1c000
	v_add_u32_e32 v156, s74, v178
	v_add_u32_e32 v172, s75, v178
	ds_read_b128 v[144:147], v156
	ds_read_b128 v[148:151], v156 offset:1024
	ds_read_b128 v[152:155], v156 offset:2048
	ds_read_b128 v[156:159], v156 offset:3072
	ds_read_b128 v[160:163], v172
	ds_read_b128 v[164:167], v172 offset:1024
	ds_read_b128 v[168:171], v172 offset:2048
	ds_read_b128 v[172:175], v172 offset:3072
	s_add_u32 s44, s44, 0x40000
	s_addc_u32 s45, s45, 0
	s_mov_b32 m0, s56
	v_lshl_add_u64 v[222:223], s[44:45], 0, v[128:129]
	ds_read_b128 v[184:187], v181 offset:32768
	ds_read_b128 v[188:191], v181 offset:33792
	ds_read_b128 v[192:195], v181 offset:34816
	ds_read_b128 v[196:199], v181 offset:35840
	ds_read_b128 v[200:203], v181 offset:36864
	ds_read_b128 v[204:207], v181 offset:37888
	ds_read_b128 v[208:211], v181 offset:38912
	ds_read_b128 v[212:215], v181 offset:39936
	global_load_lds_dwordx4 v[222:223], off
	s_mov_b32 m0, s57
	v_lshl_add_u64 v[222:223], s[44:45], 0, v[132:133]
	global_load_lds_dwordx4 v[222:223], off
	s_waitcnt vmcnt(8) lgkmcnt(0)
	s_barrier
	s_setprio 1
	v_mfma_f32_16x16x32_bf16 v[124:127], v[144:147], v[184:187], v[124:127]
	v_mfma_f32_16x16x32_bf16 v[120:123], v[152:155], v[184:187], v[120:123]
	v_mfma_f32_16x16x32_bf16 v[108:111], v[144:147], v[192:195], v[108:111]
	v_mfma_f32_16x16x32_bf16 v[104:107], v[152:155], v[192:195], v[104:107]
	v_mfma_f32_16x16x32_bf16 v[92:95], v[144:147], v[200:203], v[92:95]
	v_mfma_f32_16x16x32_bf16 v[88:91], v[152:155], v[200:203], v[88:91]
	v_mfma_f32_16x16x32_bf16 v[76:79], v[144:147], v[208:211], v[76:79]
	v_mfma_f32_16x16x32_bf16 v[72:75], v[152:155], v[208:211], v[72:75]
	v_mfma_f32_16x16x32_bf16 v[124:127], v[148:151], v[188:191], v[124:127]
	v_mfma_f32_16x16x32_bf16 v[120:123], v[156:159], v[188:191], v[120:123]
	v_mfma_f32_16x16x32_bf16 v[108:111], v[148:151], v[196:199], v[108:111]
	v_mfma_f32_16x16x32_bf16 v[104:107], v[156:159], v[196:199], v[104:107]
	v_mfma_f32_16x16x32_bf16 v[92:95], v[148:151], v[204:207], v[92:95]
	v_mfma_f32_16x16x32_bf16 v[88:91], v[156:159], v[204:207], v[88:91]
	v_mfma_f32_16x16x32_bf16 v[76:79], v[148:151], v[212:215], v[76:79]
	v_mfma_f32_16x16x32_bf16 v[72:75], v[156:159], v[212:215], v[72:75]
	v_mfma_f32_16x16x32_bf16 v[116:119], v[160:163], v[184:187], v[116:119]
	v_mfma_f32_16x16x32_bf16 v[112:115], v[168:171], v[184:187], v[112:115]
	v_mfma_f32_16x16x32_bf16 v[100:103], v[160:163], v[192:195], v[100:103]
	v_mfma_f32_16x16x32_bf16 v[96:99], v[168:171], v[192:195], v[96:99]
	v_mfma_f32_16x16x32_bf16 v[84:87], v[160:163], v[200:203], v[84:87]
	v_mfma_f32_16x16x32_bf16 v[80:83], v[168:171], v[200:203], v[80:83]
	v_mfma_f32_16x16x32_bf16 v[68:71], v[160:163], v[208:211], v[68:71]
	v_mfma_f32_16x16x32_bf16 v[64:67], v[168:171], v[208:211], v[64:67]
	v_mfma_f32_16x16x32_bf16 v[116:119], v[164:167], v[188:191], v[116:119]
	v_mfma_f32_16x16x32_bf16 v[112:115], v[172:175], v[188:191], v[112:115]
	v_mfma_f32_16x16x32_bf16 v[100:103], v[164:167], v[196:199], v[100:103]
	v_mfma_f32_16x16x32_bf16 v[96:99], v[172:175], v[196:199], v[96:99]
	s_setprio 2
	s_barrier
	v_mfma_f32_16x16x32_bf16 v[84:87], v[164:167], v[204:207], v[84:87]
	v_mfma_f32_16x16x32_bf16 v[80:83], v[172:175], v[204:207], v[80:83]
	v_mfma_f32_16x16x32_bf16 v[68:71], v[164:167], v[212:215], v[68:71]
	v_mfma_f32_16x16x32_bf16 v[64:67], v[172:175], v[212:215], v[64:67]
	s_setprio 2
	s_add_i32 s44, s74, s51
	v_lshl_add_u64 v[176:177], v[176:177], 0, s[22:23]
	s_mov_b32 m0, s44
	ds_read_b128 v[184:187], v181 offset:49152
	ds_read_b128 v[188:191], v181 offset:50176
	ds_read_b128 v[192:195], v181 offset:51200
	ds_read_b128 v[196:199], v181 offset:52224
	ds_read_b128 v[200:203], v181 offset:53248
	ds_read_b128 v[204:207], v181 offset:54272
	ds_read_b128 v[208:211], v181 offset:55296
	ds_read_b128 v[212:215], v181 offset:56320
	global_load_lds_dwordx4 v[176:177], off
	s_add_i32 m0, s44, 0x2000
	s_add_u32 s40, s40, 0x40080
	v_lshl_add_u64 v[176:177], v[216:217], 0, s[22:23]
	s_addc_u32 s41, s41, 0
	s_add_i32 s44, s75, s51
	global_load_lds_dwordx4 v[176:177], off
	s_mov_b32 m0, s44
	v_lshl_add_u64 v[176:177], s[40:41], 0, v[130:131]
	global_load_lds_dwordx4 v[176:177], off
	s_add_i32 m0, s44, 0x2000
	v_lshl_add_u64 v[176:177], s[40:41], 0, v[134:135]
	global_load_lds_dwordx4 v[176:177], off
	s_mov_b32 m0, s64
	v_lshl_add_u64 v[176:177], v[218:219], 0, s[22:23]
	global_load_lds_dwordx4 v[176:177], off
	s_mov_b32 m0, s65
	v_lshl_add_u64 v[176:177], v[220:221], 0, s[22:23]
	global_load_lds_dwordx4 v[176:177], off
	s_waitcnt vmcnt(8) lgkmcnt(0)
	s_barrier
	s_setprio 1
	v_mfma_f32_16x16x32_bf16 v[60:63], v[144:147], v[184:187], v[60:63]
	v_mfma_f32_16x16x32_bf16 v[56:59], v[152:155], v[184:187], v[56:59]
	v_mfma_f32_16x16x32_bf16 v[44:47], v[144:147], v[192:195], v[44:47]
	v_mfma_f32_16x16x32_bf16 v[40:43], v[152:155], v[192:195], v[40:43]
	v_mfma_f32_16x16x32_bf16 v[28:31], v[144:147], v[200:203], v[28:31]
	v_mfma_f32_16x16x32_bf16 v[24:27], v[152:155], v[200:203], v[24:27]
	v_mfma_f32_16x16x32_bf16 v[12:15], v[144:147], v[208:211], v[12:15]
	v_mfma_f32_16x16x32_bf16 v[8:11], v[152:155], v[208:211], v[8:11]
	v_mfma_f32_16x16x32_bf16 v[60:63], v[148:151], v[188:191], v[60:63]
	v_mfma_f32_16x16x32_bf16 v[56:59], v[156:159], v[188:191], v[56:59]
	v_mfma_f32_16x16x32_bf16 v[44:47], v[148:151], v[196:199], v[44:47]
	v_mfma_f32_16x16x32_bf16 v[40:43], v[156:159], v[196:199], v[40:43]
	v_mfma_f32_16x16x32_bf16 v[28:31], v[148:151], v[204:207], v[28:31]
	v_mfma_f32_16x16x32_bf16 v[24:27], v[156:159], v[204:207], v[24:27]
	v_mfma_f32_16x16x32_bf16 v[12:15], v[148:151], v[212:215], v[12:15]
	v_mfma_f32_16x16x32_bf16 v[8:11], v[156:159], v[212:215], v[8:11]
	v_mfma_f32_16x16x32_bf16 v[52:55], v[160:163], v[184:187], v[52:55]
	v_mfma_f32_16x16x32_bf16 v[48:51], v[168:171], v[184:187], v[48:51]
	v_mfma_f32_16x16x32_bf16 v[36:39], v[160:163], v[192:195], v[36:39]
	v_mfma_f32_16x16x32_bf16 v[32:35], v[168:171], v[192:195], v[32:35]
	v_mfma_f32_16x16x32_bf16 v[20:23], v[160:163], v[200:203], v[20:23]
	v_mfma_f32_16x16x32_bf16 v[16:19], v[168:171], v[200:203], v[16:19]
	v_mfma_f32_16x16x32_bf16 v[4:7], v[160:163], v[208:211], v[4:7]
	v_mfma_f32_16x16x32_bf16 v[0:3], v[168:171], v[208:211], v[0:3]
	v_mfma_f32_16x16x32_bf16 v[52:55], v[164:167], v[188:191], v[52:55]
	v_mfma_f32_16x16x32_bf16 v[48:51], v[172:175], v[188:191], v[48:51]
	v_mfma_f32_16x16x32_bf16 v[36:39], v[164:167], v[196:199], v[36:39]
	v_mfma_f32_16x16x32_bf16 v[32:35], v[172:175], v[196:199], v[32:35]
	s_setprio 2
	s_barrier
	v_mfma_f32_16x16x32_bf16 v[20:23], v[164:167], v[204:207], v[20:23]
	v_mfma_f32_16x16x32_bf16 v[16:19], v[172:175], v[204:207], v[16:19]
	v_mfma_f32_16x16x32_bf16 v[4:7], v[164:167], v[212:215], v[4:7]
	v_mfma_f32_16x16x32_bf16 v[0:3], v[172:175], v[212:215], v[0:3]
	s_setprio 0
	s_add_i32 s73, s73, 2
	s_add_u32 s6, s6, 0x100
	s_addc_u32 s7, s7, 0
	s_add_u32 s71, s71, 0x100
	s_addc_u32 s72, s72, 0
	s_cmp_gt_u32 s73, 13
	s_cbranch_scc0 .LBB0_952

.LBB0_1073:
	s_mov_b32 s26, s23
	s_and_b32 s24, s22, 0x80
	s_add_i32 s23, s23, 1
	s_cmp_lt_i32 s23, s20
	s_cselect_b32 s26, s23, s26
	s_lshl_b32 s26, s26, 1
	s_add_i32 s26, s26, s12
	s_ashr_i32 s27, s26, 31
	s_mul_i32 s25, s24, 0x90
	s_mulk_i32 s24, 0xc0
	s_lshl_b64 s[28:29], s[26:27], 17
	s_or_b32 s26, s26, 1
	v_add_u32_e32 v32, s25, v132
	v_add_u32_e32 v33, s24, v134
	s_ashr_i32 s27, s26, 31
	s_waitcnt vmcnt(0)
	ds_write_b128 v32, v[124:127]
	ds_write_b128 v33, v[120:123] offset:36864
	ds_write_b128 v32, v[116:119] offset:9216
	ds_write_b128 v33, v[112:115] offset:49152
	v_lshl_add_u64 v[32:33], v[128:129], 0, s[28:29]
	s_lshl_b64 s[26:27], s[26:27], 17
	v_lshl_add_u64 v[34:35], v[130:131], 0, s[28:29]
	global_load_dwordx4 v[124:127], v[32:33], off
	global_load_dwordx4 v[120:123], v[34:35], off
	v_lshl_add_u64 v[32:33], v[128:129], 0, s[26:27]
	v_lshl_add_u64 v[34:35], v[130:131], 0, s[26:27]
	global_load_dwordx4 v[116:119], v[32:33], off
	global_load_dwordx4 v[112:115], v[34:35], off
	s_cmp_gt_u32 s13, 9
	s_waitcnt lgkmcnt(0)
	s_barrier
	s_cbranch_scc1 .LBB0_1072
	s_add_i32 s26, s21, s22
	s_cmp_lg_u32 s13, 9
	s_cselect_b32 s27, s26, 0xfffffd80
	v_add_u32_e32 v152, s25, v174
	v_lshl_add_u32 v44, s27, 2, v133
	ds_read_b128 v[32:35], v152
	ds_read_b128 v[64:67], v44 offset:2816
	ds_read_b128 v[68:71], v44 offset:2848
	ds_read_b128 v[72:75], v44 offset:2880
	ds_read_b128 v[76:79], v44 offset:2912
	ds_read_b128 v[36:39], v152 offset:4608
	ds_read_b128 v[40:43], v152 offset:32
	s_waitcnt lgkmcnt(2)
	v_mfma_f32_32x32x16_bf16 v[64:79], v[32:35], v[96:99], v[64:79]
	ds_read_b128 v[80:83], v44 offset:2944
	ds_read_b128 v[84:87], v44 offset:2976
	ds_read_b128 v[88:91], v44 offset:3008
	ds_read_b128 v[92:95], v44 offset:3040
	ds_read_b128 v[32:35], v152 offset:4640
	s_add_i32 s26, s26, 64
	s_cmp_lg_u32 s13, 0
	s_cselect_b32 s25, s26, 0xfffffd80
	v_lshl_add_u32 v60, s25, 2, v133
	v_add_u32_e32 v179, s24, v135
	s_waitcnt lgkmcnt(1)
	v_mfma_f32_32x32x16_bf16 v[80:95], v[36:39], v[96:99], v[80:95]
	v_mfma_f32_32x32x16_bf16 v[64:79], v[40:43], v[100:103], v[64:79]
	s_waitcnt lgkmcnt(0)
	v_mfma_f32_32x32x16_bf16 v[80:95], v[32:35], v[100:103], v[80:95]
	ds_read_b128 v[32:35], v152 offset:64
	ds_read_b128 v[36:39], v152 offset:96
	s_waitcnt lgkmcnt(1)
	v_mfma_f32_32x32x16_bf16 v[64:79], v[32:35], v[104:107], v[64:79]
	ds_read_b128 v[32:35], v152 offset:4672
	ds_read_b128 v[48:51], v152 offset:4704
	s_waitcnt lgkmcnt(1)
	v_mfma_f32_32x32x16_bf16 v[80:95], v[32:35], v[104:107], v[80:95]
	v_mfma_f32_32x32x16_bf16 v[64:79], v[36:39], v[108:111], v[64:79]
	ds_read_b128 v[32:35], v60 offset:2816
	ds_read_b128 v[36:39], v60 offset:2848
	ds_read_b128 v[40:43], v60 offset:2880
	ds_read_b128 v[44:47], v60 offset:2912
	ds_read_b128 v[140:143], v152 offset:9216
	s_nop 6
	v_exp_f32_e32 v168, v64
	s_waitcnt lgkmcnt(5)
	v_mfma_f32_32x32x16_bf16 v[80:95], v[48:51], v[108:111], v[80:95]
	ds_read_b128 v[48:51], v60 offset:2944
	ds_read_b128 v[52:55], v60 offset:2976
	ds_read_b128 v[56:59], v60 offset:3008
	ds_read_b128 v[60:63], v60 offset:3040
	ds_read_b128 v[144:147], v152 offset:9248
	ds_read_b128 v[148:151], v152 offset:13824
	ds_read_b128 v[180:183], v152 offset:13856
	ds_read_b128 v[184:187], v152 offset:9280
	ds_read_b128 v[188:191], v152 offset:9312
	ds_read_b128 v[192:195], v152 offset:13888
	ds_read_b128 v[196:199], v152 offset:13920
	v_exp_f32_e32 v156, v65
	v_exp_f32_e32 v158, v66
	v_exp_f32_e32 v162, v67
	v_exp_f32_e32 v216, v68
	v_exp_f32_e32 v76, v76
	s_waitcnt lgkmcnt(5)
	v_mfma_f32_32x32x16_bf16 v[48:63], v[148:151], v[96:99], v[48:63]
	v_exp_f32_e32 v148, v71
	v_exp_f32_e32 v170, v80
	v_exp_f32_e32 v164, v82
	v_exp_f32_e32 v150, v86
	v_exp_f32_e32 v80, v72
	v_exp_f32_e32 v82, v73
	v_exp_f32_e32 v86, v74
	s_waitcnt lgkmcnt(4)
	v_mfma_f32_32x32x16_bf16 v[48:63], v[180:183], v[100:103], v[48:63]
	v_cvt_pk_bf16_f32 v180, v168, v156
	v_cvt_pk_bf16_f32 v181, v158, v162
	v_exp_f32_e32 v64, v77
	v_exp_f32_e32 v66, v78
	v_exp_f32_e32 v160, v81
	v_exp_f32_e32 v166, v83
	v_exp_f32_e32 v172, v84
	v_mfma_f32_32x32x16_bf16 v[32:47], v[140:143], v[96:99], v[32:47]
	v_exp_f32_e32 v140, v69
	v_exp_f32_e32 v142, v70
	v_exp_f32_e32 v70, v79
	v_exp_f32_e32 v154, v87
	v_cvt_pk_bf16_f32 v182, v216, v140
	v_cvt_pk_bf16_f32 v183, v142, v148
	v_exp_f32_e32 v84, v88
	s_waitcnt lgkmcnt(1)
	v_mfma_f32_32x32x16_bf16 v[48:63], v[192:195], v[104:107], v[48:63]
	ds_read_b64_tr_b16 v[192:193], v179 offset:36864
	ds_read_b64_tr_b16 v[194:195], v179 offset:38400
	ds_read_b64_tr_b16 v[202:203], v179 offset:38464
	ds_read_b64_tr_b16 v[200:201], v179 offset:36928
	v_exp_f32_e32 v88, v89
	v_exp_f32_e32 v152, v91
	v_exp_f32_e32 v92, v92
	v_exp_f32_e32 v68, v93
	v_exp_f32_e32 v72, v94
	v_mfma_f32_32x32x16_bf16 v[32:47], v[144:147], v[100:103], v[32:47]
	v_exp_f32_e32 v146, v90
	v_exp_f32_e32 v90, v75
	v_exp_f32_e32 v144, v85
	v_exp_f32_e32 v74, v95
	s_waitcnt lgkmcnt(0)
	v_mfma_f32_32x32x16_bf16 v[16:31], v[200:203], v[180:183], v[16:31]
	v_mfma_f32_32x32x16_bf16 v[0:15], v[192:195], v[180:183], v[0:15]
	ds_read_b64_tr_b16 v[192:193], v179 offset:39936
	ds_read_b64_tr_b16 v[194:195], v179 offset:41472
	ds_read_b64_tr_b16 v[206:207], v179 offset:41536
	ds_read_b64_tr_b16 v[204:205], v179 offset:40000
	ds_read_b64_tr_b16 v[208:209], v179 offset:43008
	ds_read_b64_tr_b16 v[210:211], v179 offset:44544
	ds_read_b64_tr_b16 v[214:215], v179 offset:44608
	ds_read_b64_tr_b16 v[212:213], v179 offset:43072
	ds_read_b64_tr_b16 v[180:181], v179 offset:46080
	ds_read_b64_tr_b16 v[182:183], v179 offset:47616
	ds_read_b64_tr_b16 v[202:203], v179 offset:47680
	ds_read_b64_tr_b16 v[200:201], v179 offset:46144
	v_mfma_f32_32x32x16_bf16 v[32:47], v[184:187], v[104:107], v[32:47]
	v_cvt_pk_bf16_f32 v184, v80, v82
	v_cvt_pk_bf16_f32 v185, v86, v90
	v_cvt_pk_bf16_f32 v186, v76, v64
	v_cvt_pk_bf16_f32 v187, v66, v70
	s_waitcnt lgkmcnt(8)
	s_nop 0
	v_mfma_f32_32x32x16_bf16 v[16:31], v[204:207], v[184:187], v[16:31]
	v_mfma_f32_32x32x16_bf16 v[0:15], v[192:195], v[184:187], v[0:15]
	v_mfma_f32_32x32x16_bf16 v[32:47], v[188:191], v[108:111], v[32:47]
	v_cvt_pk_bf16_f32 v188, v170, v160
	v_cvt_pk_bf16_f32 v189, v164, v166
	v_cvt_pk_bf16_f32 v190, v172, v144
	v_cvt_pk_bf16_f32 v191, v150, v154
	s_waitcnt lgkmcnt(4)
	s_nop 0
	v_mfma_f32_32x32x16_bf16 v[16:31], v[212:215], v[188:191], v[16:31]
	s_nop 4
	v_exp_f32_e32 v169, v32
	v_exp_f32_e32 v157, v33
	v_exp_f32_e32 v159, v34
	v_exp_f32_e32 v217, v36
	v_exp_f32_e32 v163, v35
	v_exp_f32_e32 v141, v37
	v_exp_f32_e32 v143, v38
	v_mfma_f32_32x32x16_bf16 v[0:15], v[208:211], v[188:191], v[0:15]
	v_exp_f32_e32 v149, v39
	v_exp_f32_e32 v81, v40
	v_exp_f32_e32 v83, v41
	v_exp_f32_e32 v87, v42
	v_exp_f32_e32 v91, v43
	ds_read_b64_tr_b16 v[40:41], v179 offset:49152
	ds_read_b64_tr_b16 v[42:43], v179 offset:50688
	v_cvt_pk_bf16_f32 v32, v169, v157
	v_mfma_f32_32x32x16_bf16 v[48:63], v[196:199], v[108:111], v[48:63]
	v_cvt_pk_bf16_f32 v196, v84, v88
	v_cvt_pk_bf16_f32 v197, v146, v152
	v_cvt_pk_bf16_f32 v198, v92, v68
	v_cvt_pk_bf16_f32 v199, v72, v74
	v_cvt_pk_bf16_f32 v33, v159, v163
	v_cvt_pk_bf16_f32 v34, v217, v141
	v_cvt_pk_bf16_f32 v35, v143, v149
	s_waitcnt lgkmcnt(2)
	v_mfma_f32_32x32x16_bf16 v[16:31], v[200:203], v[196:199], v[16:31]
	s_nop 2
	v_exp_f32_e32 v171, v48
	v_exp_f32_e32 v161, v49
	v_exp_f32_e32 v165, v50
	v_exp_f32_e32 v167, v51
	ds_read_b64_tr_b16 v[50:51], v179 offset:50752
	ds_read_b64_tr_b16 v[48:49], v179 offset:49216
	v_exp_f32_e32 v85, v56
	v_exp_f32_e32 v89, v57
	v_mfma_f32_32x32x16_bf16 v[0:15], v[180:183], v[196:199], v[0:15]
	v_add_f32_e64 v56, v168, v170
	v_add_f32_e64 v57, v169, v171
	v_exp_f32_e32 v173, v52
	v_exp_f32_e32 v145, v53
	v_exp_f32_e32 v151, v54
	v_exp_f32_e32 v155, v55
	v_exp_f32_e32 v77, v44
	v_exp_f32_e32 v65, v45
	s_waitcnt lgkmcnt(0)
	v_mfma_f32_32x32x16_bf16 v[16:31], v[48:51], v[32:35], v[16:31]
	v_exp_f32_e32 v67, v46
	v_exp_f32_e32 v71, v47
	ds_read_b64_tr_b16 v[52:53], v179 offset:52224
	ds_read_b64_tr_b16 v[54:55], v179 offset:53760
	v_cvt_pk_bf16_f32 v36, v81, v83
	v_cvt_pk_bf16_f32 v37, v87, v91
	v_cvt_pk_bf16_f32 v38, v77, v65
	v_cvt_pk_bf16_f32 v39, v67, v71
	v_mfma_f32_32x32x16_bf16 v[0:15], v[40:43], v[32:35], v[0:15]
	v_add_f32_e64 v32, v156, v160
	v_add_f32_e64 v33, v157, v161
	v_add_f32_e32 v56, v32, v56
	v_add_f32_e32 v57, v33, v57
	v_add_f32_e64 v48, v158, v164
	v_add_f32_e64 v49, v159, v165
	ds_read_b64_tr_b16 v[34:35], v179 offset:53824
	ds_read_b64_tr_b16 v[32:33], v179 offset:52288
	v_add_f32_e32 v50, v162, v166
	v_add_f32_e32 v51, v163, v167
	v_add_f32_e32 v48, v48, v56
	v_add_f32_e32 v49, v49, v57
	s_waitcnt lgkmcnt(0)
	v_mfma_f32_32x32x16_bf16 v[16:31], v[32:35], v[36:39], v[16:31]
	v_add_f32_e64 v78, v216, v172
	v_add_f32_e64 v79, v217, v173
	v_exp_f32_e32 v147, v58
	v_cvt_pk_bf16_f32 v44, v171, v161
	v_cvt_pk_bf16_f32 v45, v165, v167
	v_cvt_pk_bf16_f32 v46, v173, v145
	v_cvt_pk_bf16_f32 v47, v151, v155
	v_add_f32_e32 v56, v142, v150
	v_add_f32_e32 v57, v143, v151
	v_mfma_f32_32x32x16_bf16 v[0:15], v[52:55], v[36:39], v[0:15]
	v_add_f32_e64 v52, v50, v48
	v_add_f32_e64 v53, v51, v49
	ds_read_b64_tr_b16 v[48:49], v179 offset:55296
	ds_read_b64_tr_b16 v[50:51], v179 offset:56832
	ds_read_b64_tr_b16 v[34:35], v179 offset:56896
	ds_read_b64_tr_b16 v[32:33], v179 offset:55360
	v_add_f32_e32 v54, v140, v144
	v_add_f32_e32 v55, v141, v145
	v_add_f32_e32 v36, v78, v52
	v_add_f32_e32 v37, v79, v53
	v_exp_f32_e32 v153, v59
	v_add_f32_e32 v52, v54, v36
	v_add_f32_e32 v53, v55, v37
	v_add_f32_e32 v58, v148, v154
	v_add_f32_e32 v59, v149, v155
	s_waitcnt lgkmcnt(0)
	v_mfma_f32_32x32x16_bf16 v[16:31], v[32:35], v[44:47], v[16:31]
	v_add_f32_e64 v32, v56, v52
	v_add_f32_e64 v33, v57, v53
	v_exp_f32_e32 v93, v60
	v_exp_f32_e32 v69, v61
	v_add_f32_e32 v60, v80, v84
	v_add_f32_e32 v61, v81, v85
	v_add_f32_e32 v32, v58, v32
	v_add_f32_e32 v33, v59, v33
	v_exp_f32_e32 v73, v62
	v_exp_f32_e32 v75, v63
	v_mfma_f32_32x32x16_bf16 v[0:15], v[48:51], v[44:47], v[0:15]
	v_add_f32_e64 v62, v82, v88
	v_add_f32_e64 v63, v83, v89
	v_add_f32_e64 v32, v60, v32
	v_add_f32_e64 v33, v61, v33
	v_add_f32_e64 v80, v86, v146
	v_add_f32_e64 v81, v87, v147
	v_add_f32_e32 v32, v62, v32
	v_add_f32_e32 v33, v63, v33
	ds_read_b64_tr_b16 v[36:37], v179 offset:58368
	ds_read_b64_tr_b16 v[38:39], v179 offset:59904
	v_add_f32_e32 v44, v80, v32
	v_add_f32_e32 v45, v81, v33
	ds_read_b64_tr_b16 v[34:35], v179 offset:59968
	ds_read_b64_tr_b16 v[32:33], v179 offset:58432
	v_cvt_pk_bf16_f32 v40, v85, v89
	v_cvt_pk_bf16_f32 v41, v147, v153
	v_cvt_pk_bf16_f32 v42, v93, v69
	v_cvt_pk_bf16_f32 v43, v73, v75
	v_add_f32_e32 v82, v90, v152
	v_add_f32_e32 v83, v91, v153
	v_add_f32_e32 v76, v76, v92
	v_add_f32_e32 v77, v77, v93
	s_waitcnt lgkmcnt(2)
	v_mfma_f32_32x32x16_bf16 v[0:15], v[36:39], v[40:43], v[0:15]
	v_add_f32_e64 v36, v82, v44
	v_add_f32_e64 v37, v83, v45
	v_add_f32_e64 v48, v64, v68
	v_add_f32_e64 v49, v65, v69
	v_add_f32_e64 v36, v76, v36
	v_add_f32_e64 v37, v77, v37
	v_add_f32_e32 v50, v66, v72
	v_add_f32_e32 v51, v67, v73
	v_add_f32_e32 v36, v48, v36
	v_add_f32_e32 v37, v49, v37
	v_add_f32_e32 v64, v70, v74
	v_add_f32_e32 v65, v71, v75
	v_add_f32_e32 v36, v50, v36
	v_add_f32_e32 v37, v51, v37
	s_waitcnt lgkmcnt(0)
	v_mfma_f32_32x32x16_bf16 v[16:31], v[32:35], v[40:43], v[16:31]
	v_add_f32_e64 v36, v64, v36
	v_add_f32_e64 v37, v65, v37
	v_add_f32_e32 v36, v178, v36
	v_add_f32_e32 v178, v36, v37
	s_branch .LBB0_1072

.LBB0_1145:
	s_ashr_i32 s23, s22, 31
	s_lshl_b64 s[26:27], s[22:23], 19
	s_add_u32 s26, s45, s26
	s_addc_u32 s27, s46, s27
	s_and_b64 s[28:29], s[4:5], exec
	s_cselect_b32 s23, s27, s39
	s_cselect_b32 s31, s26, s38
	s_ashr_i32 s25, s24, 31
	s_lshl_b64 s[28:29], s[24:25], 19
	s_add_u32 s28, s47, s28
	s_addc_u32 s29, s48, s29
	s_and_b64 s[42:43], s[4:5], exec
	s_cselect_b32 s25, s29, s41
	s_cselect_b32 s37, s28, s40
	s_add_u32 s38, s38, 0x40080
	s_addc_u32 s39, s39, 0
	s_add_u32 s64, s40, 0x100
	s_addc_u32 s65, s41, 0
	s_mov_b32 s66, -2
	ds_read_b128 v[120:123], v233
	ds_read_b128 v[132:135], v233 offset:1024
	ds_read_b128 v[136:139], v233 offset:2048
	ds_read_b128 v[140:143], v233 offset:3072
	ds_read_b128 v[144:147], v234
	ds_read_b128 v[148:151], v234 offset:1024
	ds_read_b128 v[152:155], v234 offset:2048
	ds_read_b128 v[156:159], v234 offset:3072
	s_add_u32 s40, s38, 0xfffc0080
	s_addc_u32 s41, s39, -1
	s_cmp_eq_u32 s66, 12
	s_cselect_b32 s43, s23, s41
	s_cselect_b32 s42, s31, s40
	s_cselect_b32 s41, s25, s65
	s_cselect_b32 s40, s37, s64
	v_lshl_add_u64 v[208:209], s[38:39], 0, v[192:193]
	s_add_i32 m0, s50, 0xc000
	ds_read_b128 v[160:163], v235
	ds_read_b128 v[164:167], v235 offset:1024
	ds_read_b128 v[168:171], v235 offset:2048
	ds_read_b128 v[172:175], v235 offset:3072
	ds_read_b128 v[176:179], v235 offset:4096
	ds_read_b128 v[180:183], v235 offset:5120
	ds_read_b128 v[200:203], v235 offset:6144
	ds_read_b128 v[204:207], v235 offset:7168
	global_load_lds_dwordx4 v[208:209], off
	s_add_i32 m0, s50, 0xe000
	v_lshl_add_u64 v[208:209], s[38:39], 0, v[194:195]
	global_load_lds_dwordx4 v[208:209], off
	s_waitcnt vmcnt(8) lgkmcnt(0)
	s_barrier
	s_setprio 1
	v_mfma_f32_16x16x32_bf16 v[128:131], v[120:123], v[160:163], 0
	v_mfma_f32_16x16x32_bf16 v[124:127], v[136:139], v[160:163], 0
	v_mfma_f32_16x16x32_bf16 v[108:111], v[120:123], v[168:171], 0
	v_mfma_f32_16x16x32_bf16 v[104:107], v[136:139], v[168:171], 0
	v_mfma_f32_16x16x32_bf16 v[92:95], v[120:123], v[176:179], 0
	v_mfma_f32_16x16x32_bf16 v[88:91], v[136:139], v[176:179], 0
	v_mfma_f32_16x16x32_bf16 v[76:79], v[120:123], v[200:203], 0
	v_mfma_f32_16x16x32_bf16 v[72:75], v[136:139], v[200:203], 0
	v_mfma_f32_16x16x32_bf16 v[128:131], v[132:135], v[164:167], v[128:131]
	v_mfma_f32_16x16x32_bf16 v[124:127], v[140:143], v[164:167], v[124:127]
	v_mfma_f32_16x16x32_bf16 v[108:111], v[132:135], v[172:175], v[108:111]
	v_mfma_f32_16x16x32_bf16 v[104:107], v[140:143], v[172:175], v[104:107]
	v_mfma_f32_16x16x32_bf16 v[92:95], v[132:135], v[180:183], v[92:95]
	v_mfma_f32_16x16x32_bf16 v[88:91], v[140:143], v[180:183], v[88:91]
	v_mfma_f32_16x16x32_bf16 v[76:79], v[132:135], v[204:207], v[76:79]
	v_mfma_f32_16x16x32_bf16 v[72:75], v[140:143], v[204:207], v[72:75]
	v_mfma_f32_16x16x32_bf16 v[116:119], v[144:147], v[160:163], 0
	v_mfma_f32_16x16x32_bf16 v[112:115], v[152:155], v[160:163], 0
	v_mfma_f32_16x16x32_bf16 v[100:103], v[144:147], v[168:171], 0
	v_mfma_f32_16x16x32_bf16 v[96:99], v[152:155], v[168:171], 0
	v_mfma_f32_16x16x32_bf16 v[84:87], v[144:147], v[176:179], 0
	v_mfma_f32_16x16x32_bf16 v[80:83], v[152:155], v[176:179], 0
	v_mfma_f32_16x16x32_bf16 v[68:71], v[144:147], v[200:203], 0
	v_mfma_f32_16x16x32_bf16 v[64:67], v[152:155], v[200:203], 0
	v_mfma_f32_16x16x32_bf16 v[116:119], v[148:151], v[164:167], v[116:119]
	v_mfma_f32_16x16x32_bf16 v[112:115], v[156:159], v[164:167], v[112:115]
	v_mfma_f32_16x16x32_bf16 v[100:103], v[148:151], v[172:175], v[100:103]
	v_mfma_f32_16x16x32_bf16 v[96:99], v[156:159], v[172:175], v[96:99]
	s_setprio 2
	s_barrier
	v_mfma_f32_16x16x32_bf16 v[84:87], v[148:151], v[180:183], v[84:87]
	v_mfma_f32_16x16x32_bf16 v[80:83], v[156:159], v[180:183], v[80:83]
	v_mfma_f32_16x16x32_bf16 v[68:71], v[148:151], v[204:207], v[68:71]
	v_mfma_f32_16x16x32_bf16 v[64:67], v[156:159], v[204:207], v[64:67]
	s_setprio 2
	s_add_i32 s67, s62, s49
	v_lshl_add_u64 v[208:209], s[40:41], 0, v[186:187]
	s_mov_b32 m0, s67
	ds_read_b128 v[160:163], v235 offset:16384
	ds_read_b128 v[164:167], v235 offset:17408
	ds_read_b128 v[168:171], v235 offset:18432
	ds_read_b128 v[172:175], v235 offset:19456
	ds_read_b128 v[176:179], v235 offset:20480
	ds_read_b128 v[180:183], v235 offset:21504
	ds_read_b128 v[200:203], v235 offset:22528
	ds_read_b128 v[204:207], v235 offset:23552
	global_load_lds_dwordx4 v[208:209], off
	s_add_i32 m0, s67, 0x2000
	s_add_u32 s68, s40, 0x40000
	v_lshl_add_u64 v[210:211], s[40:41], 0, v[190:191]
	s_addc_u32 s69, s41, 0
	s_add_i32 s67, s63, s49
	global_load_lds_dwordx4 v[210:211], off
	v_lshl_add_u64 v[212:213], s[68:69], 0, v[186:187]
	s_mov_b32 m0, s67
	v_lshl_add_u64 v[214:215], s[42:43], 0, v[188:189]
	global_load_lds_dwordx4 v[212:213], off
	s_add_i32 m0, s67, 0x2000
	v_lshl_add_u64 v[212:213], s[68:69], 0, v[190:191]
	global_load_lds_dwordx4 v[212:213], off
	s_mov_b32 m0, s50
	v_lshl_add_u64 v[212:213], s[42:43], 0, v[184:185]
	global_load_lds_dwordx4 v[212:213], off
	s_mov_b32 m0, s51
	s_nop 0
	global_load_lds_dwordx4 v[214:215], off
	s_waitcnt vmcnt(8) lgkmcnt(0)
	s_barrier
	s_setprio 1
	v_mfma_f32_16x16x32_bf16 v[60:63], v[120:123], v[160:163], 0
	v_mfma_f32_16x16x32_bf16 v[56:59], v[136:139], v[160:163], 0
	v_mfma_f32_16x16x32_bf16 v[44:47], v[120:123], v[168:171], 0
	v_mfma_f32_16x16x32_bf16 v[40:43], v[136:139], v[168:171], 0
	v_mfma_f32_16x16x32_bf16 v[28:31], v[120:123], v[176:179], 0
	v_mfma_f32_16x16x32_bf16 v[24:27], v[136:139], v[176:179], 0
	v_mfma_f32_16x16x32_bf16 v[12:15], v[120:123], v[200:203], 0
	v_mfma_f32_16x16x32_bf16 v[8:11], v[136:139], v[200:203], 0
	v_mfma_f32_16x16x32_bf16 v[60:63], v[132:135], v[164:167], v[60:63]
	v_mfma_f32_16x16x32_bf16 v[56:59], v[140:143], v[164:167], v[56:59]
	v_mfma_f32_16x16x32_bf16 v[44:47], v[132:135], v[172:175], v[44:47]
	v_mfma_f32_16x16x32_bf16 v[40:43], v[140:143], v[172:175], v[40:43]
	v_mfma_f32_16x16x32_bf16 v[28:31], v[132:135], v[180:183], v[28:31]
	v_mfma_f32_16x16x32_bf16 v[24:27], v[140:143], v[180:183], v[24:27]
	v_mfma_f32_16x16x32_bf16 v[12:15], v[132:135], v[204:207], v[12:15]
	v_mfma_f32_16x16x32_bf16 v[8:11], v[140:143], v[204:207], v[8:11]
	v_mfma_f32_16x16x32_bf16 v[52:55], v[144:147], v[160:163], 0
	v_mfma_f32_16x16x32_bf16 v[48:51], v[152:155], v[160:163], 0
	v_mfma_f32_16x16x32_bf16 v[36:39], v[144:147], v[168:171], 0
	v_mfma_f32_16x16x32_bf16 v[32:35], v[152:155], v[168:171], 0
	v_mfma_f32_16x16x32_bf16 v[20:23], v[144:147], v[176:179], 0
	v_mfma_f32_16x16x32_bf16 v[16:19], v[152:155], v[176:179], 0
	v_mfma_f32_16x16x32_bf16 v[4:7], v[144:147], v[200:203], 0
	v_mfma_f32_16x16x32_bf16 v[0:3], v[152:155], v[200:203], 0
	v_mfma_f32_16x16x32_bf16 v[52:55], v[148:151], v[164:167], v[52:55]
	v_mfma_f32_16x16x32_bf16 v[48:51], v[156:159], v[164:167], v[48:51]
	v_mfma_f32_16x16x32_bf16 v[36:39], v[148:151], v[172:175], v[36:39]
	v_mfma_f32_16x16x32_bf16 v[32:35], v[156:159], v[172:175], v[32:35]
	s_setprio 2
	s_barrier
	v_mfma_f32_16x16x32_bf16 v[20:23], v[148:151], v[180:183], v[20:23]
	v_mfma_f32_16x16x32_bf16 v[16:19], v[156:159], v[180:183], v[16:19]
	v_mfma_f32_16x16x32_bf16 v[4:7], v[148:151], v[204:207], v[4:7]
	v_mfma_f32_16x16x32_bf16 v[0:3], v[156:159], v[204:207], v[0:3]
	s_setprio 0
	s_add_i32 s67, 0, 0x18000
	s_add_i32 s68, 0, 0x1c000
	v_add_u32_e32 v140, s67, v232
	v_add_u32_e32 v156, s68, v232
	ds_read_b128 v[120:123], v140
	ds_read_b128 v[132:135], v140 offset:1024
	ds_read_b128 v[136:139], v140 offset:2048
	ds_read_b128 v[140:143], v140 offset:3072
	ds_read_b128 v[144:147], v156
	ds_read_b128 v[148:151], v156 offset:1024
	ds_read_b128 v[152:155], v156 offset:2048
	ds_read_b128 v[156:159], v156 offset:3072
	s_add_u32 s42, s42, 0x40000
	s_addc_u32 s43, s43, 0
	s_mov_b32 m0, s54
	v_lshl_add_u64 v[216:217], s[42:43], 0, v[184:185]
	ds_read_b128 v[160:163], v235 offset:32768
	ds_read_b128 v[164:167], v235 offset:33792
	ds_read_b128 v[168:171], v235 offset:34816
	ds_read_b128 v[172:175], v235 offset:35840
	ds_read_b128 v[176:179], v235 offset:36864
	ds_read_b128 v[180:183], v235 offset:37888
	ds_read_b128 v[200:203], v235 offset:38912
	ds_read_b128 v[204:207], v235 offset:39936
	global_load_lds_dwordx4 v[216:217], off
	s_mov_b32 m0, s55
	v_lshl_add_u64 v[216:217], s[42:43], 0, v[188:189]
	global_load_lds_dwordx4 v[216:217], off
	s_waitcnt vmcnt(8) lgkmcnt(0)
	s_barrier
	s_setprio 1
	v_mfma_f32_16x16x32_bf16 v[128:131], v[120:123], v[160:163], v[128:131]
	v_mfma_f32_16x16x32_bf16 v[124:127], v[136:139], v[160:163], v[124:127]
	v_mfma_f32_16x16x32_bf16 v[108:111], v[120:123], v[168:171], v[108:111]
	v_mfma_f32_16x16x32_bf16 v[104:107], v[136:139], v[168:171], v[104:107]
	v_mfma_f32_16x16x32_bf16 v[92:95], v[120:123], v[176:179], v[92:95]
	v_mfma_f32_16x16x32_bf16 v[88:91], v[136:139], v[176:179], v[88:91]
	v_mfma_f32_16x16x32_bf16 v[76:79], v[120:123], v[200:203], v[76:79]
	v_mfma_f32_16x16x32_bf16 v[72:75], v[136:139], v[200:203], v[72:75]
	v_mfma_f32_16x16x32_bf16 v[128:131], v[132:135], v[164:167], v[128:131]
	v_mfma_f32_16x16x32_bf16 v[124:127], v[140:143], v[164:167], v[124:127]
	v_mfma_f32_16x16x32_bf16 v[108:111], v[132:135], v[172:175], v[108:111]
	v_mfma_f32_16x16x32_bf16 v[104:107], v[140:143], v[172:175], v[104:107]
	v_mfma_f32_16x16x32_bf16 v[92:95], v[132:135], v[180:183], v[92:95]
	v_mfma_f32_16x16x32_bf16 v[88:91], v[140:143], v[180:183], v[88:91]
	v_mfma_f32_16x16x32_bf16 v[76:79], v[132:135], v[204:207], v[76:79]
	v_mfma_f32_16x16x32_bf16 v[72:75], v[140:143], v[204:207], v[72:75]
	v_mfma_f32_16x16x32_bf16 v[116:119], v[144:147], v[160:163], v[116:119]
	v_mfma_f32_16x16x32_bf16 v[112:115], v[152:155], v[160:163], v[112:115]
	v_mfma_f32_16x16x32_bf16 v[100:103], v[144:147], v[168:171], v[100:103]
	v_mfma_f32_16x16x32_bf16 v[96:99], v[152:155], v[168:171], v[96:99]
	v_mfma_f32_16x16x32_bf16 v[84:87], v[144:147], v[176:179], v[84:87]
	v_mfma_f32_16x16x32_bf16 v[80:83], v[152:155], v[176:179], v[80:83]
	v_mfma_f32_16x16x32_bf16 v[68:71], v[144:147], v[200:203], v[68:71]
	v_mfma_f32_16x16x32_bf16 v[64:67], v[152:155], v[200:203], v[64:67]
	v_mfma_f32_16x16x32_bf16 v[116:119], v[148:151], v[164:167], v[116:119]
	v_mfma_f32_16x16x32_bf16 v[112:115], v[156:159], v[164:167], v[112:115]
	v_mfma_f32_16x16x32_bf16 v[100:103], v[148:151], v[172:175], v[100:103]
	v_mfma_f32_16x16x32_bf16 v[96:99], v[156:159], v[172:175], v[96:99]
	s_setprio 2
	s_barrier
	v_mfma_f32_16x16x32_bf16 v[84:87], v[148:151], v[180:183], v[84:87]
	v_mfma_f32_16x16x32_bf16 v[80:83], v[156:159], v[180:183], v[80:83]
	v_mfma_f32_16x16x32_bf16 v[68:71], v[148:151], v[204:207], v[68:71]
	v_mfma_f32_16x16x32_bf16 v[64:67], v[156:159], v[204:207], v[64:67]
	s_setprio 2
	s_add_i32 s42, s67, s49
	v_lshl_add_u64 v[208:209], v[208:209], 0, s[18:19]
	s_mov_b32 m0, s42
	ds_read_b128 v[160:163], v235 offset:49152
	ds_read_b128 v[164:167], v235 offset:50176
	ds_read_b128 v[168:171], v235 offset:51200
	ds_read_b128 v[172:175], v235 offset:52224
	ds_read_b128 v[176:179], v235 offset:53248
	ds_read_b128 v[180:183], v235 offset:54272
	ds_read_b128 v[200:203], v235 offset:55296
	ds_read_b128 v[204:207], v235 offset:56320
	global_load_lds_dwordx4 v[208:209], off
	s_add_i32 m0, s42, 0x2000
	s_add_u32 s40, s40, 0x40080
	v_lshl_add_u64 v[208:209], v[210:211], 0, s[18:19]
	s_addc_u32 s41, s41, 0
	s_add_i32 s42, s68, s49
	global_load_lds_dwordx4 v[208:209], off
	s_mov_b32 m0, s42
	v_lshl_add_u64 v[208:209], s[40:41], 0, v[186:187]
	global_load_lds_dwordx4 v[208:209], off
	s_add_i32 m0, s42, 0x2000
	v_lshl_add_u64 v[208:209], s[40:41], 0, v[190:191]
	global_load_lds_dwordx4 v[208:209], off
	s_mov_b32 m0, s57
	v_lshl_add_u64 v[208:209], v[212:213], 0, s[18:19]
	global_load_lds_dwordx4 v[208:209], off
	s_mov_b32 m0, s58
	v_lshl_add_u64 v[208:209], v[214:215], 0, s[18:19]
	global_load_lds_dwordx4 v[208:209], off
	s_waitcnt vmcnt(8) lgkmcnt(0)
	s_barrier
	s_setprio 1
	v_mfma_f32_16x16x32_bf16 v[60:63], v[120:123], v[160:163], v[60:63]
	v_mfma_f32_16x16x32_bf16 v[56:59], v[136:139], v[160:163], v[56:59]
	v_mfma_f32_16x16x32_bf16 v[44:47], v[120:123], v[168:171], v[44:47]
	v_mfma_f32_16x16x32_bf16 v[40:43], v[136:139], v[168:171], v[40:43]
	v_mfma_f32_16x16x32_bf16 v[28:31], v[120:123], v[176:179], v[28:31]
	v_mfma_f32_16x16x32_bf16 v[24:27], v[136:139], v[176:179], v[24:27]
	v_mfma_f32_16x16x32_bf16 v[12:15], v[120:123], v[200:203], v[12:15]
	v_mfma_f32_16x16x32_bf16 v[8:11], v[136:139], v[200:203], v[8:11]
	v_mfma_f32_16x16x32_bf16 v[60:63], v[132:135], v[164:167], v[60:63]
	v_mfma_f32_16x16x32_bf16 v[56:59], v[140:143], v[164:167], v[56:59]
	v_mfma_f32_16x16x32_bf16 v[44:47], v[132:135], v[172:175], v[44:47]
	v_mfma_f32_16x16x32_bf16 v[40:43], v[140:143], v[172:175], v[40:43]
	v_mfma_f32_16x16x32_bf16 v[28:31], v[132:135], v[180:183], v[28:31]
	v_mfma_f32_16x16x32_bf16 v[24:27], v[140:143], v[180:183], v[24:27]
	v_mfma_f32_16x16x32_bf16 v[12:15], v[132:135], v[204:207], v[12:15]
	v_mfma_f32_16x16x32_bf16 v[8:11], v[140:143], v[204:207], v[8:11]
	v_mfma_f32_16x16x32_bf16 v[52:55], v[144:147], v[160:163], v[52:55]
	v_mfma_f32_16x16x32_bf16 v[48:51], v[152:155], v[160:163], v[48:51]
	v_mfma_f32_16x16x32_bf16 v[36:39], v[144:147], v[168:171], v[36:39]
	v_mfma_f32_16x16x32_bf16 v[32:35], v[152:155], v[168:171], v[32:35]
	v_mfma_f32_16x16x32_bf16 v[20:23], v[144:147], v[176:179], v[20:23]
	v_mfma_f32_16x16x32_bf16 v[16:19], v[152:155], v[176:179], v[16:19]
	v_mfma_f32_16x16x32_bf16 v[4:7], v[144:147], v[200:203], v[4:7]
	v_mfma_f32_16x16x32_bf16 v[0:3], v[152:155], v[200:203], v[0:3]
	v_mfma_f32_16x16x32_bf16 v[52:55], v[148:151], v[164:167], v[52:55]
	v_mfma_f32_16x16x32_bf16 v[48:51], v[156:159], v[164:167], v[48:51]
	v_mfma_f32_16x16x32_bf16 v[36:39], v[148:151], v[172:175], v[36:39]
	v_mfma_f32_16x16x32_bf16 v[32:35], v[156:159], v[172:175], v[32:35]
	s_setprio 2
	s_barrier
	v_mfma_f32_16x16x32_bf16 v[20:23], v[148:151], v[180:183], v[20:23]
	v_mfma_f32_16x16x32_bf16 v[16:19], v[156:159], v[180:183], v[16:19]
	v_mfma_f32_16x16x32_bf16 v[4:7], v[148:151], v[204:207], v[4:7]
	v_mfma_f32_16x16x32_bf16 v[0:3], v[156:159], v[204:207], v[0:3]
	s_setprio 0
	s_add_i32 s66, s66, 2
	s_add_u32 s38, s38, 0x100
	s_addc_u32 s39, s39, 0
	s_add_u32 s64, s64, 0x100
	s_addc_u32 s65, s65, 0
	s_cmp_gt_u32 s66, 13
.LBB0_1146:
	ds_read_b128 v[120:123], v233
	ds_read_b128 v[132:135], v233 offset:1024
	ds_read_b128 v[136:139], v233 offset:2048
	ds_read_b128 v[140:143], v233 offset:3072
	ds_read_b128 v[144:147], v234
	ds_read_b128 v[148:151], v234 offset:1024
	ds_read_b128 v[152:155], v234 offset:2048
	ds_read_b128 v[156:159], v234 offset:3072
	s_add_u32 s40, s38, 0xfffc0080
	s_addc_u32 s41, s39, -1
	s_cmp_eq_u32 s66, 12
	s_cselect_b32 s43, s23, s41
	s_cselect_b32 s42, s31, s40
	s_cselect_b32 s41, s25, s65
	s_cselect_b32 s40, s37, s64
	v_lshl_add_u64 v[208:209], s[38:39], 0, v[192:193]
	s_add_i32 m0, s50, 0xc000
	ds_read_b128 v[160:163], v235
	ds_read_b128 v[164:167], v235 offset:1024
	ds_read_b128 v[168:171], v235 offset:2048
	ds_read_b128 v[172:175], v235 offset:3072
	ds_read_b128 v[176:179], v235 offset:4096
	ds_read_b128 v[180:183], v235 offset:5120
	ds_read_b128 v[200:203], v235 offset:6144
	ds_read_b128 v[204:207], v235 offset:7168
	global_load_lds_dwordx4 v[208:209], off
	s_add_i32 m0, s50, 0xe000
	v_lshl_add_u64 v[208:209], s[38:39], 0, v[194:195]
	global_load_lds_dwordx4 v[208:209], off
	s_waitcnt vmcnt(8) lgkmcnt(0)
	s_barrier
	s_setprio 1
	v_mfma_f32_16x16x32_bf16 v[128:131], v[120:123], v[160:163], v[128:131]
	v_mfma_f32_16x16x32_bf16 v[124:127], v[136:139], v[160:163], v[124:127]
	v_mfma_f32_16x16x32_bf16 v[108:111], v[120:123], v[168:171], v[108:111]
	v_mfma_f32_16x16x32_bf16 v[104:107], v[136:139], v[168:171], v[104:107]
	v_mfma_f32_16x16x32_bf16 v[92:95], v[120:123], v[176:179], v[92:95]
	v_mfma_f32_16x16x32_bf16 v[88:91], v[136:139], v[176:179], v[88:91]
	v_mfma_f32_16x16x32_bf16 v[76:79], v[120:123], v[200:203], v[76:79]
	v_mfma_f32_16x16x32_bf16 v[72:75], v[136:139], v[200:203], v[72:75]
	v_mfma_f32_16x16x32_bf16 v[128:131], v[132:135], v[164:167], v[128:131]
	v_mfma_f32_16x16x32_bf16 v[124:127], v[140:143], v[164:167], v[124:127]
	v_mfma_f32_16x16x32_bf16 v[108:111], v[132:135], v[172:175], v[108:111]
	v_mfma_f32_16x16x32_bf16 v[104:107], v[140:143], v[172:175], v[104:107]
	v_mfma_f32_16x16x32_bf16 v[92:95], v[132:135], v[180:183], v[92:95]
	v_mfma_f32_16x16x32_bf16 v[88:91], v[140:143], v[180:183], v[88:91]
	v_mfma_f32_16x16x32_bf16 v[76:79], v[132:135], v[204:207], v[76:79]
	v_mfma_f32_16x16x32_bf16 v[72:75], v[140:143], v[204:207], v[72:75]
	v_mfma_f32_16x16x32_bf16 v[116:119], v[144:147], v[160:163], v[116:119]
	v_mfma_f32_16x16x32_bf16 v[112:115], v[152:155], v[160:163], v[112:115]
	v_mfma_f32_16x16x32_bf16 v[100:103], v[144:147], v[168:171], v[100:103]
	v_mfma_f32_16x16x32_bf16 v[96:99], v[152:155], v[168:171], v[96:99]
	v_mfma_f32_16x16x32_bf16 v[84:87], v[144:147], v[176:179], v[84:87]
	v_mfma_f32_16x16x32_bf16 v[80:83], v[152:155], v[176:179], v[80:83]
	v_mfma_f32_16x16x32_bf16 v[68:71], v[144:147], v[200:203], v[68:71]
	v_mfma_f32_16x16x32_bf16 v[64:67], v[152:155], v[200:203], v[64:67]
	v_mfma_f32_16x16x32_bf16 v[116:119], v[148:151], v[164:167], v[116:119]
	v_mfma_f32_16x16x32_bf16 v[112:115], v[156:159], v[164:167], v[112:115]
	v_mfma_f32_16x16x32_bf16 v[100:103], v[148:151], v[172:175], v[100:103]
	v_mfma_f32_16x16x32_bf16 v[96:99], v[156:159], v[172:175], v[96:99]
	s_setprio 2
	s_barrier
	v_mfma_f32_16x16x32_bf16 v[84:87], v[148:151], v[180:183], v[84:87]
	v_mfma_f32_16x16x32_bf16 v[80:83], v[156:159], v[180:183], v[80:83]
	v_mfma_f32_16x16x32_bf16 v[68:71], v[148:151], v[204:207], v[68:71]
	v_mfma_f32_16x16x32_bf16 v[64:67], v[156:159], v[204:207], v[64:67]
	s_setprio 2
	s_add_i32 s67, s62, s49
	v_lshl_add_u64 v[208:209], s[40:41], 0, v[186:187]
	s_mov_b32 m0, s67
	ds_read_b128 v[160:163], v235 offset:16384
	ds_read_b128 v[164:167], v235 offset:17408
	ds_read_b128 v[168:171], v235 offset:18432
	ds_read_b128 v[172:175], v235 offset:19456
	ds_read_b128 v[176:179], v235 offset:20480
	ds_read_b128 v[180:183], v235 offset:21504
	ds_read_b128 v[200:203], v235 offset:22528
	ds_read_b128 v[204:207], v235 offset:23552
	global_load_lds_dwordx4 v[208:209], off
	s_add_i32 m0, s67, 0x2000
	s_add_u32 s68, s40, 0x40000
	v_lshl_add_u64 v[210:211], s[40:41], 0, v[190:191]
	s_addc_u32 s69, s41, 0
	s_add_i32 s67, s63, s49
	global_load_lds_dwordx4 v[210:211], off
	v_lshl_add_u64 v[212:213], s[68:69], 0, v[186:187]
	s_mov_b32 m0, s67
	v_lshl_add_u64 v[214:215], s[42:43], 0, v[188:189]
	global_load_lds_dwordx4 v[212:213], off
	s_add_i32 m0, s67, 0x2000
	v_lshl_add_u64 v[212:213], s[68:69], 0, v[190:191]
	global_load_lds_dwordx4 v[212:213], off
	s_mov_b32 m0, s50
	v_lshl_add_u64 v[212:213], s[42:43], 0, v[184:185]
	global_load_lds_dwordx4 v[212:213], off
	s_mov_b32 m0, s51
	s_nop 0
	global_load_lds_dwordx4 v[214:215], off
	s_waitcnt vmcnt(8) lgkmcnt(0)
	s_barrier
	s_setprio 1
	v_mfma_f32_16x16x32_bf16 v[60:63], v[120:123], v[160:163], v[60:63]
	v_mfma_f32_16x16x32_bf16 v[56:59], v[136:139], v[160:163], v[56:59]
	v_mfma_f32_16x16x32_bf16 v[44:47], v[120:123], v[168:171], v[44:47]
	v_mfma_f32_16x16x32_bf16 v[40:43], v[136:139], v[168:171], v[40:43]
	v_mfma_f32_16x16x32_bf16 v[28:31], v[120:123], v[176:179], v[28:31]
	v_mfma_f32_16x16x32_bf16 v[24:27], v[136:139], v[176:179], v[24:27]
	v_mfma_f32_16x16x32_bf16 v[12:15], v[120:123], v[200:203], v[12:15]
	v_mfma_f32_16x16x32_bf16 v[8:11], v[136:139], v[200:203], v[8:11]
	v_mfma_f32_16x16x32_bf16 v[60:63], v[132:135], v[164:167], v[60:63]
	v_mfma_f32_16x16x32_bf16 v[56:59], v[140:143], v[164:167], v[56:59]
	v_mfma_f32_16x16x32_bf16 v[44:47], v[132:135], v[172:175], v[44:47]
	v_mfma_f32_16x16x32_bf16 v[40:43], v[140:143], v[172:175], v[40:43]
	v_mfma_f32_16x16x32_bf16 v[28:31], v[132:135], v[180:183], v[28:31]
	v_mfma_f32_16x16x32_bf16 v[24:27], v[140:143], v[180:183], v[24:27]
	v_mfma_f32_16x16x32_bf16 v[12:15], v[132:135], v[204:207], v[12:15]
	v_mfma_f32_16x16x32_bf16 v[8:11], v[140:143], v[204:207], v[8:11]
	v_mfma_f32_16x16x32_bf16 v[52:55], v[144:147], v[160:163], v[52:55]
	v_mfma_f32_16x16x32_bf16 v[48:51], v[152:155], v[160:163], v[48:51]
	v_mfma_f32_16x16x32_bf16 v[36:39], v[144:147], v[168:171], v[36:39]
	v_mfma_f32_16x16x32_bf16 v[32:35], v[152:155], v[168:171], v[32:35]
	v_mfma_f32_16x16x32_bf16 v[20:23], v[144:147], v[176:179], v[20:23]
	v_mfma_f32_16x16x32_bf16 v[16:19], v[152:155], v[176:179], v[16:19]
	v_mfma_f32_16x16x32_bf16 v[4:7], v[144:147], v[200:203], v[4:7]
	v_mfma_f32_16x16x32_bf16 v[0:3], v[152:155], v[200:203], v[0:3]
	v_mfma_f32_16x16x32_bf16 v[52:55], v[148:151], v[164:167], v[52:55]
	v_mfma_f32_16x16x32_bf16 v[48:51], v[156:159], v[164:167], v[48:51]
	v_mfma_f32_16x16x32_bf16 v[36:39], v[148:151], v[172:175], v[36:39]
	v_mfma_f32_16x16x32_bf16 v[32:35], v[156:159], v[172:175], v[32:35]
	s_setprio 2
	s_barrier
	v_mfma_f32_16x16x32_bf16 v[20:23], v[148:151], v[180:183], v[20:23]
	v_mfma_f32_16x16x32_bf16 v[16:19], v[156:159], v[180:183], v[16:19]
	v_mfma_f32_16x16x32_bf16 v[4:7], v[148:151], v[204:207], v[4:7]
	v_mfma_f32_16x16x32_bf16 v[0:3], v[156:159], v[204:207], v[0:3]
	s_setprio 0
	s_add_i32 s67, 0, 0x18000
	s_add_i32 s68, 0, 0x1c000
	v_add_u32_e32 v140, s67, v232
	v_add_u32_e32 v156, s68, v232
	ds_read_b128 v[120:123], v140
	ds_read_b128 v[132:135], v140 offset:1024
	ds_read_b128 v[136:139], v140 offset:2048
	ds_read_b128 v[140:143], v140 offset:3072
	ds_read_b128 v[144:147], v156
	ds_read_b128 v[148:151], v156 offset:1024
	ds_read_b128 v[152:155], v156 offset:2048
	ds_read_b128 v[156:159], v156 offset:3072
	s_add_u32 s42, s42, 0x40000
	s_addc_u32 s43, s43, 0
	s_mov_b32 m0, s54
	v_lshl_add_u64 v[216:217], s[42:43], 0, v[184:185]
	ds_read_b128 v[160:163], v235 offset:32768
	ds_read_b128 v[164:167], v235 offset:33792
	ds_read_b128 v[168:171], v235 offset:34816
	ds_read_b128 v[172:175], v235 offset:35840
	ds_read_b128 v[176:179], v235 offset:36864
	ds_read_b128 v[180:183], v235 offset:37888
	ds_read_b128 v[200:203], v235 offset:38912
	ds_read_b128 v[204:207], v235 offset:39936
	global_load_lds_dwordx4 v[216:217], off
	s_mov_b32 m0, s55
	v_lshl_add_u64 v[216:217], s[42:43], 0, v[188:189]
	global_load_lds_dwordx4 v[216:217], off
	s_waitcnt vmcnt(8) lgkmcnt(0)
	s_barrier
	s_setprio 1
	v_mfma_f32_16x16x32_bf16 v[128:131], v[120:123], v[160:163], v[128:131]
	v_mfma_f32_16x16x32_bf16 v[124:127], v[136:139], v[160:163], v[124:127]
	v_mfma_f32_16x16x32_bf16 v[108:111], v[120:123], v[168:171], v[108:111]
	v_mfma_f32_16x16x32_bf16 v[104:107], v[136:139], v[168:171], v[104:107]
	v_mfma_f32_16x16x32_bf16 v[92:95], v[120:123], v[176:179], v[92:95]
	v_mfma_f32_16x16x32_bf16 v[88:91], v[136:139], v[176:179], v[88:91]
	v_mfma_f32_16x16x32_bf16 v[76:79], v[120:123], v[200:203], v[76:79]
	v_mfma_f32_16x16x32_bf16 v[72:75], v[136:139], v[200:203], v[72:75]
	v_mfma_f32_16x16x32_bf16 v[128:131], v[132:135], v[164:167], v[128:131]
	v_mfma_f32_16x16x32_bf16 v[124:127], v[140:143], v[164:167], v[124:127]
	v_mfma_f32_16x16x32_bf16 v[108:111], v[132:135], v[172:175], v[108:111]
	v_mfma_f32_16x16x32_bf16 v[104:107], v[140:143], v[172:175], v[104:107]
	v_mfma_f32_16x16x32_bf16 v[92:95], v[132:135], v[180:183], v[92:95]
	v_mfma_f32_16x16x32_bf16 v[88:91], v[140:143], v[180:183], v[88:91]
	v_mfma_f32_16x16x32_bf16 v[76:79], v[132:135], v[204:207], v[76:79]
	v_mfma_f32_16x16x32_bf16 v[72:75], v[140:143], v[204:207], v[72:75]
	v_mfma_f32_16x16x32_bf16 v[116:119], v[144:147], v[160:163], v[116:119]
	v_mfma_f32_16x16x32_bf16 v[112:115], v[152:155], v[160:163], v[112:115]
	v_mfma_f32_16x16x32_bf16 v[100:103], v[144:147], v[168:171], v[100:103]
	v_mfma_f32_16x16x32_bf16 v[96:99], v[152:155], v[168:171], v[96:99]
	v_mfma_f32_16x16x32_bf16 v[84:87], v[144:147], v[176:179], v[84:87]
	v_mfma_f32_16x16x32_bf16 v[80:83], v[152:155], v[176:179], v[80:83]
	v_mfma_f32_16x16x32_bf16 v[68:71], v[144:147], v[200:203], v[68:71]
	v_mfma_f32_16x16x32_bf16 v[64:67], v[152:155], v[200:203], v[64:67]
	v_mfma_f32_16x16x32_bf16 v[116:119], v[148:151], v[164:167], v[116:119]
	v_mfma_f32_16x16x32_bf16 v[112:115], v[156:159], v[164:167], v[112:115]
	v_mfma_f32_16x16x32_bf16 v[100:103], v[148:151], v[172:175], v[100:103]
	v_mfma_f32_16x16x32_bf16 v[96:99], v[156:159], v[172:175], v[96:99]
	s_setprio 2
	s_barrier
	v_mfma_f32_16x16x32_bf16 v[84:87], v[148:151], v[180:183], v[84:87]
	v_mfma_f32_16x16x32_bf16 v[80:83], v[156:159], v[180:183], v[80:83]
	v_mfma_f32_16x16x32_bf16 v[68:71], v[148:151], v[204:207], v[68:71]
	v_mfma_f32_16x16x32_bf16 v[64:67], v[156:159], v[204:207], v[64:67]
	s_setprio 2
	s_add_i32 s42, s67, s49
	v_lshl_add_u64 v[208:209], v[208:209], 0, s[18:19]
	s_mov_b32 m0, s42
	ds_read_b128 v[160:163], v235 offset:49152
	ds_read_b128 v[164:167], v235 offset:50176
	ds_read_b128 v[168:171], v235 offset:51200
	ds_read_b128 v[172:175], v235 offset:52224
	ds_read_b128 v[176:179], v235 offset:53248
	ds_read_b128 v[180:183], v235 offset:54272
	ds_read_b128 v[200:203], v235 offset:55296
	ds_read_b128 v[204:207], v235 offset:56320
	global_load_lds_dwordx4 v[208:209], off
	s_add_i32 m0, s42, 0x2000
	s_add_u32 s40, s40, 0x40080
	v_lshl_add_u64 v[208:209], v[210:211], 0, s[18:19]
	s_addc_u32 s41, s41, 0
	s_add_i32 s42, s68, s49
	global_load_lds_dwordx4 v[208:209], off
	s_mov_b32 m0, s42
	v_lshl_add_u64 v[208:209], s[40:41], 0, v[186:187]
	global_load_lds_dwordx4 v[208:209], off
	s_add_i32 m0, s42, 0x2000
	v_lshl_add_u64 v[208:209], s[40:41], 0, v[190:191]
	global_load_lds_dwordx4 v[208:209], off
	s_mov_b32 m0, s57
	v_lshl_add_u64 v[208:209], v[212:213], 0, s[18:19]
	global_load_lds_dwordx4 v[208:209], off
	s_mov_b32 m0, s58
	v_lshl_add_u64 v[208:209], v[214:215], 0, s[18:19]
	global_load_lds_dwordx4 v[208:209], off
	s_waitcnt vmcnt(8) lgkmcnt(0)
	s_barrier
	s_setprio 1
	v_mfma_f32_16x16x32_bf16 v[60:63], v[120:123], v[160:163], v[60:63]
	v_mfma_f32_16x16x32_bf16 v[56:59], v[136:139], v[160:163], v[56:59]
	v_mfma_f32_16x16x32_bf16 v[44:47], v[120:123], v[168:171], v[44:47]
	v_mfma_f32_16x16x32_bf16 v[40:43], v[136:139], v[168:171], v[40:43]
	v_mfma_f32_16x16x32_bf16 v[28:31], v[120:123], v[176:179], v[28:31]
	v_mfma_f32_16x16x32_bf16 v[24:27], v[136:139], v[176:179], v[24:27]
	v_mfma_f32_16x16x32_bf16 v[12:15], v[120:123], v[200:203], v[12:15]
	v_mfma_f32_16x16x32_bf16 v[8:11], v[136:139], v[200:203], v[8:11]
	v_mfma_f32_16x16x32_bf16 v[60:63], v[132:135], v[164:167], v[60:63]
	v_mfma_f32_16x16x32_bf16 v[56:59], v[140:143], v[164:167], v[56:59]
	v_mfma_f32_16x16x32_bf16 v[44:47], v[132:135], v[172:175], v[44:47]
	v_mfma_f32_16x16x32_bf16 v[40:43], v[140:143], v[172:175], v[40:43]
	v_mfma_f32_16x16x32_bf16 v[28:31], v[132:135], v[180:183], v[28:31]
	v_mfma_f32_16x16x32_bf16 v[24:27], v[140:143], v[180:183], v[24:27]
	v_mfma_f32_16x16x32_bf16 v[12:15], v[132:135], v[204:207], v[12:15]
	v_mfma_f32_16x16x32_bf16 v[8:11], v[140:143], v[204:207], v[8:11]
	v_mfma_f32_16x16x32_bf16 v[52:55], v[144:147], v[160:163], v[52:55]
	v_mfma_f32_16x16x32_bf16 v[48:51], v[152:155], v[160:163], v[48:51]
	v_mfma_f32_16x16x32_bf16 v[36:39], v[144:147], v[168:171], v[36:39]
	v_mfma_f32_16x16x32_bf16 v[32:35], v[152:155], v[168:171], v[32:35]
	v_mfma_f32_16x16x32_bf16 v[20:23], v[144:147], v[176:179], v[20:23]
	v_mfma_f32_16x16x32_bf16 v[16:19], v[152:155], v[176:179], v[16:19]
	v_mfma_f32_16x16x32_bf16 v[4:7], v[144:147], v[200:203], v[4:7]
	v_mfma_f32_16x16x32_bf16 v[0:3], v[152:155], v[200:203], v[0:3]
	v_mfma_f32_16x16x32_bf16 v[52:55], v[148:151], v[164:167], v[52:55]
	v_mfma_f32_16x16x32_bf16 v[48:51], v[156:159], v[164:167], v[48:51]
	v_mfma_f32_16x16x32_bf16 v[36:39], v[148:151], v[172:175], v[36:39]
	v_mfma_f32_16x16x32_bf16 v[32:35], v[156:159], v[172:175], v[32:35]
	s_setprio 2
	s_barrier
	v_mfma_f32_16x16x32_bf16 v[20:23], v[148:151], v[180:183], v[20:23]
	v_mfma_f32_16x16x32_bf16 v[16:19], v[156:159], v[180:183], v[16:19]
	v_mfma_f32_16x16x32_bf16 v[4:7], v[148:151], v[204:207], v[4:7]
	v_mfma_f32_16x16x32_bf16 v[0:3], v[156:159], v[204:207], v[0:3]
	s_setprio 0
	s_add_i32 s66, s66, 2
	s_add_u32 s38, s38, 0x100
	s_addc_u32 s39, s39, 0
	s_add_u32 s64, s64, 0x100
	s_addc_u32 s65, s65, 0
	s_cmp_gt_u32 s66, 13
	s_cbranch_scc0 .LBB0_1146

.LBB0_1309:
	s_add_u32 s51, s26, 0x100
	s_addc_u32 s52, s27, 0
	s_mov_b32 s53, -2
	ds_read_b128 v[128:131], v197
	ds_read_b128 v[132:135], v197 offset:1024
	ds_read_b128 v[136:139], v197 offset:2048
	ds_read_b128 v[140:143], v197 offset:3072
	ds_read_b128 v[144:147], v198
	ds_read_b128 v[148:151], v198 offset:1024
	ds_read_b128 v[152:155], v198 offset:2048
	ds_read_b128 v[156:159], v198 offset:3072
	s_add_u32 s4, s24, 0x100
	s_addc_u32 s5, s25, 0
	s_cmp_eq_u32 s53, 40
	s_cselect_b32 s29, s21, s5
	s_cselect_b32 s28, s20, s4
	s_cselect_b32 s27, s23, s52
	s_cselect_b32 s26, s22, s51
	v_lshl_add_u64 v[212:213], s[24:25], 0, v[172:173]
	s_add_i32 m0, s36, 0xc000
	ds_read_b128 v[160:163], v199
	ds_read_b128 v[180:183], v199 offset:1024
	ds_read_b128 v[184:187], v199 offset:2048
	ds_read_b128 v[188:191], v199 offset:3072
	ds_read_b128 v[192:195], v199 offset:4096
	ds_read_b128 v[200:203], v199 offset:5120
	ds_read_b128 v[204:207], v199 offset:6144
	ds_read_b128 v[208:211], v199 offset:7168
	global_load_lds_dwordx4 v[212:213], off
	s_add_i32 m0, s36, 0xe000
	v_lshl_add_u64 v[212:213], s[24:25], 0, v[174:175]
	global_load_lds_dwordx4 v[212:213], off
	s_waitcnt vmcnt(8) lgkmcnt(0)
	s_barrier
	s_setprio 1
	v_mfma_f32_16x16x32_bf16 v[124:127], v[128:131], v[160:163], 0
	v_mfma_f32_16x16x32_bf16 v[120:123], v[136:139], v[160:163], 0
	v_mfma_f32_16x16x32_bf16 v[116:119], v[128:131], v[184:187], 0
	v_mfma_f32_16x16x32_bf16 v[108:111], v[136:139], v[184:187], 0
	v_mfma_f32_16x16x32_bf16 v[88:91], v[128:131], v[192:195], 0
	v_mfma_f32_16x16x32_bf16 v[100:103], v[136:139], v[192:195], 0
	v_mfma_f32_16x16x32_bf16 v[72:75], v[128:131], v[204:207], 0
	v_mfma_f32_16x16x32_bf16 v[76:79], v[136:139], v[204:207], 0
	v_mfma_f32_16x16x32_bf16 v[124:127], v[132:135], v[180:183], v[124:127]
	v_mfma_f32_16x16x32_bf16 v[120:123], v[140:143], v[180:183], v[120:123]
	v_mfma_f32_16x16x32_bf16 v[116:119], v[132:135], v[188:191], v[116:119]
	v_mfma_f32_16x16x32_bf16 v[108:111], v[140:143], v[188:191], v[108:111]
	v_mfma_f32_16x16x32_bf16 v[88:91], v[132:135], v[200:203], v[88:91]
	v_mfma_f32_16x16x32_bf16 v[100:103], v[140:143], v[200:203], v[100:103]
	v_mfma_f32_16x16x32_bf16 v[72:75], v[132:135], v[208:211], v[72:75]
	v_mfma_f32_16x16x32_bf16 v[76:79], v[140:143], v[208:211], v[76:79]
	v_mfma_f32_16x16x32_bf16 v[112:115], v[144:147], v[160:163], 0
	v_mfma_f32_16x16x32_bf16 v[104:107], v[152:155], v[160:163], 0
	v_mfma_f32_16x16x32_bf16 v[96:99], v[144:147], v[184:187], 0
	v_mfma_f32_16x16x32_bf16 v[92:95], v[152:155], v[184:187], 0
	v_mfma_f32_16x16x32_bf16 v[80:83], v[144:147], v[192:195], 0
	v_mfma_f32_16x16x32_bf16 v[84:87], v[152:155], v[192:195], 0
	v_mfma_f32_16x16x32_bf16 v[64:67], v[144:147], v[204:207], 0
	v_mfma_f32_16x16x32_bf16 v[68:71], v[152:155], v[204:207], 0
	v_mfma_f32_16x16x32_bf16 v[112:115], v[148:151], v[180:183], v[112:115]
	v_mfma_f32_16x16x32_bf16 v[104:107], v[156:159], v[180:183], v[104:107]
	v_mfma_f32_16x16x32_bf16 v[96:99], v[148:151], v[188:191], v[96:99]
	v_mfma_f32_16x16x32_bf16 v[92:95], v[156:159], v[188:191], v[92:95]
	s_setprio 2
	s_barrier
	v_mfma_f32_16x16x32_bf16 v[80:83], v[148:151], v[200:203], v[80:83]
	v_mfma_f32_16x16x32_bf16 v[84:87], v[156:159], v[200:203], v[84:87]
	v_mfma_f32_16x16x32_bf16 v[64:67], v[148:151], v[208:211], v[64:67]
	v_mfma_f32_16x16x32_bf16 v[68:71], v[156:159], v[208:211], v[68:71]
	s_setprio 2
	s_add_i32 s24, s45, s35
	v_lshl_add_u64 v[212:213], s[26:27], 0, v[166:167]
	s_mov_b32 m0, s24
	ds_read_b128 v[160:163], v199 offset:16384
	ds_read_b128 v[180:183], v199 offset:17408
	ds_read_b128 v[184:187], v199 offset:18432
	ds_read_b128 v[188:191], v199 offset:19456
	ds_read_b128 v[192:195], v199 offset:20480
	ds_read_b128 v[200:203], v199 offset:21504
	ds_read_b128 v[204:207], v199 offset:22528
	ds_read_b128 v[208:211], v199 offset:23552
	global_load_lds_dwordx4 v[212:213], off
	s_add_i32 m0, s24, 0x2000
	s_add_u32 s24, s26, 0xb0000
	v_lshl_add_u64 v[214:215], s[26:27], 0, v[170:171]
	s_addc_u32 s25, s27, 0
	s_add_i32 s54, s46, s35
	global_load_lds_dwordx4 v[214:215], off
	v_lshl_add_u64 v[216:217], s[24:25], 0, v[166:167]
	s_mov_b32 m0, s54
	v_lshl_add_u64 v[218:219], s[28:29], 0, v[168:169]
	global_load_lds_dwordx4 v[216:217], off
	s_add_i32 m0, s54, 0x2000
	v_lshl_add_u64 v[216:217], s[24:25], 0, v[170:171]
	global_load_lds_dwordx4 v[216:217], off
	s_mov_b32 m0, s36
	v_lshl_add_u64 v[216:217], s[28:29], 0, v[164:165]
	global_load_lds_dwordx4 v[216:217], off
	s_mov_b32 m0, s37
	s_nop 0
	global_load_lds_dwordx4 v[218:219], off
	s_waitcnt vmcnt(8) lgkmcnt(0)
	s_barrier
	s_setprio 1
	v_mfma_f32_16x16x32_bf16 v[56:59], v[128:131], v[160:163], 0
	v_mfma_f32_16x16x32_bf16 v[60:63], v[136:139], v[160:163], 0
	v_mfma_f32_16x16x32_bf16 v[40:43], v[128:131], v[184:187], 0
	v_mfma_f32_16x16x32_bf16 v[44:47], v[136:139], v[184:187], 0
	v_mfma_f32_16x16x32_bf16 v[24:27], v[128:131], v[192:195], 0
	v_mfma_f32_16x16x32_bf16 v[28:31], v[136:139], v[192:195], 0
	v_mfma_f32_16x16x32_bf16 v[8:11], v[128:131], v[204:207], 0
	v_mfma_f32_16x16x32_bf16 v[12:15], v[136:139], v[204:207], 0
	v_mfma_f32_16x16x32_bf16 v[56:59], v[132:135], v[180:183], v[56:59]
	v_mfma_f32_16x16x32_bf16 v[60:63], v[140:143], v[180:183], v[60:63]
	v_mfma_f32_16x16x32_bf16 v[40:43], v[132:135], v[188:191], v[40:43]
	v_mfma_f32_16x16x32_bf16 v[44:47], v[140:143], v[188:191], v[44:47]
	v_mfma_f32_16x16x32_bf16 v[24:27], v[132:135], v[200:203], v[24:27]
	v_mfma_f32_16x16x32_bf16 v[28:31], v[140:143], v[200:203], v[28:31]
	v_mfma_f32_16x16x32_bf16 v[8:11], v[132:135], v[208:211], v[8:11]
	v_mfma_f32_16x16x32_bf16 v[12:15], v[140:143], v[208:211], v[12:15]
	v_mfma_f32_16x16x32_bf16 v[48:51], v[144:147], v[160:163], 0
	v_mfma_f32_16x16x32_bf16 v[52:55], v[152:155], v[160:163], 0
	v_mfma_f32_16x16x32_bf16 v[32:35], v[144:147], v[184:187], 0
	v_mfma_f32_16x16x32_bf16 v[36:39], v[152:155], v[184:187], 0
	v_mfma_f32_16x16x32_bf16 v[16:19], v[144:147], v[192:195], 0
	v_mfma_f32_16x16x32_bf16 v[20:23], v[152:155], v[192:195], 0
	v_mfma_f32_16x16x32_bf16 v[0:3], v[144:147], v[204:207], 0
	v_mfma_f32_16x16x32_bf16 v[4:7], v[152:155], v[204:207], 0
	v_mfma_f32_16x16x32_bf16 v[48:51], v[148:151], v[180:183], v[48:51]
	v_mfma_f32_16x16x32_bf16 v[52:55], v[156:159], v[180:183], v[52:55]
	v_mfma_f32_16x16x32_bf16 v[32:35], v[148:151], v[188:191], v[32:35]
	v_mfma_f32_16x16x32_bf16 v[36:39], v[156:159], v[188:191], v[36:39]
	s_setprio 2
	s_barrier
	v_mfma_f32_16x16x32_bf16 v[16:19], v[148:151], v[200:203], v[16:19]
	v_mfma_f32_16x16x32_bf16 v[20:23], v[156:159], v[200:203], v[20:23]
	v_mfma_f32_16x16x32_bf16 v[0:3], v[148:151], v[208:211], v[0:3]
	v_mfma_f32_16x16x32_bf16 v[4:7], v[156:159], v[208:211], v[4:7]
	s_setprio 0
	s_add_i32 s54, 0, 0x18000
	s_add_i32 s55, 0, 0x1c000
	v_add_u32_e32 v140, s54, v196
	v_add_u32_e32 v156, s55, v196
	ds_read_b128 v[128:131], v140
	ds_read_b128 v[132:135], v140 offset:1024
	ds_read_b128 v[136:139], v140 offset:2048
	ds_read_b128 v[140:143], v140 offset:3072
	ds_read_b128 v[144:147], v156
	ds_read_b128 v[148:151], v156 offset:1024
	ds_read_b128 v[152:155], v156 offset:2048
	ds_read_b128 v[156:159], v156 offset:3072
	s_add_u32 s24, s28, 0xb0000
	s_addc_u32 s25, s29, 0
	s_mov_b32 m0, s38
	v_lshl_add_u64 v[220:221], s[24:25], 0, v[164:165]
	ds_read_b128 v[160:163], v199 offset:32768
	ds_read_b128 v[180:183], v199 offset:33792
	ds_read_b128 v[184:187], v199 offset:34816
	ds_read_b128 v[188:191], v199 offset:35840
	ds_read_b128 v[192:195], v199 offset:36864
	ds_read_b128 v[200:203], v199 offset:37888
	ds_read_b128 v[204:207], v199 offset:38912
	ds_read_b128 v[208:211], v199 offset:39936
	global_load_lds_dwordx4 v[220:221], off
	s_mov_b32 m0, s39
	v_lshl_add_u64 v[220:221], s[24:25], 0, v[168:169]
	global_load_lds_dwordx4 v[220:221], off
	s_waitcnt vmcnt(8) lgkmcnt(0)
	s_barrier
	s_setprio 1
	v_mfma_f32_16x16x32_bf16 v[124:127], v[128:131], v[160:163], v[124:127]
	v_mfma_f32_16x16x32_bf16 v[120:123], v[136:139], v[160:163], v[120:123]
	v_mfma_f32_16x16x32_bf16 v[116:119], v[128:131], v[184:187], v[116:119]
	v_mfma_f32_16x16x32_bf16 v[108:111], v[136:139], v[184:187], v[108:111]
	v_mfma_f32_16x16x32_bf16 v[88:91], v[128:131], v[192:195], v[88:91]
	v_mfma_f32_16x16x32_bf16 v[100:103], v[136:139], v[192:195], v[100:103]
	v_mfma_f32_16x16x32_bf16 v[72:75], v[128:131], v[204:207], v[72:75]
	v_mfma_f32_16x16x32_bf16 v[76:79], v[136:139], v[204:207], v[76:79]
	v_mfma_f32_16x16x32_bf16 v[124:127], v[132:135], v[180:183], v[124:127]
	v_mfma_f32_16x16x32_bf16 v[120:123], v[140:143], v[180:183], v[120:123]
	v_mfma_f32_16x16x32_bf16 v[116:119], v[132:135], v[188:191], v[116:119]
	v_mfma_f32_16x16x32_bf16 v[108:111], v[140:143], v[188:191], v[108:111]
	v_mfma_f32_16x16x32_bf16 v[88:91], v[132:135], v[200:203], v[88:91]
	v_mfma_f32_16x16x32_bf16 v[100:103], v[140:143], v[200:203], v[100:103]
	v_mfma_f32_16x16x32_bf16 v[72:75], v[132:135], v[208:211], v[72:75]
	v_mfma_f32_16x16x32_bf16 v[76:79], v[140:143], v[208:211], v[76:79]
	v_mfma_f32_16x16x32_bf16 v[112:115], v[144:147], v[160:163], v[112:115]
	v_mfma_f32_16x16x32_bf16 v[104:107], v[152:155], v[160:163], v[104:107]
	v_mfma_f32_16x16x32_bf16 v[96:99], v[144:147], v[184:187], v[96:99]
	v_mfma_f32_16x16x32_bf16 v[92:95], v[152:155], v[184:187], v[92:95]
	v_mfma_f32_16x16x32_bf16 v[80:83], v[144:147], v[192:195], v[80:83]
	v_mfma_f32_16x16x32_bf16 v[84:87], v[152:155], v[192:195], v[84:87]
	v_mfma_f32_16x16x32_bf16 v[64:67], v[144:147], v[204:207], v[64:67]
	v_mfma_f32_16x16x32_bf16 v[68:71], v[152:155], v[204:207], v[68:71]
	v_mfma_f32_16x16x32_bf16 v[112:115], v[148:151], v[180:183], v[112:115]
	v_mfma_f32_16x16x32_bf16 v[104:107], v[156:159], v[180:183], v[104:107]
	v_mfma_f32_16x16x32_bf16 v[96:99], v[148:151], v[188:191], v[96:99]
	v_mfma_f32_16x16x32_bf16 v[92:95], v[156:159], v[188:191], v[92:95]
	s_setprio 2
	s_barrier
	v_mfma_f32_16x16x32_bf16 v[80:83], v[148:151], v[200:203], v[80:83]
	v_mfma_f32_16x16x32_bf16 v[84:87], v[156:159], v[200:203], v[84:87]
	v_mfma_f32_16x16x32_bf16 v[64:67], v[148:151], v[208:211], v[64:67]
	v_mfma_f32_16x16x32_bf16 v[68:71], v[156:159], v[208:211], v[68:71]
	s_setprio 2
	s_add_i32 s24, s54, s35
	v_lshl_add_u64 v[212:213], v[212:213], 0, s[16:17]
	s_mov_b32 m0, s24
	ds_read_b128 v[160:163], v199 offset:49152
	ds_read_b128 v[180:183], v199 offset:50176
	ds_read_b128 v[184:187], v199 offset:51200
	ds_read_b128 v[188:191], v199 offset:52224
	ds_read_b128 v[192:195], v199 offset:53248
	ds_read_b128 v[200:203], v199 offset:54272
	ds_read_b128 v[204:207], v199 offset:55296
	ds_read_b128 v[208:211], v199 offset:56320
	global_load_lds_dwordx4 v[212:213], off
	s_add_i32 m0, s24, 0x2000
	s_add_u32 s24, s26, 0xb0080
	v_lshl_add_u64 v[212:213], v[214:215], 0, s[16:17]
	s_addc_u32 s25, s27, 0
	s_add_i32 s26, s55, s35
	global_load_lds_dwordx4 v[212:213], off
	s_mov_b32 m0, s26
	v_lshl_add_u64 v[212:213], s[24:25], 0, v[166:167]
	global_load_lds_dwordx4 v[212:213], off
	s_add_i32 m0, s26, 0x2000
	v_lshl_add_u64 v[212:213], s[24:25], 0, v[170:171]
	global_load_lds_dwordx4 v[212:213], off
	s_mov_b32 m0, s41
	v_lshl_add_u64 v[212:213], v[216:217], 0, s[16:17]
	global_load_lds_dwordx4 v[212:213], off
	s_mov_b32 m0, s42
	v_lshl_add_u64 v[212:213], v[218:219], 0, s[16:17]
	global_load_lds_dwordx4 v[212:213], off
	s_waitcnt vmcnt(8) lgkmcnt(0)
	s_barrier
	s_setprio 1
	v_mfma_f32_16x16x32_bf16 v[56:59], v[128:131], v[160:163], v[56:59]
	v_mfma_f32_16x16x32_bf16 v[60:63], v[136:139], v[160:163], v[60:63]
	v_mfma_f32_16x16x32_bf16 v[40:43], v[128:131], v[184:187], v[40:43]
	v_mfma_f32_16x16x32_bf16 v[44:47], v[136:139], v[184:187], v[44:47]
	v_mfma_f32_16x16x32_bf16 v[24:27], v[128:131], v[192:195], v[24:27]
	v_mfma_f32_16x16x32_bf16 v[28:31], v[136:139], v[192:195], v[28:31]
	v_mfma_f32_16x16x32_bf16 v[8:11], v[128:131], v[204:207], v[8:11]
	v_mfma_f32_16x16x32_bf16 v[12:15], v[136:139], v[204:207], v[12:15]
	v_mfma_f32_16x16x32_bf16 v[56:59], v[132:135], v[180:183], v[56:59]
	v_mfma_f32_16x16x32_bf16 v[60:63], v[140:143], v[180:183], v[60:63]
	v_mfma_f32_16x16x32_bf16 v[40:43], v[132:135], v[188:191], v[40:43]
	v_mfma_f32_16x16x32_bf16 v[44:47], v[140:143], v[188:191], v[44:47]
	v_mfma_f32_16x16x32_bf16 v[24:27], v[132:135], v[200:203], v[24:27]
	v_mfma_f32_16x16x32_bf16 v[28:31], v[140:143], v[200:203], v[28:31]
	v_mfma_f32_16x16x32_bf16 v[8:11], v[132:135], v[208:211], v[8:11]
	v_mfma_f32_16x16x32_bf16 v[12:15], v[140:143], v[208:211], v[12:15]
	v_mfma_f32_16x16x32_bf16 v[48:51], v[144:147], v[160:163], v[48:51]
	v_mfma_f32_16x16x32_bf16 v[52:55], v[152:155], v[160:163], v[52:55]
	v_mfma_f32_16x16x32_bf16 v[32:35], v[144:147], v[184:187], v[32:35]
	v_mfma_f32_16x16x32_bf16 v[36:39], v[152:155], v[184:187], v[36:39]
	v_mfma_f32_16x16x32_bf16 v[16:19], v[144:147], v[192:195], v[16:19]
	v_mfma_f32_16x16x32_bf16 v[20:23], v[152:155], v[192:195], v[20:23]
	v_mfma_f32_16x16x32_bf16 v[0:3], v[144:147], v[204:207], v[0:3]
	v_mfma_f32_16x16x32_bf16 v[4:7], v[152:155], v[204:207], v[4:7]
	v_mfma_f32_16x16x32_bf16 v[48:51], v[148:151], v[180:183], v[48:51]
	v_mfma_f32_16x16x32_bf16 v[52:55], v[156:159], v[180:183], v[52:55]
	v_mfma_f32_16x16x32_bf16 v[32:35], v[148:151], v[188:191], v[32:35]
	v_mfma_f32_16x16x32_bf16 v[36:39], v[156:159], v[188:191], v[36:39]
	s_setprio 2
	s_barrier
	v_mfma_f32_16x16x32_bf16 v[16:19], v[148:151], v[200:203], v[16:19]
	v_mfma_f32_16x16x32_bf16 v[20:23], v[156:159], v[200:203], v[20:23]
	v_mfma_f32_16x16x32_bf16 v[0:3], v[148:151], v[208:211], v[0:3]
	v_mfma_f32_16x16x32_bf16 v[4:7], v[156:159], v[208:211], v[4:7]
	s_setprio 0
	s_add_i32 s53, s53, 2
	s_add_u32 s51, s51, 0x100
	s_addc_u32 s52, s52, 0
	s_cmp_gt_u32 s53, 41
	s_mov_b64 s[24:25], s[4:5]
.LBB0_1310:
	ds_read_b128 v[128:131], v197
	ds_read_b128 v[132:135], v197 offset:1024
	ds_read_b128 v[136:139], v197 offset:2048
	ds_read_b128 v[140:143], v197 offset:3072
	ds_read_b128 v[144:147], v198
	ds_read_b128 v[148:151], v198 offset:1024
	ds_read_b128 v[152:155], v198 offset:2048
	ds_read_b128 v[156:159], v198 offset:3072
	s_add_u32 s4, s24, 0x100
	s_addc_u32 s5, s25, 0
	s_cmp_eq_u32 s53, 40
	s_cselect_b32 s29, s21, s5
	s_cselect_b32 s28, s20, s4
	s_cselect_b32 s27, s23, s52
	s_cselect_b32 s26, s22, s51
	v_lshl_add_u64 v[212:213], s[24:25], 0, v[172:173]
	s_add_i32 m0, s36, 0xc000
	ds_read_b128 v[160:163], v199
	ds_read_b128 v[180:183], v199 offset:1024
	ds_read_b128 v[184:187], v199 offset:2048
	ds_read_b128 v[188:191], v199 offset:3072
	ds_read_b128 v[192:195], v199 offset:4096
	ds_read_b128 v[200:203], v199 offset:5120
	ds_read_b128 v[204:207], v199 offset:6144
	ds_read_b128 v[208:211], v199 offset:7168
	global_load_lds_dwordx4 v[212:213], off
	s_add_i32 m0, s36, 0xe000
	v_lshl_add_u64 v[212:213], s[24:25], 0, v[174:175]
	global_load_lds_dwordx4 v[212:213], off
	s_waitcnt vmcnt(8) lgkmcnt(0)
	s_barrier
	s_setprio 1
	v_mfma_f32_16x16x32_bf16 v[124:127], v[128:131], v[160:163], v[124:127]
	v_mfma_f32_16x16x32_bf16 v[120:123], v[136:139], v[160:163], v[120:123]
	v_mfma_f32_16x16x32_bf16 v[116:119], v[128:131], v[184:187], v[116:119]
	v_mfma_f32_16x16x32_bf16 v[108:111], v[136:139], v[184:187], v[108:111]
	v_mfma_f32_16x16x32_bf16 v[88:91], v[128:131], v[192:195], v[88:91]
	v_mfma_f32_16x16x32_bf16 v[100:103], v[136:139], v[192:195], v[100:103]
	v_mfma_f32_16x16x32_bf16 v[72:75], v[128:131], v[204:207], v[72:75]
	v_mfma_f32_16x16x32_bf16 v[76:79], v[136:139], v[204:207], v[76:79]
	v_mfma_f32_16x16x32_bf16 v[124:127], v[132:135], v[180:183], v[124:127]
	v_mfma_f32_16x16x32_bf16 v[120:123], v[140:143], v[180:183], v[120:123]
	v_mfma_f32_16x16x32_bf16 v[116:119], v[132:135], v[188:191], v[116:119]
	v_mfma_f32_16x16x32_bf16 v[108:111], v[140:143], v[188:191], v[108:111]
	v_mfma_f32_16x16x32_bf16 v[88:91], v[132:135], v[200:203], v[88:91]
	v_mfma_f32_16x16x32_bf16 v[100:103], v[140:143], v[200:203], v[100:103]
	v_mfma_f32_16x16x32_bf16 v[72:75], v[132:135], v[208:211], v[72:75]
	v_mfma_f32_16x16x32_bf16 v[76:79], v[140:143], v[208:211], v[76:79]
	v_mfma_f32_16x16x32_bf16 v[112:115], v[144:147], v[160:163], v[112:115]
	v_mfma_f32_16x16x32_bf16 v[104:107], v[152:155], v[160:163], v[104:107]
	v_mfma_f32_16x16x32_bf16 v[96:99], v[144:147], v[184:187], v[96:99]
	v_mfma_f32_16x16x32_bf16 v[92:95], v[152:155], v[184:187], v[92:95]
	v_mfma_f32_16x16x32_bf16 v[80:83], v[144:147], v[192:195], v[80:83]
	v_mfma_f32_16x16x32_bf16 v[84:87], v[152:155], v[192:195], v[84:87]
	v_mfma_f32_16x16x32_bf16 v[64:67], v[144:147], v[204:207], v[64:67]
	v_mfma_f32_16x16x32_bf16 v[68:71], v[152:155], v[204:207], v[68:71]
	v_mfma_f32_16x16x32_bf16 v[112:115], v[148:151], v[180:183], v[112:115]
	v_mfma_f32_16x16x32_bf16 v[104:107], v[156:159], v[180:183], v[104:107]
	v_mfma_f32_16x16x32_bf16 v[96:99], v[148:151], v[188:191], v[96:99]
	v_mfma_f32_16x16x32_bf16 v[92:95], v[156:159], v[188:191], v[92:95]
	s_setprio 2
	s_barrier
	v_mfma_f32_16x16x32_bf16 v[80:83], v[148:151], v[200:203], v[80:83]
	v_mfma_f32_16x16x32_bf16 v[84:87], v[156:159], v[200:203], v[84:87]
	v_mfma_f32_16x16x32_bf16 v[64:67], v[148:151], v[208:211], v[64:67]
	v_mfma_f32_16x16x32_bf16 v[68:71], v[156:159], v[208:211], v[68:71]
	s_setprio 2
	s_add_i32 s24, s45, s35
	v_lshl_add_u64 v[212:213], s[26:27], 0, v[166:167]
	s_mov_b32 m0, s24
	ds_read_b128 v[160:163], v199 offset:16384
	ds_read_b128 v[180:183], v199 offset:17408
	ds_read_b128 v[184:187], v199 offset:18432
	ds_read_b128 v[188:191], v199 offset:19456
	ds_read_b128 v[192:195], v199 offset:20480
	ds_read_b128 v[200:203], v199 offset:21504
	ds_read_b128 v[204:207], v199 offset:22528
	ds_read_b128 v[208:211], v199 offset:23552
	global_load_lds_dwordx4 v[212:213], off
	s_add_i32 m0, s24, 0x2000
	s_add_u32 s24, s26, 0xb0000
	v_lshl_add_u64 v[214:215], s[26:27], 0, v[170:171]
	s_addc_u32 s25, s27, 0
	s_add_i32 s54, s46, s35
	global_load_lds_dwordx4 v[214:215], off
	v_lshl_add_u64 v[216:217], s[24:25], 0, v[166:167]
	s_mov_b32 m0, s54
	v_lshl_add_u64 v[218:219], s[28:29], 0, v[168:169]
	global_load_lds_dwordx4 v[216:217], off
	s_add_i32 m0, s54, 0x2000
	v_lshl_add_u64 v[216:217], s[24:25], 0, v[170:171]
	global_load_lds_dwordx4 v[216:217], off
	s_mov_b32 m0, s36
	v_lshl_add_u64 v[216:217], s[28:29], 0, v[164:165]
	global_load_lds_dwordx4 v[216:217], off
	s_mov_b32 m0, s37
	s_nop 0
	global_load_lds_dwordx4 v[218:219], off
	s_waitcnt vmcnt(8) lgkmcnt(0)
	s_barrier
	s_setprio 1
	v_mfma_f32_16x16x32_bf16 v[56:59], v[128:131], v[160:163], v[56:59]
	v_mfma_f32_16x16x32_bf16 v[60:63], v[136:139], v[160:163], v[60:63]
	v_mfma_f32_16x16x32_bf16 v[40:43], v[128:131], v[184:187], v[40:43]
	v_mfma_f32_16x16x32_bf16 v[44:47], v[136:139], v[184:187], v[44:47]
	v_mfma_f32_16x16x32_bf16 v[24:27], v[128:131], v[192:195], v[24:27]
	v_mfma_f32_16x16x32_bf16 v[28:31], v[136:139], v[192:195], v[28:31]
	v_mfma_f32_16x16x32_bf16 v[8:11], v[128:131], v[204:207], v[8:11]
	v_mfma_f32_16x16x32_bf16 v[12:15], v[136:139], v[204:207], v[12:15]
	v_mfma_f32_16x16x32_bf16 v[56:59], v[132:135], v[180:183], v[56:59]
	v_mfma_f32_16x16x32_bf16 v[60:63], v[140:143], v[180:183], v[60:63]
	v_mfma_f32_16x16x32_bf16 v[40:43], v[132:135], v[188:191], v[40:43]
	v_mfma_f32_16x16x32_bf16 v[44:47], v[140:143], v[188:191], v[44:47]
	v_mfma_f32_16x16x32_bf16 v[24:27], v[132:135], v[200:203], v[24:27]
	v_mfma_f32_16x16x32_bf16 v[28:31], v[140:143], v[200:203], v[28:31]
	v_mfma_f32_16x16x32_bf16 v[8:11], v[132:135], v[208:211], v[8:11]
	v_mfma_f32_16x16x32_bf16 v[12:15], v[140:143], v[208:211], v[12:15]
	v_mfma_f32_16x16x32_bf16 v[48:51], v[144:147], v[160:163], v[48:51]
	v_mfma_f32_16x16x32_bf16 v[52:55], v[152:155], v[160:163], v[52:55]
	v_mfma_f32_16x16x32_bf16 v[32:35], v[144:147], v[184:187], v[32:35]
	v_mfma_f32_16x16x32_bf16 v[36:39], v[152:155], v[184:187], v[36:39]
	v_mfma_f32_16x16x32_bf16 v[16:19], v[144:147], v[192:195], v[16:19]
	v_mfma_f32_16x16x32_bf16 v[20:23], v[152:155], v[192:195], v[20:23]
	v_mfma_f32_16x16x32_bf16 v[0:3], v[144:147], v[204:207], v[0:3]
	v_mfma_f32_16x16x32_bf16 v[4:7], v[152:155], v[204:207], v[4:7]
	v_mfma_f32_16x16x32_bf16 v[48:51], v[148:151], v[180:183], v[48:51]
	v_mfma_f32_16x16x32_bf16 v[52:55], v[156:159], v[180:183], v[52:55]
	v_mfma_f32_16x16x32_bf16 v[32:35], v[148:151], v[188:191], v[32:35]
	v_mfma_f32_16x16x32_bf16 v[36:39], v[156:159], v[188:191], v[36:39]
	s_setprio 2
	s_barrier
	v_mfma_f32_16x16x32_bf16 v[16:19], v[148:151], v[200:203], v[16:19]
	v_mfma_f32_16x16x32_bf16 v[20:23], v[156:159], v[200:203], v[20:23]
	v_mfma_f32_16x16x32_bf16 v[0:3], v[148:151], v[208:211], v[0:3]
	v_mfma_f32_16x16x32_bf16 v[4:7], v[156:159], v[208:211], v[4:7]
	s_setprio 0
	s_add_i32 s54, 0, 0x18000
	s_add_i32 s55, 0, 0x1c000
	v_add_u32_e32 v140, s54, v196
	v_add_u32_e32 v156, s55, v196
	ds_read_b128 v[128:131], v140
	ds_read_b128 v[132:135], v140 offset:1024
	ds_read_b128 v[136:139], v140 offset:2048
	ds_read_b128 v[140:143], v140 offset:3072
	ds_read_b128 v[144:147], v156
	ds_read_b128 v[148:151], v156 offset:1024
	ds_read_b128 v[152:155], v156 offset:2048
	ds_read_b128 v[156:159], v156 offset:3072
	s_add_u32 s24, s28, 0xb0000
	s_addc_u32 s25, s29, 0
	s_mov_b32 m0, s38
	v_lshl_add_u64 v[220:221], s[24:25], 0, v[164:165]
	ds_read_b128 v[160:163], v199 offset:32768
	ds_read_b128 v[180:183], v199 offset:33792
	ds_read_b128 v[184:187], v199 offset:34816
	ds_read_b128 v[188:191], v199 offset:35840
	ds_read_b128 v[192:195], v199 offset:36864
	ds_read_b128 v[200:203], v199 offset:37888
	ds_read_b128 v[204:207], v199 offset:38912
	ds_read_b128 v[208:211], v199 offset:39936
	global_load_lds_dwordx4 v[220:221], off
	s_mov_b32 m0, s39
	v_lshl_add_u64 v[220:221], s[24:25], 0, v[168:169]
	global_load_lds_dwordx4 v[220:221], off
	s_waitcnt vmcnt(8) lgkmcnt(0)
	s_barrier
	s_setprio 1
	v_mfma_f32_16x16x32_bf16 v[124:127], v[128:131], v[160:163], v[124:127]
	v_mfma_f32_16x16x32_bf16 v[120:123], v[136:139], v[160:163], v[120:123]
	v_mfma_f32_16x16x32_bf16 v[116:119], v[128:131], v[184:187], v[116:119]
	v_mfma_f32_16x16x32_bf16 v[108:111], v[136:139], v[184:187], v[108:111]
	v_mfma_f32_16x16x32_bf16 v[88:91], v[128:131], v[192:195], v[88:91]
	v_mfma_f32_16x16x32_bf16 v[100:103], v[136:139], v[192:195], v[100:103]
	v_mfma_f32_16x16x32_bf16 v[72:75], v[128:131], v[204:207], v[72:75]
	v_mfma_f32_16x16x32_bf16 v[76:79], v[136:139], v[204:207], v[76:79]
	v_mfma_f32_16x16x32_bf16 v[124:127], v[132:135], v[180:183], v[124:127]
	v_mfma_f32_16x16x32_bf16 v[120:123], v[140:143], v[180:183], v[120:123]
	v_mfma_f32_16x16x32_bf16 v[116:119], v[132:135], v[188:191], v[116:119]
	v_mfma_f32_16x16x32_bf16 v[108:111], v[140:143], v[188:191], v[108:111]
	v_mfma_f32_16x16x32_bf16 v[88:91], v[132:135], v[200:203], v[88:91]
	v_mfma_f32_16x16x32_bf16 v[100:103], v[140:143], v[200:203], v[100:103]
	v_mfma_f32_16x16x32_bf16 v[72:75], v[132:135], v[208:211], v[72:75]
	v_mfma_f32_16x16x32_bf16 v[76:79], v[140:143], v[208:211], v[76:79]
	v_mfma_f32_16x16x32_bf16 v[112:115], v[144:147], v[160:163], v[112:115]
	v_mfma_f32_16x16x32_bf16 v[104:107], v[152:155], v[160:163], v[104:107]
	v_mfma_f32_16x16x32_bf16 v[96:99], v[144:147], v[184:187], v[96:99]
	v_mfma_f32_16x16x32_bf16 v[92:95], v[152:155], v[184:187], v[92:95]
	v_mfma_f32_16x16x32_bf16 v[80:83], v[144:147], v[192:195], v[80:83]
	v_mfma_f32_16x16x32_bf16 v[84:87], v[152:155], v[192:195], v[84:87]
	v_mfma_f32_16x16x32_bf16 v[64:67], v[144:147], v[204:207], v[64:67]
	v_mfma_f32_16x16x32_bf16 v[68:71], v[152:155], v[204:207], v[68:71]
	v_mfma_f32_16x16x32_bf16 v[112:115], v[148:151], v[180:183], v[112:115]
	v_mfma_f32_16x16x32_bf16 v[104:107], v[156:159], v[180:183], v[104:107]
	v_mfma_f32_16x16x32_bf16 v[96:99], v[148:151], v[188:191], v[96:99]
	v_mfma_f32_16x16x32_bf16 v[92:95], v[156:159], v[188:191], v[92:95]
	s_setprio 2
	s_barrier
	v_mfma_f32_16x16x32_bf16 v[80:83], v[148:151], v[200:203], v[80:83]
	v_mfma_f32_16x16x32_bf16 v[84:87], v[156:159], v[200:203], v[84:87]
	v_mfma_f32_16x16x32_bf16 v[64:67], v[148:151], v[208:211], v[64:67]
	v_mfma_f32_16x16x32_bf16 v[68:71], v[156:159], v[208:211], v[68:71]
	s_setprio 2
	s_add_i32 s24, s54, s35
	v_lshl_add_u64 v[212:213], v[212:213], 0, s[16:17]
	s_mov_b32 m0, s24
	ds_read_b128 v[160:163], v199 offset:49152
	ds_read_b128 v[180:183], v199 offset:50176
	ds_read_b128 v[184:187], v199 offset:51200
	ds_read_b128 v[188:191], v199 offset:52224
	ds_read_b128 v[192:195], v199 offset:53248
	ds_read_b128 v[200:203], v199 offset:54272
	ds_read_b128 v[204:207], v199 offset:55296
	ds_read_b128 v[208:211], v199 offset:56320
	global_load_lds_dwordx4 v[212:213], off
	s_add_i32 m0, s24, 0x2000
	s_add_u32 s24, s26, 0xb0080
	v_lshl_add_u64 v[212:213], v[214:215], 0, s[16:17]
	s_addc_u32 s25, s27, 0
	s_add_i32 s26, s55, s35
	global_load_lds_dwordx4 v[212:213], off
	s_mov_b32 m0, s26
	v_lshl_add_u64 v[212:213], s[24:25], 0, v[166:167]
	global_load_lds_dwordx4 v[212:213], off
	s_add_i32 m0, s26, 0x2000
	v_lshl_add_u64 v[212:213], s[24:25], 0, v[170:171]
	global_load_lds_dwordx4 v[212:213], off
	s_mov_b32 m0, s41
	v_lshl_add_u64 v[212:213], v[216:217], 0, s[16:17]
	global_load_lds_dwordx4 v[212:213], off
	s_mov_b32 m0, s42
	v_lshl_add_u64 v[212:213], v[218:219], 0, s[16:17]
	global_load_lds_dwordx4 v[212:213], off
	s_waitcnt vmcnt(8) lgkmcnt(0)
	s_barrier
	s_setprio 1
	v_mfma_f32_16x16x32_bf16 v[56:59], v[128:131], v[160:163], v[56:59]
	v_mfma_f32_16x16x32_bf16 v[60:63], v[136:139], v[160:163], v[60:63]
	v_mfma_f32_16x16x32_bf16 v[40:43], v[128:131], v[184:187], v[40:43]
	v_mfma_f32_16x16x32_bf16 v[44:47], v[136:139], v[184:187], v[44:47]
	v_mfma_f32_16x16x32_bf16 v[24:27], v[128:131], v[192:195], v[24:27]
	v_mfma_f32_16x16x32_bf16 v[28:31], v[136:139], v[192:195], v[28:31]
	v_mfma_f32_16x16x32_bf16 v[8:11], v[128:131], v[204:207], v[8:11]
	v_mfma_f32_16x16x32_bf16 v[12:15], v[136:139], v[204:207], v[12:15]
	v_mfma_f32_16x16x32_bf16 v[56:59], v[132:135], v[180:183], v[56:59]
	v_mfma_f32_16x16x32_bf16 v[60:63], v[140:143], v[180:183], v[60:63]
	v_mfma_f32_16x16x32_bf16 v[40:43], v[132:135], v[188:191], v[40:43]
	v_mfma_f32_16x16x32_bf16 v[44:47], v[140:143], v[188:191], v[44:47]
	v_mfma_f32_16x16x32_bf16 v[24:27], v[132:135], v[200:203], v[24:27]
	v_mfma_f32_16x16x32_bf16 v[28:31], v[140:143], v[200:203], v[28:31]
	v_mfma_f32_16x16x32_bf16 v[8:11], v[132:135], v[208:211], v[8:11]
	v_mfma_f32_16x16x32_bf16 v[12:15], v[140:143], v[208:211], v[12:15]
	v_mfma_f32_16x16x32_bf16 v[48:51], v[144:147], v[160:163], v[48:51]
	v_mfma_f32_16x16x32_bf16 v[52:55], v[152:155], v[160:163], v[52:55]
	v_mfma_f32_16x16x32_bf16 v[32:35], v[144:147], v[184:187], v[32:35]
	v_mfma_f32_16x16x32_bf16 v[36:39], v[152:155], v[184:187], v[36:39]
	v_mfma_f32_16x16x32_bf16 v[16:19], v[144:147], v[192:195], v[16:19]
	v_mfma_f32_16x16x32_bf16 v[20:23], v[152:155], v[192:195], v[20:23]
	v_mfma_f32_16x16x32_bf16 v[0:3], v[144:147], v[204:207], v[0:3]
	v_mfma_f32_16x16x32_bf16 v[4:7], v[152:155], v[204:207], v[4:7]
	v_mfma_f32_16x16x32_bf16 v[48:51], v[148:151], v[180:183], v[48:51]
	v_mfma_f32_16x16x32_bf16 v[52:55], v[156:159], v[180:183], v[52:55]
	v_mfma_f32_16x16x32_bf16 v[32:35], v[148:151], v[188:191], v[32:35]
	v_mfma_f32_16x16x32_bf16 v[36:39], v[156:159], v[188:191], v[36:39]
	s_setprio 2
	s_barrier
	v_mfma_f32_16x16x32_bf16 v[16:19], v[148:151], v[200:203], v[16:19]
	v_mfma_f32_16x16x32_bf16 v[20:23], v[156:159], v[200:203], v[20:23]
	v_mfma_f32_16x16x32_bf16 v[0:3], v[148:151], v[208:211], v[0:3]
	v_mfma_f32_16x16x32_bf16 v[4:7], v[156:159], v[208:211], v[4:7]
	s_setprio 0
	s_add_i32 s53, s53, 2
	s_add_u32 s51, s51, 0x100
	s_addc_u32 s52, s52, 0
	s_cmp_gt_u32 s53, 41
	s_mov_b64 s[24:25], s[4:5]
	s_cbranch_scc0 .LBB0_1310
